# t1 = s1 + the redundant adjacent s_setprio 0 / s_setprio 1 pair in the middle of each 32-MFMA run removed (33 sites); bracketing priority raise kept
# baseline (speedup 1.0000x reference)
; #define PG8_STAGE(bufoff, gbase, voff) do { _Pragma("unroll") for (int _i = 0; _i < 2; ++_i) \
;         __builtin_amdgcn_global_load_lds((const unsigned*)((const char*)(gbase) + (voff)[_i]), (LAS unsigned*)(lds + (bufoff) + ldsw + _i * 8192), 16, 0, 0); } while (0)
; #define PG8_LDA(dst, b, h) do { _Pragma("unroll") for (int m = 0; m < 4; ++m) _Pragma("unroll") for (int k = 0; k < 2; ++k) dst[m][k] = *(const LAS bf16x8*)(lds + PG8_SA(b, h) + aoff + m * 2048 + k * 1024); } while (0)
; #define PG8_LDB(dst, b, h) do { _Pragma("unroll") for (int n = 0; n < 2; ++n) _Pragma("unroll") for (int k = 0; k < 2; ++k) dst[n][k] = *(const LAS bf16x8*)(lds + PG8_SB(b, h) + boff + n * 2048 + k * 1024); } while (0)
; #define PG8_WAIT_V(n) asm volatile("s_waitcnt vmcnt(" #n ")" ::: "memory")
; #define PG8_BAR __builtin_amdgcn_s_barrier()
; template <class Epi>
; __device__ __forceinline__ void gemm_phase(LAS unsigned char* lds, const Gemm g, const StaticOrder& S, const Epi& E, const int tid) {
;     ...
;         for (int t = 0; t < nt; t += 2) {
;             const bool last = (t == nt - 2);
;             const char* a1 = cA + (size_t)(t + 1) * kstep;
;             const char* a2 = last ? nA : cA + (size_t)(t + 2) * kstep; const char* b2 = last ? nB : cB + (size_t)(t + 2) * kstep;
;             const char* a3 = a2 + kstep; const char* b3 = b2 + kstep;
;             PG8_LDB(B0, 0, 0); PG8_LDB(B1, 0, 1); PG8_SCHED; PG8_LDA(At, 0, 0); PG8_STAGE(PG8_SA(1, 1), a1 + hstepA, voffA);
;             PG8_WAIT_V(8); PG8_WAIT_L(0); PG8_BAR; PG8_MMA(0, 0, At, B0); PG8_MMA(0, 1, At, B1); PG8_BAR; PG8_SCHED;
;             PG8_LDA(At, 0, 1); PG8_STAGE(PG8_SB(0, 0), b2, voffB); PG8_STAGE(PG8_SB(0, 1), b2 + hstepB, voffB); PG8_STAGE(PG8_SA(0, 0), a2, voffA);
;             PG8_WAIT_V(8); PG8_WAIT_L(0); PG8_BAR; PG8_MMA(1, 0, At, B0); PG8_MMA(1, 1, At, B1); PG8_BAR; PG8_SCHED;
;             PG8_LDB(B0, 1, 0); PG8_LDB(B1, 1, 1); PG8_SCHED; PG8_LDA(At, 1, 0); PG8_STAGE(PG8_SA(0, 1), a2 + hstepA, voffA);
;             PG8_WAIT_V(8); PG8_WAIT_L(0); PG8_BAR; PG8_MMA(0, 0, At, B0); PG8_MMA(0, 1, At, B1); PG8_BAR; PG8_SCHED;
;             PG8_LDA(At, 1, 1); PG8_STAGE(PG8_SB(1, 0), b3, voffB); PG8_STAGE(PG8_SB(1, 1), b3 + hstepB, voffB); PG8_STAGE(PG8_SA(1, 0), a3, voffA);
;             PG8_WAIT_V(8); PG8_WAIT_L(0); PG8_BAR; PG8_MMA(1, 0, At, B0); PG8_MMA(1, 1, At, B1); PG8_BAR; PG8_SCHED;
.LBB0_183:
	v_mov_b32_e32 v137, 0
	s_andn2_b64 vcc, exec, s[96:97]
	s_cbranch_vccnz .LBB0_187
	s_add_u32 s0, s36, 0x100
	s_addc_u32 s1, s37, 0
	s_add_u32 s6, s38, 0x80
	s_addc_u32 s7, s39, 0
	s_mov_b32 s36, 0
	s_add_i32 s38, s36, 2
	s_add_u32 s39, s6, 0x80
	s_addc_u32 s37, s7, 0
	s_add_i32 s62, 0, 0x10000
	s_cmp_eq_u32 s53, s36
	s_cselect_b32 s37, s31, s37
	s_cselect_b32 s36, s30, s39
	s_cselect_b32 s61, s35, s1
	s_cselect_b32 s60, s34, s0
	s_add_i32 s39, 0, 0x14000
	v_add_u32_e32 v152, s62, v168
	v_add_u32_e32 v170, s39, v168
	ds_read_b128 v[82:85], v152
	ds_read_b128 v[86:89], v152 offset:1024
	ds_read_b128 v[138:141], v152 offset:2048
	ds_read_b128 v[152:155], v152 offset:3072
	ds_read_b128 v[156:159], v170
	ds_read_b128 v[160:163], v170 offset:1024
	ds_read_b128 v[164:167], v170 offset:2048
	ds_read_b128 v[170:173], v170 offset:3072
	v_lshl_add_u64 v[194:195], s[6:7], 0, v[150:151]
	s_add_i32 m0, s44, 0xc000
	ds_read_b128 v[174:177], v169
	ds_read_b128 v[178:181], v169 offset:1024
	ds_read_b128 v[182:185], v169 offset:2048
	ds_read_b128 v[186:189], v169 offset:3072
	ds_read_b128 v[190:193], v169 offset:4096
	ds_read_b128 v[202:205], v169 offset:5120
	ds_read_b128 v[206:209], v169 offset:6144
	ds_read_b128 v[210:213], v169 offset:7168
	global_load_lds_dwordx4 v[194:195], off
	v_lshl_add_u64 v[194:195], s[6:7], 0, v[148:149]
	s_add_i32 m0, s44, 0xe000
	s_nop 0
	global_load_lds_dwordx4 v[194:195], off
	s_waitcnt vmcnt(8)
	s_waitcnt lgkmcnt(0)
	s_nop 0
	s_barrier
	s_setprio 1
	s_waitcnt lgkmcnt(0)
	v_mfma_f32_16x16x32_bf16 v[134:137], v[82:85], v[174:177], 0
	v_mfma_f32_16x16x32_bf16 v[62:65], v[138:141], v[174:177], 0
	v_mfma_f32_16x16x32_bf16 v[126:129], v[82:85], v[182:185], 0
	v_mfma_f32_16x16x32_bf16 v[54:57], v[138:141], v[182:185], 0
	v_mfma_f32_16x16x32_bf16 v[118:121], v[82:85], v[190:193], 0
	v_mfma_f32_16x16x32_bf16 v[46:49], v[138:141], v[190:193], 0
	v_mfma_f32_16x16x32_bf16 v[110:113], v[82:85], v[206:209], 0
	v_mfma_f32_16x16x32_bf16 v[38:41], v[138:141], v[206:209], 0
	v_mfma_f32_16x16x32_bf16 v[134:137], v[86:89], v[178:181], v[134:137]
	v_mfma_f32_16x16x32_bf16 v[62:65], v[152:155], v[178:181], v[62:65]
	v_mfma_f32_16x16x32_bf16 v[126:129], v[86:89], v[186:189], v[126:129]
	v_mfma_f32_16x16x32_bf16 v[54:57], v[152:155], v[186:189], v[54:57]
	v_mfma_f32_16x16x32_bf16 v[118:121], v[86:89], v[202:205], v[118:121]
	v_mfma_f32_16x16x32_bf16 v[46:49], v[152:155], v[202:205], v[46:49]
	v_mfma_f32_16x16x32_bf16 v[110:113], v[86:89], v[210:213], v[110:113]
	v_mfma_f32_16x16x32_bf16 v[38:41], v[152:155], v[210:213], v[38:41]
	v_mfma_f32_16x16x32_bf16 v[130:133], v[156:159], v[174:177], 0
	v_mfma_f32_16x16x32_bf16 v[58:61], v[164:167], v[174:177], 0
	v_mfma_f32_16x16x32_bf16 v[122:125], v[156:159], v[182:185], 0
	v_mfma_f32_16x16x32_bf16 v[50:53], v[164:167], v[182:185], 0
	v_mfma_f32_16x16x32_bf16 v[114:117], v[156:159], v[190:193], 0
	v_mfma_f32_16x16x32_bf16 v[42:45], v[164:167], v[190:193], 0
	v_mfma_f32_16x16x32_bf16 v[106:109], v[156:159], v[206:209], 0
	v_mfma_f32_16x16x32_bf16 v[34:37], v[164:167], v[206:209], 0
	v_mfma_f32_16x16x32_bf16 v[130:133], v[160:163], v[178:181], v[130:133]
	v_mfma_f32_16x16x32_bf16 v[58:61], v[170:173], v[178:181], v[58:61]
	v_mfma_f32_16x16x32_bf16 v[122:125], v[160:163], v[186:189], v[122:125]
	v_mfma_f32_16x16x32_bf16 v[50:53], v[170:173], v[186:189], v[50:53]
	v_mfma_f32_16x16x32_bf16 v[114:117], v[160:163], v[202:205], v[114:117]
	v_mfma_f32_16x16x32_bf16 v[42:45], v[170:173], v[202:205], v[42:45]
	v_mfma_f32_16x16x32_bf16 v[106:109], v[160:163], v[210:213], v[106:109]
	v_mfma_f32_16x16x32_bf16 v[34:37], v[170:173], v[210:213], v[34:37]
	s_setprio 0
	s_barrier
	s_add_i32 s62, s62, s3
	v_lshl_add_u64 v[194:195], s[60:61], 0, v[0:1]
	s_mov_b32 m0, s62
	ds_read_b128 v[174:177], v169 offset:16384
	ds_read_b128 v[178:181], v169 offset:17408
	ds_read_b128 v[182:185], v169 offset:18432
	ds_read_b128 v[186:189], v169 offset:19456
	ds_read_b128 v[190:193], v169 offset:20480
	ds_read_b128 v[202:205], v169 offset:21504
	ds_read_b128 v[206:209], v169 offset:22528
	ds_read_b128 v[210:213], v169 offset:23552
	global_load_lds_dwordx4 v[194:195], off
	s_add_i32 m0, s62, 0x2000
	v_lshl_add_u64 v[196:197], s[60:61], 0, v[146:147]
	s_add_u32 s60, s60, s12
	s_addc_u32 s61, s61, s13
	s_add_i32 s39, s39, s3
	global_load_lds_dwordx4 v[196:197], off
	v_lshl_add_u64 v[198:199], s[60:61], 0, v[0:1]
	s_mov_b32 m0, s39
	v_lshl_add_u64 v[214:215], s[60:61], 0, v[146:147]
	global_load_lds_dwordx4 v[198:199], off
	s_add_i32 m0, s39, 0x2000
	v_lshl_add_u64 v[216:217], s[36:37], 0, v[142:143]
	global_load_lds_dwordx4 v[214:215], off
	s_mov_b32 m0, s44
	v_lshl_add_u64 v[218:219], s[36:37], 0, v[144:145]
	global_load_lds_dwordx4 v[216:217], off
	s_mov_b32 m0, s45
	s_nop 0
	global_load_lds_dwordx4 v[218:219], off
	s_waitcnt vmcnt(8)
	s_waitcnt lgkmcnt(0)
	s_barrier
	s_setprio 1
	s_waitcnt lgkmcnt(0)
	v_mfma_f32_16x16x32_bf16 v[102:105], v[82:85], v[174:177], 0
	v_mfma_f32_16x16x32_bf16 v[30:33], v[138:141], v[174:177], 0
	v_mfma_f32_16x16x32_bf16 v[94:97], v[82:85], v[182:185], 0
	v_mfma_f32_16x16x32_bf16 v[22:25], v[138:141], v[182:185], 0
	v_mfma_f32_16x16x32_bf16 v[78:81], v[82:85], v[190:193], 0
	v_mfma_f32_16x16x32_bf16 v[14:17], v[138:141], v[190:193], 0
	v_mfma_f32_16x16x32_bf16 v[70:73], v[82:85], v[206:209], 0
	v_mfma_f32_16x16x32_bf16 v[6:9], v[138:141], v[206:209], 0
	v_mfma_f32_16x16x32_bf16 v[102:105], v[86:89], v[178:181], v[102:105]
	v_mfma_f32_16x16x32_bf16 v[30:33], v[152:155], v[178:181], v[30:33]
	v_mfma_f32_16x16x32_bf16 v[94:97], v[86:89], v[186:189], v[94:97]
	v_mfma_f32_16x16x32_bf16 v[22:25], v[152:155], v[186:189], v[22:25]
	v_mfma_f32_16x16x32_bf16 v[78:81], v[86:89], v[202:205], v[78:81]
	v_mfma_f32_16x16x32_bf16 v[14:17], v[152:155], v[202:205], v[14:17]
	v_mfma_f32_16x16x32_bf16 v[70:73], v[86:89], v[210:213], v[70:73]
	v_mfma_f32_16x16x32_bf16 v[6:9], v[152:155], v[210:213], v[6:9]
	v_mfma_f32_16x16x32_bf16 v[26:29], v[164:167], v[174:177], 0
	v_mfma_f32_16x16x32_bf16 v[18:21], v[164:167], v[182:185], 0
	v_mfma_f32_16x16x32_bf16 v[74:77], v[156:159], v[190:193], 0
	v_mfma_f32_16x16x32_bf16 v[10:13], v[164:167], v[190:193], 0
	v_mfma_f32_16x16x32_bf16 v[66:69], v[156:159], v[206:209], 0
	v_mfma_f32_16x16x32_bf16 v[2:5], v[164:167], v[206:209], 0
	v_mfma_f32_16x16x32_bf16 v[82:85], v[156:159], v[174:177], 0
	v_mfma_f32_16x16x32_bf16 v[26:29], v[170:173], v[178:181], v[26:29]
	v_mfma_f32_16x16x32_bf16 v[86:89], v[156:159], v[182:185], 0
	v_mfma_f32_16x16x32_bf16 v[18:21], v[170:173], v[186:189], v[18:21]
	v_mfma_f32_16x16x32_bf16 v[74:77], v[160:163], v[202:205], v[74:77]
	v_mfma_f32_16x16x32_bf16 v[10:13], v[170:173], v[202:205], v[10:13]
	v_mfma_f32_16x16x32_bf16 v[66:69], v[160:163], v[210:213], v[66:69]
	v_mfma_f32_16x16x32_bf16 v[2:5], v[170:173], v[210:213], v[2:5]
	v_mfma_f32_16x16x32_bf16 v[82:85], v[160:163], v[178:181], v[82:85]
	v_mfma_f32_16x16x32_bf16 v[86:89], v[160:163], v[186:189], v[86:89]
	s_setprio 0
	s_barrier
	s_branch .Lkl185_sp2
; #define PG8_STAGE(bufoff, gbase, voff) do { _Pragma("unroll") for (int _i = 0; _i < 2; ++_i) \
;         __builtin_amdgcn_global_load_lds((const unsigned*)((const char*)(gbase) + (voff)[_i]), (LAS unsigned*)(lds + (bufoff) + ldsw + _i * 8192), 16, 0, 0); } while (0)
; #define PG8_LDA(dst, b, h) do { _Pragma("unroll") for (int m = 0; m < 4; ++m) _Pragma("unroll") for (int k = 0; k < 2; ++k) dst[m][k] = *(const LAS bf16x8*)(lds + PG8_SA(b, h) + aoff + m * 2048 + k * 1024); } while (0)
; #define PG8_LDB(dst, b, h) do { _Pragma("unroll") for (int n = 0; n < 2; ++n) _Pragma("unroll") for (int k = 0; k < 2; ++k) dst[n][k] = *(const LAS bf16x8*)(lds + PG8_SB(b, h) + boff + n * 2048 + k * 1024); } while (0)
; #define PG8_MMA(ai, bj, At, Bt) do { __builtin_amdgcn_s_setprio(1); _Pragma("unroll") for (int m = 0; m < 4; ++m) _Pragma("unroll") for (int n = 0; n < 2; ++n) _Pragma("unroll") for (int k = 0; k < 2; ++k) \
;         acc[ai][bj][m][n] = __builtin_amdgcn_mfma_f32_16x16x32_bf16(Bt[n][k], At[m][k], acc[ai][bj][m][n], 0, 0, 0); __builtin_amdgcn_s_setprio(0); } while (0)
; #define PG8_WAIT_V(n) asm volatile("s_waitcnt vmcnt(" #n ")" ::: "memory")
; #define PG8_WAIT_L(n) asm volatile("s_waitcnt lgkmcnt(" #n ")" ::: "memory")
; #define PG8_BAR __builtin_amdgcn_s_barrier()
; #define PG8_SCHED __builtin_amdgcn_sched_barrier(0)
; template <class Epi>
; __device__ __forceinline__ void gemm_phase(LAS unsigned char* lds, const Gemm g, const StaticOrder& S, const Epi& E, const int tid) {
;     ...
;         for (int t = 0; t < nt; t += 2) {
;             const bool last = (t == nt - 2);
;             const char* a1 = cA + (size_t)(t + 1) * kstep;
;             const char* a2 = last ? nA : cA + (size_t)(t + 2) * kstep; const char* b2 = last ? nB : cB + (size_t)(t + 2) * kstep;
;             const char* a3 = a2 + kstep; const char* b3 = b2 + kstep;
;             PG8_LDB(B0, 0, 0); PG8_LDB(B1, 0, 1); PG8_SCHED; PG8_LDA(At, 0, 0); PG8_STAGE(PG8_SA(1, 1), a1 + hstepA, voffA);
;             PG8_WAIT_V(8); PG8_WAIT_L(0); PG8_BAR; PG8_MMA(0, 0, At, B0); PG8_MMA(0, 1, At, B1); PG8_BAR; PG8_SCHED;
;             PG8_LDA(At, 0, 1); PG8_STAGE(PG8_SB(0, 0), b2, voffB); PG8_STAGE(PG8_SB(0, 1), b2 + hstepB, voffB); PG8_STAGE(PG8_SA(0, 0), a2, voffA);
;             PG8_WAIT_V(8); PG8_WAIT_L(0); PG8_BAR; PG8_MMA(1, 0, At, B0); PG8_MMA(1, 1, At, B1); PG8_BAR; PG8_SCHED;
.LBB0_185:
	s_add_i32 s38, s36, 2
	s_add_u32 s39, s6, 0x80
	s_addc_u32 s37, s7, 0
	s_add_i32 s62, 0, 0x10000
	s_cmp_eq_u32 s53, s36
	s_cselect_b32 s37, s31, s37
	s_cselect_b32 s36, s30, s39
	s_cselect_b32 s61, s35, s1
	s_cselect_b32 s60, s34, s0
	s_add_i32 s39, 0, 0x14000
	v_add_u32_e32 v152, s62, v168
	v_add_u32_e32 v170, s39, v168
	ds_read_b128 v[82:85], v152
	ds_read_b128 v[86:89], v152 offset:1024
	ds_read_b128 v[138:141], v152 offset:2048
	ds_read_b128 v[152:155], v152 offset:3072
	ds_read_b128 v[156:159], v170
	ds_read_b128 v[160:163], v170 offset:1024
	ds_read_b128 v[164:167], v170 offset:2048
	ds_read_b128 v[170:173], v170 offset:3072
	v_lshl_add_u64 v[194:195], s[6:7], 0, v[150:151]
	s_add_i32 m0, s44, 0xc000
	ds_read_b128 v[174:177], v169
	ds_read_b128 v[178:181], v169 offset:1024
	ds_read_b128 v[182:185], v169 offset:2048
	ds_read_b128 v[186:189], v169 offset:3072
	ds_read_b128 v[190:193], v169 offset:4096
	ds_read_b128 v[202:205], v169 offset:5120
	ds_read_b128 v[206:209], v169 offset:6144
	ds_read_b128 v[210:213], v169 offset:7168
	global_load_lds_dwordx4 v[194:195], off
	v_lshl_add_u64 v[194:195], s[6:7], 0, v[148:149]
	s_add_i32 m0, s44, 0xe000
	s_nop 0
	global_load_lds_dwordx4 v[194:195], off
	s_waitcnt vmcnt(8)
	s_waitcnt lgkmcnt(0)
	s_barrier
	s_setprio 1
	s_waitcnt lgkmcnt(0)
	v_mfma_f32_16x16x32_bf16 v[134:137], v[82:85], v[174:177], v[134:137]
	v_mfma_f32_16x16x32_bf16 v[62:65], v[138:141], v[174:177], v[62:65]
	v_mfma_f32_16x16x32_bf16 v[126:129], v[82:85], v[182:185], v[126:129]
	v_mfma_f32_16x16x32_bf16 v[54:57], v[138:141], v[182:185], v[54:57]
	v_mfma_f32_16x16x32_bf16 v[118:121], v[82:85], v[190:193], v[118:121]
	v_mfma_f32_16x16x32_bf16 v[46:49], v[138:141], v[190:193], v[46:49]
	v_mfma_f32_16x16x32_bf16 v[110:113], v[82:85], v[206:209], v[110:113]
	v_mfma_f32_16x16x32_bf16 v[38:41], v[138:141], v[206:209], v[38:41]
	v_mfma_f32_16x16x32_bf16 v[134:137], v[86:89], v[178:181], v[134:137]
	v_mfma_f32_16x16x32_bf16 v[62:65], v[152:155], v[178:181], v[62:65]
	v_mfma_f32_16x16x32_bf16 v[126:129], v[86:89], v[186:189], v[126:129]
	v_mfma_f32_16x16x32_bf16 v[54:57], v[152:155], v[186:189], v[54:57]
	v_mfma_f32_16x16x32_bf16 v[118:121], v[86:89], v[202:205], v[118:121]
	v_mfma_f32_16x16x32_bf16 v[46:49], v[152:155], v[202:205], v[46:49]
	v_mfma_f32_16x16x32_bf16 v[110:113], v[86:89], v[210:213], v[110:113]
	v_mfma_f32_16x16x32_bf16 v[38:41], v[152:155], v[210:213], v[38:41]
	v_mfma_f32_16x16x32_bf16 v[130:133], v[156:159], v[174:177], v[130:133]
	v_mfma_f32_16x16x32_bf16 v[58:61], v[164:167], v[174:177], v[58:61]
	v_mfma_f32_16x16x32_bf16 v[122:125], v[156:159], v[182:185], v[122:125]
	v_mfma_f32_16x16x32_bf16 v[50:53], v[164:167], v[182:185], v[50:53]
	v_mfma_f32_16x16x32_bf16 v[114:117], v[156:159], v[190:193], v[114:117]
	v_mfma_f32_16x16x32_bf16 v[42:45], v[164:167], v[190:193], v[42:45]
	v_mfma_f32_16x16x32_bf16 v[106:109], v[156:159], v[206:209], v[106:109]
	v_mfma_f32_16x16x32_bf16 v[34:37], v[164:167], v[206:209], v[34:37]
	v_mfma_f32_16x16x32_bf16 v[130:133], v[160:163], v[178:181], v[130:133]
	v_mfma_f32_16x16x32_bf16 v[58:61], v[170:173], v[178:181], v[58:61]
	v_mfma_f32_16x16x32_bf16 v[122:125], v[160:163], v[186:189], v[122:125]
	v_mfma_f32_16x16x32_bf16 v[50:53], v[170:173], v[186:189], v[50:53]
	v_mfma_f32_16x16x32_bf16 v[114:117], v[160:163], v[202:205], v[114:117]
	v_mfma_f32_16x16x32_bf16 v[42:45], v[170:173], v[202:205], v[42:45]
	v_mfma_f32_16x16x32_bf16 v[106:109], v[160:163], v[210:213], v[106:109]
	v_mfma_f32_16x16x32_bf16 v[34:37], v[170:173], v[210:213], v[34:37]
	s_setprio 0
	s_barrier
	s_add_i32 s62, s62, s3
	v_lshl_add_u64 v[194:195], s[60:61], 0, v[0:1]
	s_mov_b32 m0, s62
	ds_read_b128 v[174:177], v169 offset:16384
	ds_read_b128 v[178:181], v169 offset:17408
	ds_read_b128 v[182:185], v169 offset:18432
	ds_read_b128 v[186:189], v169 offset:19456
	ds_read_b128 v[190:193], v169 offset:20480
	ds_read_b128 v[202:205], v169 offset:21504
	ds_read_b128 v[206:209], v169 offset:22528
	ds_read_b128 v[210:213], v169 offset:23552
	global_load_lds_dwordx4 v[194:195], off
	s_add_i32 m0, s62, 0x2000
	v_lshl_add_u64 v[196:197], s[60:61], 0, v[146:147]
	s_add_u32 s60, s60, s12
	s_addc_u32 s61, s61, s13
	s_add_i32 s39, s39, s3
	global_load_lds_dwordx4 v[196:197], off
	v_lshl_add_u64 v[198:199], s[60:61], 0, v[0:1]
	s_mov_b32 m0, s39
	v_lshl_add_u64 v[214:215], s[60:61], 0, v[146:147]
	global_load_lds_dwordx4 v[198:199], off
	s_add_i32 m0, s39, 0x2000
	v_lshl_add_u64 v[216:217], s[36:37], 0, v[142:143]
	global_load_lds_dwordx4 v[214:215], off
	s_mov_b32 m0, s44
	v_lshl_add_u64 v[218:219], s[36:37], 0, v[144:145]
	global_load_lds_dwordx4 v[216:217], off
	s_mov_b32 m0, s45
	s_nop 0
	global_load_lds_dwordx4 v[218:219], off
	s_waitcnt vmcnt(8)
	s_waitcnt lgkmcnt(0)
	s_barrier
	s_setprio 1
	s_waitcnt lgkmcnt(0)
	v_mfma_f32_16x16x32_bf16 v[102:105], v[82:85], v[174:177], v[102:105]
	v_mfma_f32_16x16x32_bf16 v[30:33], v[138:141], v[174:177], v[30:33]
	v_mfma_f32_16x16x32_bf16 v[94:97], v[82:85], v[182:185], v[94:97]
	v_mfma_f32_16x16x32_bf16 v[22:25], v[138:141], v[182:185], v[22:25]
	v_mfma_f32_16x16x32_bf16 v[78:81], v[82:85], v[190:193], v[78:81]
	v_mfma_f32_16x16x32_bf16 v[14:17], v[138:141], v[190:193], v[14:17]
	v_mfma_f32_16x16x32_bf16 v[70:73], v[82:85], v[206:209], v[70:73]
	v_mfma_f32_16x16x32_bf16 v[6:9], v[138:141], v[206:209], v[6:9]
	v_mfma_f32_16x16x32_bf16 v[102:105], v[86:89], v[178:181], v[102:105]
	v_mfma_f32_16x16x32_bf16 v[30:33], v[152:155], v[178:181], v[30:33]
	v_mfma_f32_16x16x32_bf16 v[94:97], v[86:89], v[186:189], v[94:97]
	v_mfma_f32_16x16x32_bf16 v[22:25], v[152:155], v[186:189], v[22:25]
	v_mfma_f32_16x16x32_bf16 v[78:81], v[86:89], v[202:205], v[78:81]
	v_mfma_f32_16x16x32_bf16 v[14:17], v[152:155], v[202:205], v[14:17]
	v_mfma_f32_16x16x32_bf16 v[70:73], v[86:89], v[210:213], v[70:73]
	v_mfma_f32_16x16x32_bf16 v[6:9], v[152:155], v[210:213], v[6:9]
	v_mfma_f32_16x16x32_bf16 v[26:29], v[164:167], v[174:177], v[26:29]
	v_mfma_f32_16x16x32_bf16 v[18:21], v[164:167], v[182:185], v[18:21]
	v_mfma_f32_16x16x32_bf16 v[74:77], v[156:159], v[190:193], v[74:77]
	v_mfma_f32_16x16x32_bf16 v[10:13], v[164:167], v[190:193], v[10:13]
	v_mfma_f32_16x16x32_bf16 v[66:69], v[156:159], v[206:209], v[66:69]
	v_mfma_f32_16x16x32_bf16 v[2:5], v[164:167], v[206:209], v[2:5]
	v_mfma_f32_16x16x32_bf16 v[82:85], v[156:159], v[174:177], v[98:101]
	v_mfma_f32_16x16x32_bf16 v[26:29], v[170:173], v[178:181], v[26:29]
	v_mfma_f32_16x16x32_bf16 v[86:89], v[156:159], v[182:185], v[90:93]
	v_mfma_f32_16x16x32_bf16 v[18:21], v[170:173], v[186:189], v[18:21]
	v_mfma_f32_16x16x32_bf16 v[74:77], v[160:163], v[202:205], v[74:77]
	v_mfma_f32_16x16x32_bf16 v[10:13], v[170:173], v[202:205], v[10:13]
	v_mfma_f32_16x16x32_bf16 v[66:69], v[160:163], v[210:213], v[66:69]
	v_mfma_f32_16x16x32_bf16 v[2:5], v[170:173], v[210:213], v[2:5]
	v_mfma_f32_16x16x32_bf16 v[82:85], v[160:163], v[178:181], v[82:85]
	v_mfma_f32_16x16x32_bf16 v[86:89], v[160:163], v[186:189], v[86:89]
	s_setprio 0
	s_barrier
; #define PG8_STAGE(bufoff, gbase, voff) do { _Pragma("unroll") for (int _i = 0; _i < 2; ++_i) \
;         __builtin_amdgcn_global_load_lds((const unsigned*)((const char*)(gbase) + (voff)[_i]), (LAS unsigned*)(lds + (bufoff) + ldsw + _i * 8192), 16, 0, 0); } while (0)
; #define PG8_LDA(dst, b, h) do { _Pragma("unroll") for (int m = 0; m < 4; ++m) _Pragma("unroll") for (int k = 0; k < 2; ++k) dst[m][k] = *(const LAS bf16x8*)(lds + PG8_SA(b, h) + aoff + m * 2048 + k * 1024); } while (0)
; #define PG8_LDB(dst, b, h) do { _Pragma("unroll") for (int n = 0; n < 2; ++n) _Pragma("unroll") for (int k = 0; k < 2; ++k) dst[n][k] = *(const LAS bf16x8*)(lds + PG8_SB(b, h) + boff + n * 2048 + k * 1024); } while (0)
; #define PG8_MMA(ai, bj, At, Bt) do { __builtin_amdgcn_s_setprio(1); _Pragma("unroll") for (int m = 0; m < 4; ++m) _Pragma("unroll") for (int n = 0; n < 2; ++n) _Pragma("unroll") for (int k = 0; k < 2; ++k) \
;         acc[ai][bj][m][n] = __builtin_amdgcn_mfma_f32_16x16x32_bf16(Bt[n][k], At[m][k], acc[ai][bj][m][n], 0, 0, 0); __builtin_amdgcn_s_setprio(0); } while (0)
; #define PG8_WAIT_V(n) asm volatile("s_waitcnt vmcnt(" #n ")" ::: "memory")
; #define PG8_WAIT_L(n) asm volatile("s_waitcnt lgkmcnt(" #n ")" ::: "memory")
; #define PG8_BAR __builtin_amdgcn_s_barrier()
; #define PG8_SCHED __builtin_amdgcn_sched_barrier(0)
; template <class Epi>
; __device__ __forceinline__ void gemm_phase(LAS unsigned char* lds, const Gemm g, const StaticOrder& S, const Epi& E, const int tid) {
;     ...
;             PG8_LDB(B0, 1, 0); PG8_LDB(B1, 1, 1); PG8_SCHED; PG8_LDA(At, 1, 0); PG8_STAGE(PG8_SA(0, 1), a2 + hstepA, voffA);
;             PG8_WAIT_V(8); PG8_WAIT_L(0); PG8_BAR; PG8_MMA(0, 0, At, B0); PG8_MMA(0, 1, At, B1); PG8_BAR; PG8_SCHED;
.Lkl185_sp2:
	s_add_i32 s39, 0, 0x18000
	s_add_i32 s60, 0, 0x1c000
	v_add_u32_e32 v152, s39, v168
	v_add_u32_e32 v170, s60, v168
	ds_read_b128 v[90:93], v152
	ds_read_b128 v[98:101], v152 offset:1024
	ds_read_b128 v[138:141], v152 offset:2048
	ds_read_b128 v[152:155], v152 offset:3072
	ds_read_b128 v[156:159], v170
	ds_read_b128 v[160:163], v170 offset:1024
	ds_read_b128 v[164:167], v170 offset:2048
	ds_read_b128 v[170:173], v170 offset:3072
	s_add_u32 s36, s36, s10
	s_addc_u32 s37, s37, s11
	s_mov_b32 m0, s46
	v_lshl_add_u64 v[220:221], s[36:37], 0, v[142:143]
	ds_read_b128 v[174:177], v169 offset:32768
	ds_read_b128 v[178:181], v169 offset:33792
	ds_read_b128 v[182:185], v169 offset:34816
	ds_read_b128 v[186:189], v169 offset:35840
	ds_read_b128 v[190:193], v169 offset:36864
	ds_read_b128 v[202:205], v169 offset:37888
	ds_read_b128 v[206:209], v169 offset:38912
	ds_read_b128 v[210:213], v169 offset:39936
	global_load_lds_dwordx4 v[220:221], off
	v_lshl_add_u64 v[220:221], s[36:37], 0, v[144:145]
	s_mov_b32 m0, s47
	s_nop 0
	global_load_lds_dwordx4 v[220:221], off
	s_waitcnt vmcnt(8)
	s_waitcnt lgkmcnt(0)
	s_barrier
	s_setprio 1
	s_waitcnt lgkmcnt(0)
	v_mfma_f32_16x16x32_bf16 v[134:137], v[90:93], v[174:177], v[134:137]
	v_mfma_f32_16x16x32_bf16 v[62:65], v[138:141], v[174:177], v[62:65]
	v_mfma_f32_16x16x32_bf16 v[126:129], v[90:93], v[182:185], v[126:129]
	v_mfma_f32_16x16x32_bf16 v[54:57], v[138:141], v[182:185], v[54:57]
	v_mfma_f32_16x16x32_bf16 v[118:121], v[90:93], v[190:193], v[118:121]
	v_mfma_f32_16x16x32_bf16 v[46:49], v[138:141], v[190:193], v[46:49]
	v_mfma_f32_16x16x32_bf16 v[110:113], v[90:93], v[206:209], v[110:113]
	v_mfma_f32_16x16x32_bf16 v[38:41], v[138:141], v[206:209], v[38:41]
	v_mfma_f32_16x16x32_bf16 v[134:137], v[98:101], v[178:181], v[134:137]
	v_mfma_f32_16x16x32_bf16 v[62:65], v[152:155], v[178:181], v[62:65]
	v_mfma_f32_16x16x32_bf16 v[126:129], v[98:101], v[186:189], v[126:129]
	v_mfma_f32_16x16x32_bf16 v[54:57], v[152:155], v[186:189], v[54:57]
	v_mfma_f32_16x16x32_bf16 v[118:121], v[98:101], v[202:205], v[118:121]
	v_mfma_f32_16x16x32_bf16 v[46:49], v[152:155], v[202:205], v[46:49]
	v_mfma_f32_16x16x32_bf16 v[110:113], v[98:101], v[210:213], v[110:113]
	v_mfma_f32_16x16x32_bf16 v[38:41], v[152:155], v[210:213], v[38:41]
	v_mfma_f32_16x16x32_bf16 v[130:133], v[156:159], v[174:177], v[130:133]
	v_mfma_f32_16x16x32_bf16 v[58:61], v[164:167], v[174:177], v[58:61]
	v_mfma_f32_16x16x32_bf16 v[122:125], v[156:159], v[182:185], v[122:125]
	v_mfma_f32_16x16x32_bf16 v[50:53], v[164:167], v[182:185], v[50:53]
	v_mfma_f32_16x16x32_bf16 v[114:117], v[156:159], v[190:193], v[114:117]
	v_mfma_f32_16x16x32_bf16 v[42:45], v[164:167], v[190:193], v[42:45]
	v_mfma_f32_16x16x32_bf16 v[106:109], v[156:159], v[206:209], v[106:109]
	v_mfma_f32_16x16x32_bf16 v[34:37], v[164:167], v[206:209], v[34:37]
	v_mfma_f32_16x16x32_bf16 v[130:133], v[160:163], v[178:181], v[130:133]
	v_mfma_f32_16x16x32_bf16 v[58:61], v[170:173], v[178:181], v[58:61]
	v_mfma_f32_16x16x32_bf16 v[122:125], v[160:163], v[186:189], v[122:125]
	v_mfma_f32_16x16x32_bf16 v[50:53], v[170:173], v[186:189], v[50:53]
	v_mfma_f32_16x16x32_bf16 v[114:117], v[160:163], v[202:205], v[114:117]
	v_mfma_f32_16x16x32_bf16 v[42:45], v[170:173], v[202:205], v[42:45]
	v_mfma_f32_16x16x32_bf16 v[106:109], v[160:163], v[210:213], v[106:109]
	v_mfma_f32_16x16x32_bf16 v[34:37], v[170:173], v[210:213], v[34:37]
	s_setprio 0
	s_barrier
; #define PG8_STAGE(bufoff, gbase, voff) do { _Pragma("unroll") for (int _i = 0; _i < 2; ++_i) \
;         __builtin_amdgcn_global_load_lds((const unsigned*)((const char*)(gbase) + (voff)[_i]), (LAS unsigned*)(lds + (bufoff) + ldsw + _i * 8192), 16, 0, 0); } while (0)
; #define PG8_LDA(dst, b, h) do { _Pragma("unroll") for (int m = 0; m < 4; ++m) _Pragma("unroll") for (int k = 0; k < 2; ++k) dst[m][k] = *(const LAS bf16x8*)(lds + PG8_SA(b, h) + aoff + m * 2048 + k * 1024); } while (0)
; #define PG8_MMA(ai, bj, At, Bt) do { __builtin_amdgcn_s_setprio(1); _Pragma("unroll") for (int m = 0; m < 4; ++m) _Pragma("unroll") for (int n = 0; n < 2; ++n) _Pragma("unroll") for (int k = 0; k < 2; ++k) \
;         acc[ai][bj][m][n] = __builtin_amdgcn_mfma_f32_16x16x32_bf16(Bt[n][k], At[m][k], acc[ai][bj][m][n], 0, 0, 0); __builtin_amdgcn_s_setprio(0); } while (0)
; #define PG8_WAIT_V(n) asm volatile("s_waitcnt vmcnt(" #n ")" ::: "memory")
; #define PG8_WAIT_L(n) asm volatile("s_waitcnt lgkmcnt(" #n ")" ::: "memory")
; #define PG8_BAR __builtin_amdgcn_s_barrier()
; #define PG8_SCHED __builtin_amdgcn_sched_barrier(0)
; template <class Epi>
; __device__ __forceinline__ void gemm_phase(LAS unsigned char* lds, const Gemm g, const StaticOrder& S, const Epi& E, const int tid) {
;     ...
;             PG8_LDA(At, 1, 1); PG8_STAGE(PG8_SB(1, 0), b3, voffB); PG8_STAGE(PG8_SB(1, 1), b3 + hstepB, voffB); PG8_STAGE(PG8_SA(1, 0), a3, voffA);
;             PG8_WAIT_V(8); PG8_WAIT_L(0); PG8_BAR; PG8_MMA(1, 0, At, B0); PG8_MMA(1, 1, At, B1); PG8_BAR; PG8_SCHED;
;         }
	s_add_i32 s36, s39, s3
	v_lshl_add_u64 v[194:195], v[194:195], 0, s[80:81]
	s_mov_b32 m0, s36
	ds_read_b128 v[174:177], v169 offset:49152
	ds_read_b128 v[178:181], v169 offset:50176
	ds_read_b128 v[182:185], v169 offset:51200
	ds_read_b128 v[186:189], v169 offset:52224
	ds_read_b128 v[190:193], v169 offset:53248
	ds_read_b128 v[202:205], v169 offset:54272
	ds_read_b128 v[206:209], v169 offset:55296
	ds_read_b128 v[210:213], v169 offset:56320
	global_load_lds_dwordx4 v[194:195], off
	v_lshl_add_u64 v[194:195], v[196:197], 0, s[80:81]
	s_add_i32 m0, s36, 0x2000
	s_add_i32 s36, s60, s3
	global_load_lds_dwordx4 v[194:195], off
	v_lshl_add_u64 v[194:195], v[198:199], 0, s[80:81]
	s_mov_b32 m0, s36
	s_nop 0
	global_load_lds_dwordx4 v[194:195], off
	v_lshl_add_u64 v[194:195], v[214:215], 0, s[80:81]
	s_add_i32 m0, s36, 0x2000
	s_nop 0
	global_load_lds_dwordx4 v[194:195], off
	v_lshl_add_u64 v[194:195], v[216:217], 0, s[80:81]
	s_mov_b32 m0, s51
	s_nop 0
	global_load_lds_dwordx4 v[194:195], off
	v_lshl_add_u64 v[194:195], v[218:219], 0, s[80:81]
	s_mov_b32 m0, s52
	s_nop 0
	global_load_lds_dwordx4 v[194:195], off
	s_waitcnt vmcnt(8)
	s_waitcnt lgkmcnt(0)
	s_nop 0
	s_barrier
	s_setprio 1
	s_waitcnt lgkmcnt(0)
	v_mfma_f32_16x16x32_bf16 v[102:105], v[90:93], v[174:177], v[102:105]
	v_mfma_f32_16x16x32_bf16 v[30:33], v[138:141], v[174:177], v[30:33]
	v_mfma_f32_16x16x32_bf16 v[94:97], v[90:93], v[182:185], v[94:97]
	v_mfma_f32_16x16x32_bf16 v[22:25], v[138:141], v[182:185], v[22:25]
	v_mfma_f32_16x16x32_bf16 v[78:81], v[90:93], v[190:193], v[78:81]
	v_mfma_f32_16x16x32_bf16 v[14:17], v[138:141], v[190:193], v[14:17]
	v_mfma_f32_16x16x32_bf16 v[70:73], v[90:93], v[206:209], v[70:73]
	v_mfma_f32_16x16x32_bf16 v[6:9], v[138:141], v[206:209], v[6:9]
	v_mfma_f32_16x16x32_bf16 v[102:105], v[98:101], v[178:181], v[102:105]
	v_mfma_f32_16x16x32_bf16 v[30:33], v[152:155], v[178:181], v[30:33]
	v_mfma_f32_16x16x32_bf16 v[94:97], v[98:101], v[186:189], v[94:97]
	v_mfma_f32_16x16x32_bf16 v[22:25], v[152:155], v[186:189], v[22:25]
	v_mfma_f32_16x16x32_bf16 v[78:81], v[98:101], v[202:205], v[78:81]
	v_mfma_f32_16x16x32_bf16 v[14:17], v[152:155], v[202:205], v[14:17]
	v_mfma_f32_16x16x32_bf16 v[70:73], v[98:101], v[210:213], v[70:73]
	v_mfma_f32_16x16x32_bf16 v[6:9], v[152:155], v[210:213], v[6:9]
	v_mfma_f32_16x16x32_bf16 v[82:85], v[156:159], v[174:177], v[82:85]
	v_mfma_f32_16x16x32_bf16 v[98:101], v[160:163], v[178:181], v[82:85]
	v_mfma_f32_16x16x32_bf16 v[26:29], v[164:167], v[174:177], v[26:29]
	v_mfma_f32_16x16x32_bf16 v[82:85], v[156:159], v[182:185], v[86:89]
	v_mfma_f32_16x16x32_bf16 v[18:21], v[164:167], v[182:185], v[18:21]
	v_mfma_f32_16x16x32_bf16 v[74:77], v[156:159], v[190:193], v[74:77]
	v_mfma_f32_16x16x32_bf16 v[10:13], v[164:167], v[190:193], v[10:13]
	v_mfma_f32_16x16x32_bf16 v[66:69], v[156:159], v[206:209], v[66:69]
	v_mfma_f32_16x16x32_bf16 v[2:5], v[164:167], v[206:209], v[2:5]
	v_mfma_f32_16x16x32_bf16 v[26:29], v[170:173], v[178:181], v[26:29]
	v_mfma_f32_16x16x32_bf16 v[90:93], v[160:163], v[186:189], v[82:85]
	v_mfma_f32_16x16x32_bf16 v[18:21], v[170:173], v[186:189], v[18:21]
	v_mfma_f32_16x16x32_bf16 v[74:77], v[160:163], v[202:205], v[74:77]
	v_mfma_f32_16x16x32_bf16 v[10:13], v[170:173], v[202:205], v[10:13]
	v_mfma_f32_16x16x32_bf16 v[66:69], v[160:163], v[210:213], v[66:69]
	v_mfma_f32_16x16x32_bf16 v[2:5], v[170:173], v[210:213], v[2:5]
	s_setprio 0
	s_barrier
	s_add_u32 s0, s0, 0x100
	s_addc_u32 s1, s1, 0
	s_add_u32 s6, s6, 0x100
	s_addc_u32 s7, s7, 0
	s_cmp_ge_i32 s38, s48
	s_mov_b32 s36, s38
	s_cbranch_scc0 .LBB0_185
	s_movk_i32 s61, 0xf000
	s_mov_b32 s60, 0x800000

; #define PG8_STAGE(bufoff, gbase, voff) do { _Pragma("unroll") for (int _i = 0; _i < 2; ++_i) \
;         __builtin_amdgcn_global_load_lds((const unsigned*)((const char*)(gbase) + (voff)[_i]), (LAS unsigned*)(lds + (bufoff) + ldsw + _i * 8192), 16, 0, 0); } while (0)
; #define PG8_LDA(dst, b, h) do { _Pragma("unroll") for (int m = 0; m < 4; ++m) _Pragma("unroll") for (int k = 0; k < 2; ++k) dst[m][k] = *(const LAS bf16x8*)(lds + PG8_SA(b, h) + aoff + m * 2048 + k * 1024); } while (0)
; #define PG8_LDB(dst, b, h) do { _Pragma("unroll") for (int n = 0; n < 2; ++n) _Pragma("unroll") for (int k = 0; k < 2; ++k) dst[n][k] = *(const LAS bf16x8*)(lds + PG8_SB(b, h) + boff + n * 2048 + k * 1024); } while (0)
; #define PG8_MMA(ai, bj, At, Bt) do { __builtin_amdgcn_s_setprio(1); _Pragma("unroll") for (int m = 0; m < 4; ++m) _Pragma("unroll") for (int n = 0; n < 2; ++n) _Pragma("unroll") for (int k = 0; k < 2; ++k) \
;         acc[ai][bj][m][n] = __builtin_amdgcn_mfma_f32_16x16x32_bf16(Bt[n][k], At[m][k], acc[ai][bj][m][n], 0, 0, 0); __builtin_amdgcn_s_setprio(0); } while (0)
; #define PG8_WAIT_V(n) asm volatile("s_waitcnt vmcnt(" #n ")" ::: "memory")
; #define PG8_WAIT_L(n) asm volatile("s_waitcnt lgkmcnt(" #n ")" ::: "memory")
; #define PG8_BAR __builtin_amdgcn_s_barrier()
; #define PG8_SCHED __builtin_amdgcn_sched_barrier(0)
; template <class Epi>
; __device__ __forceinline__ void gemm_phase(LAS unsigned char* lds, const Gemm g, const StaticOrder& S, const Epi& E, const int tid) {
;     ...
;             PG8_LDB(B0, 0, 0); PG8_LDB(B1, 0, 1); PG8_SCHED; PG8_LDA(At, 0, 0); PG8_STAGE(PG8_SA(1, 1), a1 + hstepA, voffA);
;             PG8_WAIT_V(8); PG8_WAIT_L(0); PG8_BAR; PG8_MMA(0, 0, At, B0); PG8_MMA(0, 1, At, B1); PG8_BAR; PG8_SCHED;
;             PG8_LDA(At, 0, 1); PG8_STAGE(PG8_SB(0, 0), b2, voffB); PG8_STAGE(PG8_SB(0, 1), b2 + hstepB, voffB); PG8_STAGE(PG8_SA(0, 0), a2, voffA);
.Lkl298_nofa:
	s_waitcnt vmcnt(18)
	s_waitcnt lgkmcnt(0)
	s_nop 0
	s_barrier
	s_setprio 1
	s_waitcnt lgkmcnt(0)
	v_mfma_f32_16x16x32_bf16 v[122:125], v[130:133], v[162:165], 0
	v_mfma_f32_16x16x32_bf16 v[126:129], v[138:141], v[162:165], 0
	v_mfma_f32_16x16x32_bf16 v[110:113], v[130:133], v[170:173], 0
	v_mfma_f32_16x16x32_bf16 v[106:109], v[138:141], v[170:173], 0
	v_mfma_f32_16x16x32_bf16 v[94:97], v[130:133], v[178:181], 0
	v_mfma_f32_16x16x32_bf16 v[90:93], v[138:141], v[178:181], 0
	v_mfma_f32_16x16x32_bf16 v[78:81], v[130:133], v[186:189], 0
	v_mfma_f32_16x16x32_bf16 v[74:77], v[138:141], v[186:189], 0
	v_mfma_f32_16x16x32_bf16 v[122:125], v[134:137], v[166:169], v[122:125]
	v_mfma_f32_16x16x32_bf16 v[126:129], v[142:145], v[166:169], v[126:129]
	v_mfma_f32_16x16x32_bf16 v[110:113], v[134:137], v[174:177], v[110:113]
	v_mfma_f32_16x16x32_bf16 v[106:109], v[142:145], v[174:177], v[106:109]
	v_mfma_f32_16x16x32_bf16 v[94:97], v[134:137], v[182:185], v[94:97]
	v_mfma_f32_16x16x32_bf16 v[90:93], v[142:145], v[182:185], v[90:93]
	v_mfma_f32_16x16x32_bf16 v[78:81], v[134:137], v[190:193], v[78:81]
	v_mfma_f32_16x16x32_bf16 v[74:77], v[142:145], v[190:193], v[74:77]
	v_mfma_f32_16x16x32_bf16 v[118:121], v[146:149], v[162:165], 0
	v_mfma_f32_16x16x32_bf16 v[114:117], v[154:157], v[162:165], 0
	v_mfma_f32_16x16x32_bf16 v[102:105], v[146:149], v[170:173], 0
	v_mfma_f32_16x16x32_bf16 v[98:101], v[154:157], v[170:173], 0
	v_mfma_f32_16x16x32_bf16 v[86:89], v[146:149], v[178:181], 0
	v_mfma_f32_16x16x32_bf16 v[82:85], v[154:157], v[178:181], 0
	v_mfma_f32_16x16x32_bf16 v[70:73], v[146:149], v[186:189], 0
	v_mfma_f32_16x16x32_bf16 v[66:69], v[154:157], v[186:189], 0
	v_mfma_f32_16x16x32_bf16 v[118:121], v[150:153], v[166:169], v[118:121]
	v_mfma_f32_16x16x32_bf16 v[114:117], v[158:161], v[166:169], v[114:117]
	v_mfma_f32_16x16x32_bf16 v[102:105], v[150:153], v[174:177], v[102:105]
	v_mfma_f32_16x16x32_bf16 v[98:101], v[158:161], v[174:177], v[98:101]
	v_mfma_f32_16x16x32_bf16 v[86:89], v[150:153], v[182:185], v[86:89]
	v_mfma_f32_16x16x32_bf16 v[82:85], v[158:161], v[182:185], v[82:85]
	v_mfma_f32_16x16x32_bf16 v[70:73], v[150:153], v[190:193], v[70:73]
	v_mfma_f32_16x16x32_bf16 v[66:69], v[158:161], v[190:193], v[66:69]
	s_setprio 0
	s_barrier
	s_add_i32 s60, s60, s11
	v_lshl_add_u64 v[212:213], s[58:59], 0, v[0:1]
	s_mov_b32 m0, s60
	ds_read_b128 v[162:165], v194 offset:16384
	ds_read_b128 v[166:169], v194 offset:17408
	ds_read_b128 v[170:173], v194 offset:18432
	ds_read_b128 v[174:177], v194 offset:19456
	ds_read_b128 v[178:181], v194 offset:20480
	ds_read_b128 v[182:185], v194 offset:21504
	ds_read_b128 v[186:189], v194 offset:22528
	ds_read_b128 v[190:193], v194 offset:23552
	global_load_lds_dwordx4 v[212:213], off
	s_add_i32 m0, s60, 0x2000
	v_lshl_add_u64 v[214:215], s[58:59], 0, v[206:207]
	s_add_u32 s58, s58, s14
	s_addc_u32 s59, s59, s15
	s_add_i32 s37, s37, s11
	global_load_lds_dwordx4 v[214:215], off
	v_lshl_add_u64 v[216:217], s[58:59], 0, v[0:1]
	s_mov_b32 m0, s37
	v_lshl_add_u64 v[218:219], s[58:59], 0, v[206:207]
	global_load_lds_dwordx4 v[216:217], off
	s_add_i32 m0, s37, 0x2000
	v_lshl_add_u64 v[220:221], s[34:35], 0, v[202:203]
	global_load_lds_dwordx4 v[218:219], off
	s_mov_b32 m0, s38
	v_lshl_add_u64 v[222:223], s[34:35], 0, v[204:205]
	global_load_lds_dwordx4 v[220:221], off
	s_mov_b32 m0, s39
	s_nop 0
	global_load_lds_dwordx4 v[222:223], off
	s_cmp_eq_u32 s53, 1
	s_cbranch_scc1 .Lkl298_w1f
	s_waitcnt vmcnt(24)
	s_branch .Lkl298_w1j

; #define PG8_STAGE(bufoff, gbase, voff) do { _Pragma("unroll") for (int _i = 0; _i < 2; ++_i) \
;         __builtin_amdgcn_global_load_lds((const unsigned*)((const char*)(gbase) + (voff)[_i]), (LAS unsigned*)(lds + (bufoff) + ldsw + _i * 8192), 16, 0, 0); } while (0)
; #define PG8_LDA(dst, b, h) do { _Pragma("unroll") for (int m = 0; m < 4; ++m) _Pragma("unroll") for (int k = 0; k < 2; ++k) dst[m][k] = *(const LAS bf16x8*)(lds + PG8_SA(b, h) + aoff + m * 2048 + k * 1024); } while (0)
; #define PG8_LDB(dst, b, h) do { _Pragma("unroll") for (int n = 0; n < 2; ++n) _Pragma("unroll") for (int k = 0; k < 2; ++k) dst[n][k] = *(const LAS bf16x8*)(lds + PG8_SB(b, h) + boff + n * 2048 + k * 1024); } while (0)
; #define PG8_MMA(ai, bj, At, Bt) do { __builtin_amdgcn_s_setprio(1); _Pragma("unroll") for (int m = 0; m < 4; ++m) _Pragma("unroll") for (int n = 0; n < 2; ++n) _Pragma("unroll") for (int k = 0; k < 2; ++k) \
;         acc[ai][bj][m][n] = __builtin_amdgcn_mfma_f32_16x16x32_bf16(Bt[n][k], At[m][k], acc[ai][bj][m][n], 0, 0, 0); __builtin_amdgcn_s_setprio(0); } while (0)
; #define PG8_WAIT_V(n) asm volatile("s_waitcnt vmcnt(" #n ")" ::: "memory")
; #define PG8_WAIT_L(n) asm volatile("s_waitcnt lgkmcnt(" #n ")" ::: "memory")
; #define PG8_BAR __builtin_amdgcn_s_barrier()
; #define PG8_SCHED __builtin_amdgcn_sched_barrier(0)
; template <class Epi>
; __device__ __forceinline__ void gemm_phase(LAS unsigned char* lds, const Gemm g, const StaticOrder& S, const Epi& E, const int tid) {
;     ...
;             PG8_WAIT_V(8); PG8_WAIT_L(0); PG8_BAR; PG8_MMA(1, 0, At, B0); PG8_MMA(1, 1, At, B1); PG8_BAR; PG8_SCHED;
;             PG8_LDB(B0, 1, 0); PG8_LDB(B1, 1, 1); PG8_SCHED; PG8_LDA(At, 1, 0); PG8_STAGE(PG8_SA(0, 1), a2 + hstepA, voffA);
.Lkl298_w1j:
	s_waitcnt lgkmcnt(0)
	s_barrier
	s_setprio 1
	s_waitcnt lgkmcnt(0)
	v_mfma_f32_16x16x32_bf16 v[62:65], v[130:133], v[162:165], 0
	v_mfma_f32_16x16x32_bf16 v[58:61], v[138:141], v[162:165], 0
	v_mfma_f32_16x16x32_bf16 v[46:49], v[130:133], v[170:173], 0
	v_mfma_f32_16x16x32_bf16 v[42:45], v[138:141], v[170:173], 0
	v_mfma_f32_16x16x32_bf16 v[30:33], v[130:133], v[178:181], 0
	v_mfma_f32_16x16x32_bf16 v[26:29], v[138:141], v[178:181], 0
	v_mfma_f32_16x16x32_bf16 v[14:17], v[130:133], v[186:189], 0
	v_mfma_f32_16x16x32_bf16 v[10:13], v[138:141], v[186:189], 0
	v_mfma_f32_16x16x32_bf16 v[62:65], v[134:137], v[166:169], v[62:65]
	v_mfma_f32_16x16x32_bf16 v[58:61], v[142:145], v[166:169], v[58:61]
	v_mfma_f32_16x16x32_bf16 v[46:49], v[134:137], v[174:177], v[46:49]
	v_mfma_f32_16x16x32_bf16 v[42:45], v[142:145], v[174:177], v[42:45]
	v_mfma_f32_16x16x32_bf16 v[30:33], v[134:137], v[182:185], v[30:33]
	v_mfma_f32_16x16x32_bf16 v[26:29], v[142:145], v[182:185], v[26:29]
	v_mfma_f32_16x16x32_bf16 v[14:17], v[134:137], v[190:193], v[14:17]
	v_mfma_f32_16x16x32_bf16 v[10:13], v[142:145], v[190:193], v[10:13]
	v_mfma_f32_16x16x32_bf16 v[54:57], v[146:149], v[162:165], 0
	v_mfma_f32_16x16x32_bf16 v[50:53], v[154:157], v[162:165], 0
	v_mfma_f32_16x16x32_bf16 v[38:41], v[146:149], v[170:173], 0
	v_mfma_f32_16x16x32_bf16 v[34:37], v[154:157], v[170:173], 0
	v_mfma_f32_16x16x32_bf16 v[22:25], v[146:149], v[178:181], 0
	v_mfma_f32_16x16x32_bf16 v[18:21], v[154:157], v[178:181], 0
	v_mfma_f32_16x16x32_bf16 v[6:9], v[146:149], v[186:189], 0
	v_mfma_f32_16x16x32_bf16 v[2:5], v[154:157], v[186:189], 0
	v_mfma_f32_16x16x32_bf16 v[54:57], v[150:153], v[166:169], v[54:57]
	v_mfma_f32_16x16x32_bf16 v[50:53], v[158:161], v[166:169], v[50:53]
	v_mfma_f32_16x16x32_bf16 v[38:41], v[150:153], v[174:177], v[38:41]
	v_mfma_f32_16x16x32_bf16 v[34:37], v[158:161], v[174:177], v[34:37]
	v_mfma_f32_16x16x32_bf16 v[22:25], v[150:153], v[182:185], v[22:25]
	v_mfma_f32_16x16x32_bf16 v[18:21], v[158:161], v[182:185], v[18:21]
	v_mfma_f32_16x16x32_bf16 v[6:9], v[150:153], v[190:193], v[6:9]
	v_mfma_f32_16x16x32_bf16 v[2:5], v[158:161], v[190:193], v[2:5]
	s_setprio 0
	s_barrier
	s_add_i32 s37, 0, 0x18000
	s_add_i32 s58, 0, 0x1c000
	v_add_u32_e32 v142, s37, v248
	v_add_u32_e32 v158, s58, v248
	ds_read_b128 v[130:133], v142
	ds_read_b128 v[134:137], v142 offset:1024
	ds_read_b128 v[138:141], v142 offset:2048
	ds_read_b128 v[142:145], v142 offset:3072
	ds_read_b128 v[146:149], v158
	ds_read_b128 v[150:153], v158 offset:1024
	ds_read_b128 v[154:157], v158 offset:2048
	ds_read_b128 v[158:161], v158 offset:3072
	s_add_u32 s34, s34, s12
	s_addc_u32 s35, s35, s13
	s_mov_b32 m0, s43
	v_lshl_add_u64 v[224:225], s[34:35], 0, v[202:203]
	ds_read_b128 v[162:165], v194 offset:32768
	ds_read_b128 v[166:169], v194 offset:33792
	ds_read_b128 v[170:173], v194 offset:34816
	ds_read_b128 v[174:177], v194 offset:35840
	ds_read_b128 v[178:181], v194 offset:36864
	ds_read_b128 v[182:185], v194 offset:37888
	ds_read_b128 v[186:189], v194 offset:38912
	ds_read_b128 v[190:193], v194 offset:39936
	global_load_lds_dwordx4 v[224:225], off
	v_lshl_add_u64 v[224:225], s[34:35], 0, v[204:205]
	s_mov_b32 m0, s44
	s_nop 0
	global_load_lds_dwordx4 v[224:225], off
	s_cmp_eq_u32 s53, 1
	s_cbranch_scc1 .Lkl298_w2f
	s_waitcnt vmcnt(24)
	s_branch .Lkl298_w2j

; #define PG8_STAGE(bufoff, gbase, voff) do { _Pragma("unroll") for (int _i = 0; _i < 2; ++_i) \
;         __builtin_amdgcn_global_load_lds((const unsigned*)((const char*)(gbase) + (voff)[_i]), (LAS unsigned*)(lds + (bufoff) + ldsw + _i * 8192), 16, 0, 0); } while (0)
; #define PG8_LDA(dst, b, h) do { _Pragma("unroll") for (int m = 0; m < 4; ++m) _Pragma("unroll") for (int k = 0; k < 2; ++k) dst[m][k] = *(const LAS bf16x8*)(lds + PG8_SA(b, h) + aoff + m * 2048 + k * 1024); } while (0)
; #define PG8_LDB(dst, b, h) do { _Pragma("unroll") for (int n = 0; n < 2; ++n) _Pragma("unroll") for (int k = 0; k < 2; ++k) dst[n][k] = *(const LAS bf16x8*)(lds + PG8_SB(b, h) + boff + n * 2048 + k * 1024); } while (0)
; #define PG8_MMA(ai, bj, At, Bt) do { __builtin_amdgcn_s_setprio(1); _Pragma("unroll") for (int m = 0; m < 4; ++m) _Pragma("unroll") for (int n = 0; n < 2; ++n) _Pragma("unroll") for (int k = 0; k < 2; ++k) \
;         acc[ai][bj][m][n] = __builtin_amdgcn_mfma_f32_16x16x32_bf16(Bt[n][k], At[m][k], acc[ai][bj][m][n], 0, 0, 0); __builtin_amdgcn_s_setprio(0); } while (0)
; #define PG8_WAIT_V(n) asm volatile("s_waitcnt vmcnt(" #n ")" ::: "memory")
; #define PG8_WAIT_L(n) asm volatile("s_waitcnt lgkmcnt(" #n ")" ::: "memory")
; #define PG8_BAR __builtin_amdgcn_s_barrier()
; #define PG8_SCHED __builtin_amdgcn_sched_barrier(0)
; template <class Epi>
; __device__ __forceinline__ void gemm_phase(LAS unsigned char* lds, const Gemm g, const StaticOrder& S, const Epi& E, const int tid) {
;     ...
;         for (int t = 0; t < nt; t += 2) {
;             const bool last = (t == nt - 2);
;             const char* a1 = cA + (size_t)(t + 1) * kstep;
;             const char* a2 = last ? nA : cA + (size_t)(t + 2) * kstep; const char* b2 = last ? nB : cB + (size_t)(t + 2) * kstep;
;             const char* a3 = a2 + kstep; const char* b3 = b2 + kstep;
;             PG8_LDB(B0, 0, 0); PG8_LDB(B1, 0, 1); PG8_SCHED; PG8_LDA(At, 0, 0); PG8_STAGE(PG8_SA(1, 1), a1 + hstepA, voffA);
;             PG8_WAIT_V(8); PG8_WAIT_L(0); PG8_BAR; PG8_MMA(0, 0, At, B0); PG8_MMA(0, 1, At, B1); PG8_BAR; PG8_SCHED;
;     ...
;             PG8_WAIT_V(8); PG8_WAIT_L(0); PG8_BAR; PG8_MMA(0, 0, At, B0); PG8_MMA(0, 1, At, B1); PG8_BAR; PG8_SCHED;
.Lkl298_w2j:
	s_waitcnt lgkmcnt(0)
	s_barrier
	s_setprio 1
	s_waitcnt lgkmcnt(0)
	v_mfma_f32_16x16x32_bf16 v[122:125], v[130:133], v[162:165], v[122:125]
	v_mfma_f32_16x16x32_bf16 v[126:129], v[138:141], v[162:165], v[126:129]
	v_mfma_f32_16x16x32_bf16 v[110:113], v[130:133], v[170:173], v[110:113]
	v_mfma_f32_16x16x32_bf16 v[106:109], v[138:141], v[170:173], v[106:109]
	v_mfma_f32_16x16x32_bf16 v[94:97], v[130:133], v[178:181], v[94:97]
	v_mfma_f32_16x16x32_bf16 v[90:93], v[138:141], v[178:181], v[90:93]
	v_mfma_f32_16x16x32_bf16 v[78:81], v[130:133], v[186:189], v[78:81]
	v_mfma_f32_16x16x32_bf16 v[74:77], v[138:141], v[186:189], v[74:77]
	v_mfma_f32_16x16x32_bf16 v[122:125], v[134:137], v[166:169], v[122:125]
	v_mfma_f32_16x16x32_bf16 v[126:129], v[142:145], v[166:169], v[126:129]
	v_mfma_f32_16x16x32_bf16 v[110:113], v[134:137], v[174:177], v[110:113]
	v_mfma_f32_16x16x32_bf16 v[106:109], v[142:145], v[174:177], v[106:109]
	v_mfma_f32_16x16x32_bf16 v[94:97], v[134:137], v[182:185], v[94:97]
	v_mfma_f32_16x16x32_bf16 v[90:93], v[142:145], v[182:185], v[90:93]
	v_mfma_f32_16x16x32_bf16 v[78:81], v[134:137], v[190:193], v[78:81]
	v_mfma_f32_16x16x32_bf16 v[74:77], v[142:145], v[190:193], v[74:77]
	v_mfma_f32_16x16x32_bf16 v[118:121], v[146:149], v[162:165], v[118:121]
	v_mfma_f32_16x16x32_bf16 v[114:117], v[154:157], v[162:165], v[114:117]
	v_mfma_f32_16x16x32_bf16 v[102:105], v[146:149], v[170:173], v[102:105]
	v_mfma_f32_16x16x32_bf16 v[98:101], v[154:157], v[170:173], v[98:101]
	v_mfma_f32_16x16x32_bf16 v[86:89], v[146:149], v[178:181], v[86:89]
	v_mfma_f32_16x16x32_bf16 v[82:85], v[154:157], v[178:181], v[82:85]
	v_mfma_f32_16x16x32_bf16 v[70:73], v[146:149], v[186:189], v[70:73]
	v_mfma_f32_16x16x32_bf16 v[66:69], v[154:157], v[186:189], v[66:69]
	v_mfma_f32_16x16x32_bf16 v[118:121], v[150:153], v[166:169], v[118:121]
	v_mfma_f32_16x16x32_bf16 v[114:117], v[158:161], v[166:169], v[114:117]
	v_mfma_f32_16x16x32_bf16 v[102:105], v[150:153], v[174:177], v[102:105]
	v_mfma_f32_16x16x32_bf16 v[98:101], v[158:161], v[174:177], v[98:101]
	v_mfma_f32_16x16x32_bf16 v[86:89], v[150:153], v[182:185], v[86:89]
	v_mfma_f32_16x16x32_bf16 v[82:85], v[158:161], v[182:185], v[82:85]
	v_mfma_f32_16x16x32_bf16 v[70:73], v[150:153], v[190:193], v[70:73]
	v_mfma_f32_16x16x32_bf16 v[66:69], v[158:161], v[190:193], v[66:69]
	s_setprio 0
	s_barrier
	s_branch .Lkl298_sp3
.LBB0_298:
	s_add_i32 s36, s34, 2
	s_add_u32 s37, s6, 0x80
	s_addc_u32 s35, s7, 0
	s_add_i32 s60, 0, 0x10000
	s_cmp_eq_u32 s51, s34
	s_cselect_b32 s35, s29, s35
	s_cselect_b32 s34, s28, s37
	s_cselect_b32 s59, s31, s1
	s_cselect_b32 s58, s30, s0
	s_add_i32 s37, 0, 0x14000
	v_add_u32_e32 v142, s60, v248
	v_add_u32_e32 v158, s37, v248
	ds_read_b128 v[130:133], v142
	ds_read_b128 v[134:137], v142 offset:1024
	ds_read_b128 v[138:141], v142 offset:2048
	ds_read_b128 v[142:145], v142 offset:3072
	ds_read_b128 v[146:149], v158
	ds_read_b128 v[150:153], v158 offset:1024
	ds_read_b128 v[154:157], v158 offset:2048
	ds_read_b128 v[158:161], v158 offset:3072
	v_lshl_add_u64 v[212:213], s[6:7], 0, v[210:211]
	s_add_i32 m0, s38, 0xc000
	ds_read_b128 v[162:165], v194
	ds_read_b128 v[166:169], v194 offset:1024
	ds_read_b128 v[170:173], v194 offset:2048
	ds_read_b128 v[174:177], v194 offset:3072
	ds_read_b128 v[178:181], v194 offset:4096
	ds_read_b128 v[182:185], v194 offset:5120
	ds_read_b128 v[186:189], v194 offset:6144
	ds_read_b128 v[190:193], v194 offset:7168
	global_load_lds_dwordx4 v[212:213], off
	v_lshl_add_u64 v[212:213], s[6:7], 0, v[208:209]
	s_add_i32 m0, s38, 0xe000
	s_nop 0
	global_load_lds_dwordx4 v[212:213], off
	s_waitcnt vmcnt(8)
	s_waitcnt lgkmcnt(0)
	s_barrier
	s_setprio 1
	s_waitcnt lgkmcnt(0)
	v_mfma_f32_16x16x32_bf16 v[122:125], v[130:133], v[162:165], v[122:125]
	v_mfma_f32_16x16x32_bf16 v[126:129], v[138:141], v[162:165], v[126:129]
	v_mfma_f32_16x16x32_bf16 v[110:113], v[130:133], v[170:173], v[110:113]
	v_mfma_f32_16x16x32_bf16 v[106:109], v[138:141], v[170:173], v[106:109]
	v_mfma_f32_16x16x32_bf16 v[94:97], v[130:133], v[178:181], v[94:97]
	v_mfma_f32_16x16x32_bf16 v[90:93], v[138:141], v[178:181], v[90:93]
	v_mfma_f32_16x16x32_bf16 v[78:81], v[130:133], v[186:189], v[78:81]
	v_mfma_f32_16x16x32_bf16 v[74:77], v[138:141], v[186:189], v[74:77]
	v_mfma_f32_16x16x32_bf16 v[122:125], v[134:137], v[166:169], v[122:125]
	v_mfma_f32_16x16x32_bf16 v[126:129], v[142:145], v[166:169], v[126:129]
	v_mfma_f32_16x16x32_bf16 v[110:113], v[134:137], v[174:177], v[110:113]
	v_mfma_f32_16x16x32_bf16 v[106:109], v[142:145], v[174:177], v[106:109]
	v_mfma_f32_16x16x32_bf16 v[94:97], v[134:137], v[182:185], v[94:97]
	v_mfma_f32_16x16x32_bf16 v[90:93], v[142:145], v[182:185], v[90:93]
	v_mfma_f32_16x16x32_bf16 v[78:81], v[134:137], v[190:193], v[78:81]
	v_mfma_f32_16x16x32_bf16 v[74:77], v[142:145], v[190:193], v[74:77]
	v_mfma_f32_16x16x32_bf16 v[118:121], v[146:149], v[162:165], v[118:121]
	v_mfma_f32_16x16x32_bf16 v[114:117], v[154:157], v[162:165], v[114:117]
	v_mfma_f32_16x16x32_bf16 v[102:105], v[146:149], v[170:173], v[102:105]
	v_mfma_f32_16x16x32_bf16 v[98:101], v[154:157], v[170:173], v[98:101]
	v_mfma_f32_16x16x32_bf16 v[86:89], v[146:149], v[178:181], v[86:89]
	v_mfma_f32_16x16x32_bf16 v[82:85], v[154:157], v[178:181], v[82:85]
	v_mfma_f32_16x16x32_bf16 v[70:73], v[146:149], v[186:189], v[70:73]
	v_mfma_f32_16x16x32_bf16 v[66:69], v[154:157], v[186:189], v[66:69]
	v_mfma_f32_16x16x32_bf16 v[118:121], v[150:153], v[166:169], v[118:121]
	v_mfma_f32_16x16x32_bf16 v[114:117], v[158:161], v[166:169], v[114:117]
	v_mfma_f32_16x16x32_bf16 v[102:105], v[150:153], v[174:177], v[102:105]
	v_mfma_f32_16x16x32_bf16 v[98:101], v[158:161], v[174:177], v[98:101]
	v_mfma_f32_16x16x32_bf16 v[86:89], v[150:153], v[182:185], v[86:89]
	v_mfma_f32_16x16x32_bf16 v[82:85], v[158:161], v[182:185], v[82:85]
	v_mfma_f32_16x16x32_bf16 v[70:73], v[150:153], v[190:193], v[70:73]
	v_mfma_f32_16x16x32_bf16 v[66:69], v[158:161], v[190:193], v[66:69]
	s_setprio 0
	s_barrier
; #define PG8_STAGE(bufoff, gbase, voff) do { _Pragma("unroll") for (int _i = 0; _i < 2; ++_i) \
;         __builtin_amdgcn_global_load_lds((const unsigned*)((const char*)(gbase) + (voff)[_i]), (LAS unsigned*)(lds + (bufoff) + ldsw + _i * 8192), 16, 0, 0); } while (0)
; #define PG8_LDA(dst, b, h) do { _Pragma("unroll") for (int m = 0; m < 4; ++m) _Pragma("unroll") for (int k = 0; k < 2; ++k) dst[m][k] = *(const LAS bf16x8*)(lds + PG8_SA(b, h) + aoff + m * 2048 + k * 1024); } while (0)
; #define PG8_LDB(dst, b, h) do { _Pragma("unroll") for (int n = 0; n < 2; ++n) _Pragma("unroll") for (int k = 0; k < 2; ++k) dst[n][k] = *(const LAS bf16x8*)(lds + PG8_SB(b, h) + boff + n * 2048 + k * 1024); } while (0)
; #define PG8_MMA(ai, bj, At, Bt) do { __builtin_amdgcn_s_setprio(1); _Pragma("unroll") for (int m = 0; m < 4; ++m) _Pragma("unroll") for (int n = 0; n < 2; ++n) _Pragma("unroll") for (int k = 0; k < 2; ++k) \
;         acc[ai][bj][m][n] = __builtin_amdgcn_mfma_f32_16x16x32_bf16(Bt[n][k], At[m][k], acc[ai][bj][m][n], 0, 0, 0); __builtin_amdgcn_s_setprio(0); } while (0)
; #define PG8_WAIT_V(n) asm volatile("s_waitcnt vmcnt(" #n ")" ::: "memory")
; #define PG8_WAIT_L(n) asm volatile("s_waitcnt lgkmcnt(" #n ")" ::: "memory")
; #define PG8_BAR __builtin_amdgcn_s_barrier()
; #define PG8_SCHED __builtin_amdgcn_sched_barrier(0)
; template <class Epi>
; __device__ __forceinline__ void gemm_phase(LAS unsigned char* lds, const Gemm g, const StaticOrder& S, const Epi& E, const int tid) {
;     ...
;             PG8_LDA(At, 0, 1); PG8_STAGE(PG8_SB(0, 0), b2, voffB); PG8_STAGE(PG8_SB(0, 1), b2 + hstepB, voffB); PG8_STAGE(PG8_SA(0, 0), a2, voffA);
;             PG8_WAIT_V(8); PG8_WAIT_L(0); PG8_BAR; PG8_MMA(1, 0, At, B0); PG8_MMA(1, 1, At, B1); PG8_BAR; PG8_SCHED;
;             PG8_LDB(B0, 1, 0); PG8_LDB(B1, 1, 1); PG8_SCHED; PG8_LDA(At, 1, 0); PG8_STAGE(PG8_SA(0, 1), a2 + hstepA, voffA);
;             PG8_WAIT_V(8); PG8_WAIT_L(0); PG8_BAR; PG8_MMA(0, 0, At, B0); PG8_MMA(0, 1, At, B1); PG8_BAR; PG8_SCHED;
	s_add_i32 s60, s60, s11
	v_lshl_add_u64 v[212:213], s[58:59], 0, v[0:1]
	s_mov_b32 m0, s60
	ds_read_b128 v[162:165], v194 offset:16384
	ds_read_b128 v[166:169], v194 offset:17408
	ds_read_b128 v[170:173], v194 offset:18432
	ds_read_b128 v[174:177], v194 offset:19456
	ds_read_b128 v[178:181], v194 offset:20480
	ds_read_b128 v[182:185], v194 offset:21504
	ds_read_b128 v[186:189], v194 offset:22528
	ds_read_b128 v[190:193], v194 offset:23552
	global_load_lds_dwordx4 v[212:213], off
	s_add_i32 m0, s60, 0x2000
	v_lshl_add_u64 v[214:215], s[58:59], 0, v[206:207]
	s_add_u32 s58, s58, s14
	s_addc_u32 s59, s59, s15
	s_add_i32 s37, s37, s11
	global_load_lds_dwordx4 v[214:215], off
	v_lshl_add_u64 v[216:217], s[58:59], 0, v[0:1]
	s_mov_b32 m0, s37
	v_lshl_add_u64 v[218:219], s[58:59], 0, v[206:207]
	global_load_lds_dwordx4 v[216:217], off
	s_add_i32 m0, s37, 0x2000
	v_lshl_add_u64 v[220:221], s[34:35], 0, v[202:203]
	global_load_lds_dwordx4 v[218:219], off
	s_mov_b32 m0, s38
	v_lshl_add_u64 v[222:223], s[34:35], 0, v[204:205]
	global_load_lds_dwordx4 v[220:221], off
	s_mov_b32 m0, s39
	s_nop 0
	global_load_lds_dwordx4 v[222:223], off
	s_waitcnt vmcnt(8)
	s_waitcnt lgkmcnt(0)
	s_barrier
	s_setprio 1
	s_waitcnt lgkmcnt(0)
	v_mfma_f32_16x16x32_bf16 v[62:65], v[130:133], v[162:165], v[62:65]
	v_mfma_f32_16x16x32_bf16 v[58:61], v[138:141], v[162:165], v[58:61]
	v_mfma_f32_16x16x32_bf16 v[46:49], v[130:133], v[170:173], v[46:49]
	v_mfma_f32_16x16x32_bf16 v[42:45], v[138:141], v[170:173], v[42:45]
	v_mfma_f32_16x16x32_bf16 v[30:33], v[130:133], v[178:181], v[30:33]
	v_mfma_f32_16x16x32_bf16 v[26:29], v[138:141], v[178:181], v[26:29]
	v_mfma_f32_16x16x32_bf16 v[14:17], v[130:133], v[186:189], v[14:17]
	v_mfma_f32_16x16x32_bf16 v[10:13], v[138:141], v[186:189], v[10:13]
	v_mfma_f32_16x16x32_bf16 v[62:65], v[134:137], v[166:169], v[62:65]
	v_mfma_f32_16x16x32_bf16 v[58:61], v[142:145], v[166:169], v[58:61]
	v_mfma_f32_16x16x32_bf16 v[46:49], v[134:137], v[174:177], v[46:49]
	v_mfma_f32_16x16x32_bf16 v[42:45], v[142:145], v[174:177], v[42:45]
	v_mfma_f32_16x16x32_bf16 v[30:33], v[134:137], v[182:185], v[30:33]
	v_mfma_f32_16x16x32_bf16 v[26:29], v[142:145], v[182:185], v[26:29]
	v_mfma_f32_16x16x32_bf16 v[14:17], v[134:137], v[190:193], v[14:17]
	v_mfma_f32_16x16x32_bf16 v[10:13], v[142:145], v[190:193], v[10:13]
	v_mfma_f32_16x16x32_bf16 v[54:57], v[146:149], v[162:165], v[54:57]
	v_mfma_f32_16x16x32_bf16 v[50:53], v[154:157], v[162:165], v[50:53]
	v_mfma_f32_16x16x32_bf16 v[38:41], v[146:149], v[170:173], v[38:41]
	v_mfma_f32_16x16x32_bf16 v[34:37], v[154:157], v[170:173], v[34:37]
	v_mfma_f32_16x16x32_bf16 v[22:25], v[146:149], v[178:181], v[22:25]
	v_mfma_f32_16x16x32_bf16 v[18:21], v[154:157], v[178:181], v[18:21]
	v_mfma_f32_16x16x32_bf16 v[6:9], v[146:149], v[186:189], v[6:9]
	v_mfma_f32_16x16x32_bf16 v[2:5], v[154:157], v[186:189], v[2:5]
	v_mfma_f32_16x16x32_bf16 v[54:57], v[150:153], v[166:169], v[54:57]
	v_mfma_f32_16x16x32_bf16 v[50:53], v[158:161], v[166:169], v[50:53]
	v_mfma_f32_16x16x32_bf16 v[38:41], v[150:153], v[174:177], v[38:41]
	v_mfma_f32_16x16x32_bf16 v[34:37], v[158:161], v[174:177], v[34:37]
	v_mfma_f32_16x16x32_bf16 v[22:25], v[150:153], v[182:185], v[22:25]
	v_mfma_f32_16x16x32_bf16 v[18:21], v[158:161], v[182:185], v[18:21]
	v_mfma_f32_16x16x32_bf16 v[6:9], v[150:153], v[190:193], v[6:9]
	v_mfma_f32_16x16x32_bf16 v[2:5], v[158:161], v[190:193], v[2:5]
	s_setprio 0
	s_barrier
.Lkl298_sp2:
	s_add_i32 s37, 0, 0x18000
	s_add_i32 s58, 0, 0x1c000
	v_add_u32_e32 v142, s37, v248
	v_add_u32_e32 v158, s58, v248
	ds_read_b128 v[130:133], v142
	ds_read_b128 v[134:137], v142 offset:1024
	ds_read_b128 v[138:141], v142 offset:2048
	ds_read_b128 v[142:145], v142 offset:3072
	ds_read_b128 v[146:149], v158
	ds_read_b128 v[150:153], v158 offset:1024
	ds_read_b128 v[154:157], v158 offset:2048
	ds_read_b128 v[158:161], v158 offset:3072
	s_add_u32 s34, s34, s12
	s_addc_u32 s35, s35, s13
	s_mov_b32 m0, s43
	v_lshl_add_u64 v[224:225], s[34:35], 0, v[202:203]
	ds_read_b128 v[162:165], v194 offset:32768
	ds_read_b128 v[166:169], v194 offset:33792
	ds_read_b128 v[170:173], v194 offset:34816
	ds_read_b128 v[174:177], v194 offset:35840
	ds_read_b128 v[178:181], v194 offset:36864
	ds_read_b128 v[182:185], v194 offset:37888
	ds_read_b128 v[186:189], v194 offset:38912
	ds_read_b128 v[190:193], v194 offset:39936
	global_load_lds_dwordx4 v[224:225], off
	v_lshl_add_u64 v[224:225], s[34:35], 0, v[204:205]
	s_mov_b32 m0, s44
	s_nop 0
	global_load_lds_dwordx4 v[224:225], off
	s_waitcnt vmcnt(8)
	s_waitcnt lgkmcnt(0)
	s_barrier
	s_setprio 1
	s_waitcnt lgkmcnt(0)
	v_mfma_f32_16x16x32_bf16 v[122:125], v[130:133], v[162:165], v[122:125]
	v_mfma_f32_16x16x32_bf16 v[126:129], v[138:141], v[162:165], v[126:129]
	v_mfma_f32_16x16x32_bf16 v[110:113], v[130:133], v[170:173], v[110:113]
	v_mfma_f32_16x16x32_bf16 v[106:109], v[138:141], v[170:173], v[106:109]
	v_mfma_f32_16x16x32_bf16 v[94:97], v[130:133], v[178:181], v[94:97]
	v_mfma_f32_16x16x32_bf16 v[90:93], v[138:141], v[178:181], v[90:93]
	v_mfma_f32_16x16x32_bf16 v[78:81], v[130:133], v[186:189], v[78:81]
	v_mfma_f32_16x16x32_bf16 v[74:77], v[138:141], v[186:189], v[74:77]
	v_mfma_f32_16x16x32_bf16 v[122:125], v[134:137], v[166:169], v[122:125]
	v_mfma_f32_16x16x32_bf16 v[126:129], v[142:145], v[166:169], v[126:129]
	v_mfma_f32_16x16x32_bf16 v[110:113], v[134:137], v[174:177], v[110:113]
	v_mfma_f32_16x16x32_bf16 v[106:109], v[142:145], v[174:177], v[106:109]
	v_mfma_f32_16x16x32_bf16 v[94:97], v[134:137], v[182:185], v[94:97]
	v_mfma_f32_16x16x32_bf16 v[90:93], v[142:145], v[182:185], v[90:93]
	v_mfma_f32_16x16x32_bf16 v[78:81], v[134:137], v[190:193], v[78:81]
	v_mfma_f32_16x16x32_bf16 v[74:77], v[142:145], v[190:193], v[74:77]
	v_mfma_f32_16x16x32_bf16 v[118:121], v[146:149], v[162:165], v[118:121]
	v_mfma_f32_16x16x32_bf16 v[114:117], v[154:157], v[162:165], v[114:117]
	v_mfma_f32_16x16x32_bf16 v[102:105], v[146:149], v[170:173], v[102:105]
	v_mfma_f32_16x16x32_bf16 v[98:101], v[154:157], v[170:173], v[98:101]
	v_mfma_f32_16x16x32_bf16 v[86:89], v[146:149], v[178:181], v[86:89]
	v_mfma_f32_16x16x32_bf16 v[82:85], v[154:157], v[178:181], v[82:85]
	v_mfma_f32_16x16x32_bf16 v[70:73], v[146:149], v[186:189], v[70:73]
	v_mfma_f32_16x16x32_bf16 v[66:69], v[154:157], v[186:189], v[66:69]
	v_mfma_f32_16x16x32_bf16 v[118:121], v[150:153], v[166:169], v[118:121]
	v_mfma_f32_16x16x32_bf16 v[114:117], v[158:161], v[166:169], v[114:117]
	v_mfma_f32_16x16x32_bf16 v[102:105], v[150:153], v[174:177], v[102:105]
	v_mfma_f32_16x16x32_bf16 v[98:101], v[158:161], v[174:177], v[98:101]
	v_mfma_f32_16x16x32_bf16 v[86:89], v[150:153], v[182:185], v[86:89]
	v_mfma_f32_16x16x32_bf16 v[82:85], v[158:161], v[182:185], v[82:85]
	v_mfma_f32_16x16x32_bf16 v[70:73], v[150:153], v[190:193], v[70:73]
	v_mfma_f32_16x16x32_bf16 v[66:69], v[158:161], v[190:193], v[66:69]
	s_setprio 0
	s_barrier
; #define PG8_STAGE(bufoff, gbase, voff) do { _Pragma("unroll") for (int _i = 0; _i < 2; ++_i) \
;         __builtin_amdgcn_global_load_lds((const unsigned*)((const char*)(gbase) + (voff)[_i]), (LAS unsigned*)(lds + (bufoff) + ldsw + _i * 8192), 16, 0, 0); } while (0)
; #define PG8_LDA(dst, b, h) do { _Pragma("unroll") for (int m = 0; m < 4; ++m) _Pragma("unroll") for (int k = 0; k < 2; ++k) dst[m][k] = *(const LAS bf16x8*)(lds + PG8_SA(b, h) + aoff + m * 2048 + k * 1024); } while (0)
; #define PG8_MMA(ai, bj, At, Bt) do { __builtin_amdgcn_s_setprio(1); _Pragma("unroll") for (int m = 0; m < 4; ++m) _Pragma("unroll") for (int n = 0; n < 2; ++n) _Pragma("unroll") for (int k = 0; k < 2; ++k) \
;         acc[ai][bj][m][n] = __builtin_amdgcn_mfma_f32_16x16x32_bf16(Bt[n][k], At[m][k], acc[ai][bj][m][n], 0, 0, 0); __builtin_amdgcn_s_setprio(0); } while (0)
; #define PG8_WAIT_V(n) asm volatile("s_waitcnt vmcnt(" #n ")" ::: "memory")
; #define PG8_WAIT_L(n) asm volatile("s_waitcnt lgkmcnt(" #n ")" ::: "memory")
; #define PG8_BAR __builtin_amdgcn_s_barrier()
; #define PG8_SCHED __builtin_amdgcn_sched_barrier(0)
; template <class Epi>
; __device__ __forceinline__ void gemm_phase(LAS unsigned char* lds, const Gemm g, const StaticOrder& S, const Epi& E, const int tid) {
;     ...
;             PG8_LDA(At, 1, 1); PG8_STAGE(PG8_SB(1, 0), b3, voffB); PG8_STAGE(PG8_SB(1, 1), b3 + hstepB, voffB); PG8_STAGE(PG8_SA(1, 0), a3, voffA);
;             PG8_WAIT_V(8); PG8_WAIT_L(0); PG8_BAR; PG8_MMA(1, 0, At, B0); PG8_MMA(1, 1, At, B1); PG8_BAR; PG8_SCHED;
;         }
;         if (wr == 0) PG8_BAR;
.Lkl298_sp3:
	s_add_i32 s34, s37, s11
	v_lshl_add_u64 v[212:213], v[212:213], 0, s[80:81]
	s_mov_b32 m0, s34
	ds_read_b128 v[162:165], v194 offset:49152
	ds_read_b128 v[166:169], v194 offset:50176
	ds_read_b128 v[170:173], v194 offset:51200
	ds_read_b128 v[174:177], v194 offset:52224
	ds_read_b128 v[178:181], v194 offset:53248
	ds_read_b128 v[182:185], v194 offset:54272
	ds_read_b128 v[186:189], v194 offset:55296
	ds_read_b128 v[190:193], v194 offset:56320
	global_load_lds_dwordx4 v[212:213], off
	v_lshl_add_u64 v[212:213], v[214:215], 0, s[80:81]
	s_add_i32 m0, s34, 0x2000
	s_add_i32 s34, s58, s11
	global_load_lds_dwordx4 v[212:213], off
	v_lshl_add_u64 v[212:213], v[216:217], 0, s[80:81]
	s_mov_b32 m0, s34
	s_nop 0
	global_load_lds_dwordx4 v[212:213], off
	v_lshl_add_u64 v[212:213], v[218:219], 0, s[80:81]
	s_add_i32 m0, s34, 0x2000
	s_nop 0
	global_load_lds_dwordx4 v[212:213], off
	v_lshl_add_u64 v[212:213], v[220:221], 0, s[80:81]
	s_mov_b32 m0, s49
	s_nop 0
	global_load_lds_dwordx4 v[212:213], off
	v_lshl_add_u64 v[212:213], v[222:223], 0, s[80:81]
	s_mov_b32 m0, s50
	s_nop 0
	global_load_lds_dwordx4 v[212:213], off
	s_waitcnt vmcnt(8)
	s_waitcnt lgkmcnt(0)
	s_nop 0
	s_barrier
	s_setprio 1
	s_waitcnt lgkmcnt(0)
	v_mfma_f32_16x16x32_bf16 v[62:65], v[130:133], v[162:165], v[62:65]
	v_mfma_f32_16x16x32_bf16 v[58:61], v[138:141], v[162:165], v[58:61]
	v_mfma_f32_16x16x32_bf16 v[46:49], v[130:133], v[170:173], v[46:49]
	v_mfma_f32_16x16x32_bf16 v[42:45], v[138:141], v[170:173], v[42:45]
	v_mfma_f32_16x16x32_bf16 v[30:33], v[130:133], v[178:181], v[30:33]
	v_mfma_f32_16x16x32_bf16 v[26:29], v[138:141], v[178:181], v[26:29]
	v_mfma_f32_16x16x32_bf16 v[14:17], v[130:133], v[186:189], v[14:17]
	v_mfma_f32_16x16x32_bf16 v[10:13], v[138:141], v[186:189], v[10:13]
	v_mfma_f32_16x16x32_bf16 v[62:65], v[134:137], v[166:169], v[62:65]
	v_mfma_f32_16x16x32_bf16 v[58:61], v[142:145], v[166:169], v[58:61]
	v_mfma_f32_16x16x32_bf16 v[46:49], v[134:137], v[174:177], v[46:49]
	v_mfma_f32_16x16x32_bf16 v[42:45], v[142:145], v[174:177], v[42:45]
	v_mfma_f32_16x16x32_bf16 v[30:33], v[134:137], v[182:185], v[30:33]
	v_mfma_f32_16x16x32_bf16 v[26:29], v[142:145], v[182:185], v[26:29]
	v_mfma_f32_16x16x32_bf16 v[14:17], v[134:137], v[190:193], v[14:17]
	v_mfma_f32_16x16x32_bf16 v[10:13], v[142:145], v[190:193], v[10:13]
	v_mfma_f32_16x16x32_bf16 v[54:57], v[146:149], v[162:165], v[54:57]
	v_mfma_f32_16x16x32_bf16 v[50:53], v[154:157], v[162:165], v[50:53]
	v_mfma_f32_16x16x32_bf16 v[38:41], v[146:149], v[170:173], v[38:41]
	v_mfma_f32_16x16x32_bf16 v[34:37], v[154:157], v[170:173], v[34:37]
	v_mfma_f32_16x16x32_bf16 v[22:25], v[146:149], v[178:181], v[22:25]
	v_mfma_f32_16x16x32_bf16 v[18:21], v[154:157], v[178:181], v[18:21]
	v_mfma_f32_16x16x32_bf16 v[6:9], v[146:149], v[186:189], v[6:9]
	v_mfma_f32_16x16x32_bf16 v[2:5], v[154:157], v[186:189], v[2:5]
	v_mfma_f32_16x16x32_bf16 v[54:57], v[150:153], v[166:169], v[54:57]
	v_mfma_f32_16x16x32_bf16 v[50:53], v[158:161], v[166:169], v[50:53]
	v_mfma_f32_16x16x32_bf16 v[38:41], v[150:153], v[174:177], v[38:41]
	v_mfma_f32_16x16x32_bf16 v[34:37], v[158:161], v[174:177], v[34:37]
	v_mfma_f32_16x16x32_bf16 v[22:25], v[150:153], v[182:185], v[22:25]
	v_mfma_f32_16x16x32_bf16 v[18:21], v[158:161], v[182:185], v[18:21]
	v_mfma_f32_16x16x32_bf16 v[6:9], v[150:153], v[190:193], v[6:9]
	v_mfma_f32_16x16x32_bf16 v[2:5], v[158:161], v[190:193], v[2:5]
	s_setprio 0
	s_barrier
	s_add_u32 s0, s0, 0x100
	s_addc_u32 s1, s1, 0
	s_add_u32 s6, s6, 0x100
	s_addc_u32 s7, s7, 0
	s_cmp_ge_i32 s36, s46
	s_mov_b32 s34, s36
	s_cbranch_scc0 .LBB0_298
	s_and_b64 vcc, exec, s[4:5]
	s_cbranch_vccnz .Lkl298_noa
	s_add_u32 s98, s28, 0x80
	s_addc_u32 s99, s29, 0
	v_lshl_add_u64 v[212:213], s[98:99], 0, v[210:211]
	s_add_i32 m0, s38, 0xc000
	s_nop 0
	global_load_lds_dwordx4 v[212:213], off
	v_lshl_add_u64 v[212:213], s[98:99], 0, v[208:209]
	s_add_i32 m0, s38, 0xe000
	s_nop 0
	global_load_lds_dwordx4 v[212:213], off

; #define PG8_STAGE(bufoff, gbase, voff) do { _Pragma("unroll") for (int _i = 0; _i < 2; ++_i) \
;         __builtin_amdgcn_global_load_lds((const unsigned*)((const char*)(gbase) + (voff)[_i]), (LAS unsigned*)(lds + (bufoff) + ldsw + _i * 8192), 16, 0, 0); } while (0)
; #define PG8_LDA(dst, b, h) do { _Pragma("unroll") for (int m = 0; m < 4; ++m) _Pragma("unroll") for (int k = 0; k < 2; ++k) dst[m][k] = *(const LAS bf16x8*)(lds + PG8_SA(b, h) + aoff + m * 2048 + k * 1024); } while (0)
; #define PG8_LDB(dst, b, h) do { _Pragma("unroll") for (int n = 0; n < 2; ++n) _Pragma("unroll") for (int k = 0; k < 2; ++k) dst[n][k] = *(const LAS bf16x8*)(lds + PG8_SB(b, h) + boff + n * 2048 + k * 1024); } while (0)
; #define PG8_MMA(ai, bj, At, Bt) do { __builtin_amdgcn_s_setprio(1); _Pragma("unroll") for (int m = 0; m < 4; ++m) _Pragma("unroll") for (int n = 0; n < 2; ++n) _Pragma("unroll") for (int k = 0; k < 2; ++k) \
;         acc[ai][bj][m][n] = __builtin_amdgcn_mfma_f32_16x16x32_bf16(Bt[n][k], At[m][k], acc[ai][bj][m][n], 0, 0, 0); __builtin_amdgcn_s_setprio(0); } while (0)
; #define PG8_WAIT_V(n) asm volatile("s_waitcnt vmcnt(" #n ")" ::: "memory")
; #define PG8_WAIT_L(n) asm volatile("s_waitcnt lgkmcnt(" #n ")" ::: "memory")
; #define PG8_BAR __builtin_amdgcn_s_barrier()
; #define PG8_SCHED __builtin_amdgcn_sched_barrier(0)
; template <class Epi>
; __device__ __forceinline__ void gemm_phase(LAS unsigned char* lds, const Gemm g, const StaticOrder& S, const Epi& E, const int tid) {
;     ...
;         for (int t = 0; t < nt; t += 2) {
;             const bool last = (t == nt - 2);
;             const char* a1 = cA + (size_t)(t + 1) * kstep;
;             const char* a2 = last ? nA : cA + (size_t)(t + 2) * kstep; const char* b2 = last ? nB : cB + (size_t)(t + 2) * kstep;
;             const char* a3 = a2 + kstep; const char* b3 = b2 + kstep;
;             PG8_LDB(B0, 0, 0); PG8_LDB(B1, 0, 1); PG8_SCHED; PG8_LDA(At, 0, 0); PG8_STAGE(PG8_SA(1, 1), a1 + hstepA, voffA);
;             PG8_WAIT_V(8); PG8_WAIT_L(0); PG8_BAR; PG8_MMA(0, 0, At, B0); PG8_MMA(0, 1, At, B1); PG8_BAR; PG8_SCHED;
;             PG8_LDA(At, 0, 1); PG8_STAGE(PG8_SB(0, 0), b2, voffB); PG8_STAGE(PG8_SB(0, 1), b2 + hstepB, voffB); PG8_STAGE(PG8_SA(0, 0), a2, voffA);
;             PG8_WAIT_V(8); PG8_WAIT_L(0); PG8_BAR; PG8_MMA(1, 0, At, B0); PG8_MMA(1, 1, At, B1); PG8_BAR; PG8_SCHED;
.LBB0_346:
	v_mov_b32_e32 v125, 0
	s_andn2_b64 vcc, exec, s[10:11]
	s_cbranch_vccnz .LBB0_349
	s_add_u32 s0, s36, 0x100
	s_addc_u32 s1, s37, 0
	s_add_u32 s36, s38, 0x80
	s_addc_u32 s37, s39, 0
	s_mov_b32 s38, 0
	s_add_i32 s62, s38, 2
	s_add_u32 s63, s36, 0x80
	s_addc_u32 s39, s37, 0
	s_add_i32 s66, 0, 0x10000
	s_cmp_eq_u32 s56, s38
	s_cselect_b32 s39, s7, s39
	s_cselect_b32 s38, s6, s63
	s_cselect_b32 s65, s31, s1
	s_cselect_b32 s64, s30, s0
	s_add_i32 s63, 0, 0x14000
	v_add_u32_e32 v142, s66, v234
	v_add_u32_e32 v158, s63, v234
	ds_read_b128 v[130:133], v142
	ds_read_b128 v[134:137], v142 offset:1024
	ds_read_b128 v[138:141], v142 offset:2048
	ds_read_b128 v[142:145], v142 offset:3072
	ds_read_b128 v[146:149], v158
	ds_read_b128 v[150:153], v158 offset:1024
	ds_read_b128 v[154:157], v158 offset:2048
	ds_read_b128 v[158:161], v158 offset:3072
	v_lshl_add_u64 v[194:195], s[36:37], 0, v[210:211]
	s_add_i32 m0, s44, 0xc000
	ds_read_b128 v[162:165], v235
	ds_read_b128 v[166:169], v235 offset:1024
	ds_read_b128 v[170:173], v235 offset:2048
	ds_read_b128 v[174:177], v235 offset:3072
	ds_read_b128 v[178:181], v235 offset:4096
	ds_read_b128 v[182:185], v235 offset:5120
	ds_read_b128 v[186:189], v235 offset:6144
	ds_read_b128 v[190:193], v235 offset:7168
	global_load_lds_dwordx4 v[194:195], off
	v_lshl_add_u64 v[194:195], s[36:37], 0, v[208:209]
	s_add_i32 m0, s44, 0xe000
	s_nop 0
	global_load_lds_dwordx4 v[194:195], off
	s_waitcnt vmcnt(8)
	s_waitcnt lgkmcnt(0)
	s_barrier
	s_setprio 1
	s_waitcnt lgkmcnt(0)
	v_mfma_f32_16x16x32_bf16 v[122:125], v[130:133], v[162:165], 0
	v_mfma_f32_16x16x32_bf16 v[126:129], v[138:141], v[162:165], 0
	v_mfma_f32_16x16x32_bf16 v[110:113], v[130:133], v[170:173], 0
	v_mfma_f32_16x16x32_bf16 v[106:109], v[138:141], v[170:173], 0
	v_mfma_f32_16x16x32_bf16 v[94:97], v[130:133], v[178:181], 0
	v_mfma_f32_16x16x32_bf16 v[90:93], v[138:141], v[178:181], 0
	v_mfma_f32_16x16x32_bf16 v[78:81], v[130:133], v[186:189], 0
	v_mfma_f32_16x16x32_bf16 v[74:77], v[138:141], v[186:189], 0
	v_mfma_f32_16x16x32_bf16 v[122:125], v[134:137], v[166:169], v[122:125]
	v_mfma_f32_16x16x32_bf16 v[126:129], v[142:145], v[166:169], v[126:129]
	v_mfma_f32_16x16x32_bf16 v[110:113], v[134:137], v[174:177], v[110:113]
	v_mfma_f32_16x16x32_bf16 v[106:109], v[142:145], v[174:177], v[106:109]
	v_mfma_f32_16x16x32_bf16 v[94:97], v[134:137], v[182:185], v[94:97]
	v_mfma_f32_16x16x32_bf16 v[90:93], v[142:145], v[182:185], v[90:93]
	v_mfma_f32_16x16x32_bf16 v[78:81], v[134:137], v[190:193], v[78:81]
	v_mfma_f32_16x16x32_bf16 v[74:77], v[142:145], v[190:193], v[74:77]
	v_mfma_f32_16x16x32_bf16 v[118:121], v[146:149], v[162:165], 0
	v_mfma_f32_16x16x32_bf16 v[114:117], v[154:157], v[162:165], 0
	v_mfma_f32_16x16x32_bf16 v[102:105], v[146:149], v[170:173], 0
	v_mfma_f32_16x16x32_bf16 v[98:101], v[154:157], v[170:173], 0
	v_mfma_f32_16x16x32_bf16 v[86:89], v[146:149], v[178:181], 0
	v_mfma_f32_16x16x32_bf16 v[82:85], v[154:157], v[178:181], 0
	v_mfma_f32_16x16x32_bf16 v[70:73], v[146:149], v[186:189], 0
	v_mfma_f32_16x16x32_bf16 v[66:69], v[154:157], v[186:189], 0
	v_mfma_f32_16x16x32_bf16 v[118:121], v[150:153], v[166:169], v[118:121]
	v_mfma_f32_16x16x32_bf16 v[114:117], v[158:161], v[166:169], v[114:117]
	v_mfma_f32_16x16x32_bf16 v[102:105], v[150:153], v[174:177], v[102:105]
	v_mfma_f32_16x16x32_bf16 v[98:101], v[158:161], v[174:177], v[98:101]
	v_mfma_f32_16x16x32_bf16 v[86:89], v[150:153], v[182:185], v[86:89]
	v_mfma_f32_16x16x32_bf16 v[82:85], v[158:161], v[182:185], v[82:85]
	v_mfma_f32_16x16x32_bf16 v[70:73], v[150:153], v[190:193], v[70:73]
	v_mfma_f32_16x16x32_bf16 v[66:69], v[158:161], v[190:193], v[66:69]
	s_setprio 0
	s_barrier
	s_add_i32 s66, s66, s43
	v_lshl_add_u64 v[194:195], s[64:65], 0, v[0:1]
	s_mov_b32 m0, s66
	ds_read_b128 v[162:165], v235 offset:16384
	ds_read_b128 v[166:169], v235 offset:17408
	ds_read_b128 v[170:173], v235 offset:18432
	ds_read_b128 v[174:177], v235 offset:19456
	ds_read_b128 v[178:181], v235 offset:20480
	ds_read_b128 v[182:185], v235 offset:21504
	ds_read_b128 v[186:189], v235 offset:22528
	ds_read_b128 v[190:193], v235 offset:23552
	global_load_lds_dwordx4 v[194:195], off
	s_add_i32 m0, s66, 0x2000
	v_lshl_add_u64 v[212:213], s[64:65], 0, v[206:207]
	s_add_u32 s64, s64, s14
	s_addc_u32 s65, s65, s15
	s_add_i32 s63, s63, s43
	global_load_lds_dwordx4 v[212:213], off
	v_lshl_add_u64 v[214:215], s[64:65], 0, v[0:1]
	s_mov_b32 m0, s63
	v_lshl_add_u64 v[216:217], s[64:65], 0, v[206:207]
	global_load_lds_dwordx4 v[214:215], off
	s_add_i32 m0, s63, 0x2000
	v_lshl_add_u64 v[218:219], s[38:39], 0, v[202:203]
	global_load_lds_dwordx4 v[216:217], off
	s_mov_b32 m0, s44
	v_lshl_add_u64 v[220:221], s[38:39], 0, v[204:205]
	global_load_lds_dwordx4 v[218:219], off
	s_mov_b32 m0, s45
	s_nop 0
	global_load_lds_dwordx4 v[220:221], off
	s_waitcnt vmcnt(8)
	s_waitcnt lgkmcnt(0)
	s_barrier
	s_setprio 1
	s_waitcnt lgkmcnt(0)
	v_mfma_f32_16x16x32_bf16 v[62:65], v[130:133], v[162:165], 0
	v_mfma_f32_16x16x32_bf16 v[58:61], v[138:141], v[162:165], 0
	v_mfma_f32_16x16x32_bf16 v[46:49], v[130:133], v[170:173], 0
	v_mfma_f32_16x16x32_bf16 v[42:45], v[138:141], v[170:173], 0
	v_mfma_f32_16x16x32_bf16 v[30:33], v[130:133], v[178:181], 0
	v_mfma_f32_16x16x32_bf16 v[26:29], v[138:141], v[178:181], 0
	v_mfma_f32_16x16x32_bf16 v[14:17], v[130:133], v[186:189], 0
	v_mfma_f32_16x16x32_bf16 v[10:13], v[138:141], v[186:189], 0
	v_mfma_f32_16x16x32_bf16 v[62:65], v[134:137], v[166:169], v[62:65]
	v_mfma_f32_16x16x32_bf16 v[58:61], v[142:145], v[166:169], v[58:61]
	v_mfma_f32_16x16x32_bf16 v[46:49], v[134:137], v[174:177], v[46:49]
	v_mfma_f32_16x16x32_bf16 v[42:45], v[142:145], v[174:177], v[42:45]
	v_mfma_f32_16x16x32_bf16 v[30:33], v[134:137], v[182:185], v[30:33]
	v_mfma_f32_16x16x32_bf16 v[26:29], v[142:145], v[182:185], v[26:29]
	v_mfma_f32_16x16x32_bf16 v[14:17], v[134:137], v[190:193], v[14:17]
	v_mfma_f32_16x16x32_bf16 v[10:13], v[142:145], v[190:193], v[10:13]
	v_mfma_f32_16x16x32_bf16 v[54:57], v[146:149], v[162:165], 0
	v_mfma_f32_16x16x32_bf16 v[50:53], v[154:157], v[162:165], 0
	v_mfma_f32_16x16x32_bf16 v[38:41], v[146:149], v[170:173], 0
	v_mfma_f32_16x16x32_bf16 v[34:37], v[154:157], v[170:173], 0
	v_mfma_f32_16x16x32_bf16 v[22:25], v[146:149], v[178:181], 0
	v_mfma_f32_16x16x32_bf16 v[18:21], v[154:157], v[178:181], 0
	v_mfma_f32_16x16x32_bf16 v[6:9], v[146:149], v[186:189], 0
	v_mfma_f32_16x16x32_bf16 v[2:5], v[154:157], v[186:189], 0
	v_mfma_f32_16x16x32_bf16 v[54:57], v[150:153], v[166:169], v[54:57]
	v_mfma_f32_16x16x32_bf16 v[50:53], v[158:161], v[166:169], v[50:53]
	v_mfma_f32_16x16x32_bf16 v[38:41], v[150:153], v[174:177], v[38:41]
	v_mfma_f32_16x16x32_bf16 v[34:37], v[158:161], v[174:177], v[34:37]
	v_mfma_f32_16x16x32_bf16 v[22:25], v[150:153], v[182:185], v[22:25]
	v_mfma_f32_16x16x32_bf16 v[18:21], v[158:161], v[182:185], v[18:21]
	v_mfma_f32_16x16x32_bf16 v[6:9], v[150:153], v[190:193], v[6:9]
	v_mfma_f32_16x16x32_bf16 v[2:5], v[158:161], v[190:193], v[2:5]
	s_setprio 0
	s_barrier
	s_branch .Lkl348_sp2
; #define PG8_STAGE(bufoff, gbase, voff) do { _Pragma("unroll") for (int _i = 0; _i < 2; ++_i) \
;         __builtin_amdgcn_global_load_lds((const unsigned*)((const char*)(gbase) + (voff)[_i]), (LAS unsigned*)(lds + (bufoff) + ldsw + _i * 8192), 16, 0, 0); } while (0)
; #define PG8_LDA(dst, b, h) do { _Pragma("unroll") for (int m = 0; m < 4; ++m) _Pragma("unroll") for (int k = 0; k < 2; ++k) dst[m][k] = *(const LAS bf16x8*)(lds + PG8_SA(b, h) + aoff + m * 2048 + k * 1024); } while (0)
; #define PG8_LDB(dst, b, h) do { _Pragma("unroll") for (int n = 0; n < 2; ++n) _Pragma("unroll") for (int k = 0; k < 2; ++k) dst[n][k] = *(const LAS bf16x8*)(lds + PG8_SB(b, h) + boff + n * 2048 + k * 1024); } while (0)
; #define PG8_MMA(ai, bj, At, Bt) do { __builtin_amdgcn_s_setprio(1); _Pragma("unroll") for (int m = 0; m < 4; ++m) _Pragma("unroll") for (int n = 0; n < 2; ++n) _Pragma("unroll") for (int k = 0; k < 2; ++k) \
;         acc[ai][bj][m][n] = __builtin_amdgcn_mfma_f32_16x16x32_bf16(Bt[n][k], At[m][k], acc[ai][bj][m][n], 0, 0, 0); __builtin_amdgcn_s_setprio(0); } while (0)
; #define PG8_WAIT_V(n) asm volatile("s_waitcnt vmcnt(" #n ")" ::: "memory")
; #define PG8_WAIT_L(n) asm volatile("s_waitcnt lgkmcnt(" #n ")" ::: "memory")
; #define PG8_BAR __builtin_amdgcn_s_barrier()
; #define PG8_SCHED __builtin_amdgcn_sched_barrier(0)
; template <class Epi>
; __device__ __forceinline__ void gemm_phase(LAS unsigned char* lds, const Gemm g, const StaticOrder& S, const Epi& E, const int tid) {
;     ...
;         for (int t = 0; t < nt; t += 2) {
;             const bool last = (t == nt - 2);
;             const char* a1 = cA + (size_t)(t + 1) * kstep;
;             const char* a2 = last ? nA : cA + (size_t)(t + 2) * kstep; const char* b2 = last ? nB : cB + (size_t)(t + 2) * kstep;
;             const char* a3 = a2 + kstep; const char* b3 = b2 + kstep;
;             PG8_LDB(B0, 0, 0); PG8_LDB(B1, 0, 1); PG8_SCHED; PG8_LDA(At, 0, 0); PG8_STAGE(PG8_SA(1, 1), a1 + hstepA, voffA);
;             PG8_WAIT_V(8); PG8_WAIT_L(0); PG8_BAR; PG8_MMA(0, 0, At, B0); PG8_MMA(0, 1, At, B1); PG8_BAR; PG8_SCHED;
;             PG8_LDA(At, 0, 1); PG8_STAGE(PG8_SB(0, 0), b2, voffB); PG8_STAGE(PG8_SB(0, 1), b2 + hstepB, voffB); PG8_STAGE(PG8_SA(0, 0), a2, voffA);
;             PG8_WAIT_V(8); PG8_WAIT_L(0); PG8_BAR; PG8_MMA(1, 0, At, B0); PG8_MMA(1, 1, At, B1); PG8_BAR; PG8_SCHED;
.LBB0_348:
	s_add_i32 s62, s38, 2
	s_add_u32 s63, s36, 0x80
	s_addc_u32 s39, s37, 0
	s_add_i32 s66, 0, 0x10000
	s_cmp_eq_u32 s56, s38
	s_cselect_b32 s39, s7, s39
	s_cselect_b32 s38, s6, s63
	s_cselect_b32 s65, s31, s1
	s_cselect_b32 s64, s30, s0
	s_add_i32 s63, 0, 0x14000
	v_add_u32_e32 v142, s66, v234
	v_add_u32_e32 v158, s63, v234
	ds_read_b128 v[130:133], v142
	ds_read_b128 v[134:137], v142 offset:1024
	ds_read_b128 v[138:141], v142 offset:2048
	ds_read_b128 v[142:145], v142 offset:3072
	ds_read_b128 v[146:149], v158
	ds_read_b128 v[150:153], v158 offset:1024
	ds_read_b128 v[154:157], v158 offset:2048
	ds_read_b128 v[158:161], v158 offset:3072
	v_lshl_add_u64 v[194:195], s[36:37], 0, v[210:211]
	s_add_i32 m0, s44, 0xc000
	ds_read_b128 v[162:165], v235
	ds_read_b128 v[166:169], v235 offset:1024
	ds_read_b128 v[170:173], v235 offset:2048
	ds_read_b128 v[174:177], v235 offset:3072
	ds_read_b128 v[178:181], v235 offset:4096
	ds_read_b128 v[182:185], v235 offset:5120
	ds_read_b128 v[186:189], v235 offset:6144
	ds_read_b128 v[190:193], v235 offset:7168
	global_load_lds_dwordx4 v[194:195], off
	v_lshl_add_u64 v[194:195], s[36:37], 0, v[208:209]
	s_add_i32 m0, s44, 0xe000
	s_nop 0
	global_load_lds_dwordx4 v[194:195], off
	s_waitcnt vmcnt(8)
	s_waitcnt lgkmcnt(0)
	s_barrier
	s_setprio 1
	s_waitcnt lgkmcnt(0)
	v_mfma_f32_16x16x32_bf16 v[122:125], v[130:133], v[162:165], v[122:125]
	v_mfma_f32_16x16x32_bf16 v[126:129], v[138:141], v[162:165], v[126:129]
	v_mfma_f32_16x16x32_bf16 v[110:113], v[130:133], v[170:173], v[110:113]
	v_mfma_f32_16x16x32_bf16 v[106:109], v[138:141], v[170:173], v[106:109]
	v_mfma_f32_16x16x32_bf16 v[94:97], v[130:133], v[178:181], v[94:97]
	v_mfma_f32_16x16x32_bf16 v[90:93], v[138:141], v[178:181], v[90:93]
	v_mfma_f32_16x16x32_bf16 v[78:81], v[130:133], v[186:189], v[78:81]
	v_mfma_f32_16x16x32_bf16 v[74:77], v[138:141], v[186:189], v[74:77]
	v_mfma_f32_16x16x32_bf16 v[122:125], v[134:137], v[166:169], v[122:125]
	v_mfma_f32_16x16x32_bf16 v[126:129], v[142:145], v[166:169], v[126:129]
	v_mfma_f32_16x16x32_bf16 v[110:113], v[134:137], v[174:177], v[110:113]
	v_mfma_f32_16x16x32_bf16 v[106:109], v[142:145], v[174:177], v[106:109]
	v_mfma_f32_16x16x32_bf16 v[94:97], v[134:137], v[182:185], v[94:97]
	v_mfma_f32_16x16x32_bf16 v[90:93], v[142:145], v[182:185], v[90:93]
	v_mfma_f32_16x16x32_bf16 v[78:81], v[134:137], v[190:193], v[78:81]
	v_mfma_f32_16x16x32_bf16 v[74:77], v[142:145], v[190:193], v[74:77]
	v_mfma_f32_16x16x32_bf16 v[118:121], v[146:149], v[162:165], v[118:121]
	v_mfma_f32_16x16x32_bf16 v[114:117], v[154:157], v[162:165], v[114:117]
	v_mfma_f32_16x16x32_bf16 v[102:105], v[146:149], v[170:173], v[102:105]
	v_mfma_f32_16x16x32_bf16 v[98:101], v[154:157], v[170:173], v[98:101]
	v_mfma_f32_16x16x32_bf16 v[86:89], v[146:149], v[178:181], v[86:89]
	v_mfma_f32_16x16x32_bf16 v[82:85], v[154:157], v[178:181], v[82:85]
	v_mfma_f32_16x16x32_bf16 v[70:73], v[146:149], v[186:189], v[70:73]
	v_mfma_f32_16x16x32_bf16 v[66:69], v[154:157], v[186:189], v[66:69]
	v_mfma_f32_16x16x32_bf16 v[118:121], v[150:153], v[166:169], v[118:121]
	v_mfma_f32_16x16x32_bf16 v[114:117], v[158:161], v[166:169], v[114:117]
	v_mfma_f32_16x16x32_bf16 v[102:105], v[150:153], v[174:177], v[102:105]
	v_mfma_f32_16x16x32_bf16 v[98:101], v[158:161], v[174:177], v[98:101]
	v_mfma_f32_16x16x32_bf16 v[86:89], v[150:153], v[182:185], v[86:89]
	v_mfma_f32_16x16x32_bf16 v[82:85], v[158:161], v[182:185], v[82:85]
	v_mfma_f32_16x16x32_bf16 v[70:73], v[150:153], v[190:193], v[70:73]
	v_mfma_f32_16x16x32_bf16 v[66:69], v[158:161], v[190:193], v[66:69]
	s_setprio 0
	s_barrier
	s_add_i32 s66, s66, s43
	v_lshl_add_u64 v[194:195], s[64:65], 0, v[0:1]
	s_mov_b32 m0, s66
	ds_read_b128 v[162:165], v235 offset:16384
	ds_read_b128 v[166:169], v235 offset:17408
	ds_read_b128 v[170:173], v235 offset:18432
	ds_read_b128 v[174:177], v235 offset:19456
	ds_read_b128 v[178:181], v235 offset:20480
	ds_read_b128 v[182:185], v235 offset:21504
	ds_read_b128 v[186:189], v235 offset:22528
	ds_read_b128 v[190:193], v235 offset:23552
	global_load_lds_dwordx4 v[194:195], off
	s_add_i32 m0, s66, 0x2000
	v_lshl_add_u64 v[212:213], s[64:65], 0, v[206:207]
	s_add_u32 s64, s64, s14
	s_addc_u32 s65, s65, s15
	s_add_i32 s63, s63, s43
	global_load_lds_dwordx4 v[212:213], off
	v_lshl_add_u64 v[214:215], s[64:65], 0, v[0:1]
	s_mov_b32 m0, s63
	v_lshl_add_u64 v[216:217], s[64:65], 0, v[206:207]
	global_load_lds_dwordx4 v[214:215], off
	s_add_i32 m0, s63, 0x2000
	v_lshl_add_u64 v[218:219], s[38:39], 0, v[202:203]
	global_load_lds_dwordx4 v[216:217], off
	s_mov_b32 m0, s44
	v_lshl_add_u64 v[220:221], s[38:39], 0, v[204:205]
	global_load_lds_dwordx4 v[218:219], off
	s_mov_b32 m0, s45
	s_nop 0
	global_load_lds_dwordx4 v[220:221], off
	s_waitcnt vmcnt(8)
	s_waitcnt lgkmcnt(0)
	s_barrier
; #define PG8_STAGE(bufoff, gbase, voff) do { _Pragma("unroll") for (int _i = 0; _i < 2; ++_i) \
;         __builtin_amdgcn_global_load_lds((const unsigned*)((const char*)(gbase) + (voff)[_i]), (LAS unsigned*)(lds + (bufoff) + ldsw + _i * 8192), 16, 0, 0); } while (0)
; #define PG8_LDA(dst, b, h) do { _Pragma("unroll") for (int m = 0; m < 4; ++m) _Pragma("unroll") for (int k = 0; k < 2; ++k) dst[m][k] = *(const LAS bf16x8*)(lds + PG8_SA(b, h) + aoff + m * 2048 + k * 1024); } while (0)
; #define PG8_LDB(dst, b, h) do { _Pragma("unroll") for (int n = 0; n < 2; ++n) _Pragma("unroll") for (int k = 0; k < 2; ++k) dst[n][k] = *(const LAS bf16x8*)(lds + PG8_SB(b, h) + boff + n * 2048 + k * 1024); } while (0)
; #define PG8_MMA(ai, bj, At, Bt) do { __builtin_amdgcn_s_setprio(1); _Pragma("unroll") for (int m = 0; m < 4; ++m) _Pragma("unroll") for (int n = 0; n < 2; ++n) _Pragma("unroll") for (int k = 0; k < 2; ++k) \
;         acc[ai][bj][m][n] = __builtin_amdgcn_mfma_f32_16x16x32_bf16(Bt[n][k], At[m][k], acc[ai][bj][m][n], 0, 0, 0); __builtin_amdgcn_s_setprio(0); } while (0)
; #define PG8_WAIT_V(n) asm volatile("s_waitcnt vmcnt(" #n ")" ::: "memory")
; #define PG8_WAIT_L(n) asm volatile("s_waitcnt lgkmcnt(" #n ")" ::: "memory")
; #define PG8_BAR __builtin_amdgcn_s_barrier()
; #define PG8_SCHED __builtin_amdgcn_sched_barrier(0)
; template <class Epi>
; __device__ __forceinline__ void gemm_phase(LAS unsigned char* lds, const Gemm g, const StaticOrder& S, const Epi& E, const int tid) {
;     ...
;             PG8_WAIT_V(8); PG8_WAIT_L(0); PG8_BAR; PG8_MMA(1, 0, At, B0); PG8_MMA(1, 1, At, B1); PG8_BAR; PG8_SCHED;
;             PG8_LDB(B0, 1, 0); PG8_LDB(B1, 1, 1); PG8_SCHED; PG8_LDA(At, 1, 0); PG8_STAGE(PG8_SA(0, 1), a2 + hstepA, voffA);
;             PG8_WAIT_V(8); PG8_WAIT_L(0); PG8_BAR; PG8_MMA(0, 0, At, B0); PG8_MMA(0, 1, At, B1); PG8_BAR; PG8_SCHED;
	s_setprio 1
	s_waitcnt lgkmcnt(0)
	v_mfma_f32_16x16x32_bf16 v[62:65], v[130:133], v[162:165], v[62:65]
	v_mfma_f32_16x16x32_bf16 v[58:61], v[138:141], v[162:165], v[58:61]
	v_mfma_f32_16x16x32_bf16 v[46:49], v[130:133], v[170:173], v[46:49]
	v_mfma_f32_16x16x32_bf16 v[42:45], v[138:141], v[170:173], v[42:45]
	v_mfma_f32_16x16x32_bf16 v[30:33], v[130:133], v[178:181], v[30:33]
	v_mfma_f32_16x16x32_bf16 v[26:29], v[138:141], v[178:181], v[26:29]
	v_mfma_f32_16x16x32_bf16 v[14:17], v[130:133], v[186:189], v[14:17]
	v_mfma_f32_16x16x32_bf16 v[10:13], v[138:141], v[186:189], v[10:13]
	v_mfma_f32_16x16x32_bf16 v[62:65], v[134:137], v[166:169], v[62:65]
	v_mfma_f32_16x16x32_bf16 v[58:61], v[142:145], v[166:169], v[58:61]
	v_mfma_f32_16x16x32_bf16 v[46:49], v[134:137], v[174:177], v[46:49]
	v_mfma_f32_16x16x32_bf16 v[42:45], v[142:145], v[174:177], v[42:45]
	v_mfma_f32_16x16x32_bf16 v[30:33], v[134:137], v[182:185], v[30:33]
	v_mfma_f32_16x16x32_bf16 v[26:29], v[142:145], v[182:185], v[26:29]
	v_mfma_f32_16x16x32_bf16 v[14:17], v[134:137], v[190:193], v[14:17]
	v_mfma_f32_16x16x32_bf16 v[10:13], v[142:145], v[190:193], v[10:13]
	v_mfma_f32_16x16x32_bf16 v[54:57], v[146:149], v[162:165], v[54:57]
	v_mfma_f32_16x16x32_bf16 v[50:53], v[154:157], v[162:165], v[50:53]
	v_mfma_f32_16x16x32_bf16 v[38:41], v[146:149], v[170:173], v[38:41]
	v_mfma_f32_16x16x32_bf16 v[34:37], v[154:157], v[170:173], v[34:37]
	v_mfma_f32_16x16x32_bf16 v[22:25], v[146:149], v[178:181], v[22:25]
	v_mfma_f32_16x16x32_bf16 v[18:21], v[154:157], v[178:181], v[18:21]
	v_mfma_f32_16x16x32_bf16 v[6:9], v[146:149], v[186:189], v[6:9]
	v_mfma_f32_16x16x32_bf16 v[2:5], v[154:157], v[186:189], v[2:5]
	v_mfma_f32_16x16x32_bf16 v[54:57], v[150:153], v[166:169], v[54:57]
	v_mfma_f32_16x16x32_bf16 v[50:53], v[158:161], v[166:169], v[50:53]
	v_mfma_f32_16x16x32_bf16 v[38:41], v[150:153], v[174:177], v[38:41]
	v_mfma_f32_16x16x32_bf16 v[34:37], v[158:161], v[174:177], v[34:37]
	v_mfma_f32_16x16x32_bf16 v[22:25], v[150:153], v[182:185], v[22:25]
	v_mfma_f32_16x16x32_bf16 v[18:21], v[158:161], v[182:185], v[18:21]
	v_mfma_f32_16x16x32_bf16 v[6:9], v[150:153], v[190:193], v[6:9]
	v_mfma_f32_16x16x32_bf16 v[2:5], v[158:161], v[190:193], v[2:5]
	s_setprio 0
	s_barrier
.Lkl348_sp2:
	s_add_i32 s63, 0, 0x18000
	s_add_i32 s64, 0, 0x1c000
	v_add_u32_e32 v142, s63, v234
	v_add_u32_e32 v158, s64, v234
	ds_read_b128 v[130:133], v142
	ds_read_b128 v[134:137], v142 offset:1024
	ds_read_b128 v[138:141], v142 offset:2048
	ds_read_b128 v[142:145], v142 offset:3072
	ds_read_b128 v[146:149], v158
	ds_read_b128 v[150:153], v158 offset:1024
	ds_read_b128 v[154:157], v158 offset:2048
	ds_read_b128 v[158:161], v158 offset:3072
	s_add_u32 s38, s38, s12
	s_addc_u32 s39, s39, s13
	s_mov_b32 m0, s46
	v_lshl_add_u64 v[222:223], s[38:39], 0, v[202:203]
	ds_read_b128 v[162:165], v235 offset:32768
	ds_read_b128 v[166:169], v235 offset:33792
	ds_read_b128 v[170:173], v235 offset:34816
	ds_read_b128 v[174:177], v235 offset:35840
	ds_read_b128 v[178:181], v235 offset:36864
	ds_read_b128 v[182:185], v235 offset:37888
	ds_read_b128 v[186:189], v235 offset:38912
	ds_read_b128 v[190:193], v235 offset:39936
	global_load_lds_dwordx4 v[222:223], off
	v_lshl_add_u64 v[222:223], s[38:39], 0, v[204:205]
	s_mov_b32 m0, s47
	s_nop 0
	global_load_lds_dwordx4 v[222:223], off
	s_waitcnt vmcnt(8)
	s_waitcnt lgkmcnt(0)
	s_barrier
	s_setprio 1
	s_waitcnt lgkmcnt(0)
	v_mfma_f32_16x16x32_bf16 v[122:125], v[130:133], v[162:165], v[122:125]
	v_mfma_f32_16x16x32_bf16 v[126:129], v[138:141], v[162:165], v[126:129]
	v_mfma_f32_16x16x32_bf16 v[110:113], v[130:133], v[170:173], v[110:113]
	v_mfma_f32_16x16x32_bf16 v[106:109], v[138:141], v[170:173], v[106:109]
	v_mfma_f32_16x16x32_bf16 v[94:97], v[130:133], v[178:181], v[94:97]
	v_mfma_f32_16x16x32_bf16 v[90:93], v[138:141], v[178:181], v[90:93]
	v_mfma_f32_16x16x32_bf16 v[78:81], v[130:133], v[186:189], v[78:81]
	v_mfma_f32_16x16x32_bf16 v[74:77], v[138:141], v[186:189], v[74:77]
	v_mfma_f32_16x16x32_bf16 v[122:125], v[134:137], v[166:169], v[122:125]
	v_mfma_f32_16x16x32_bf16 v[126:129], v[142:145], v[166:169], v[126:129]
	v_mfma_f32_16x16x32_bf16 v[110:113], v[134:137], v[174:177], v[110:113]
	v_mfma_f32_16x16x32_bf16 v[106:109], v[142:145], v[174:177], v[106:109]
	v_mfma_f32_16x16x32_bf16 v[94:97], v[134:137], v[182:185], v[94:97]
	v_mfma_f32_16x16x32_bf16 v[90:93], v[142:145], v[182:185], v[90:93]
	v_mfma_f32_16x16x32_bf16 v[78:81], v[134:137], v[190:193], v[78:81]
	v_mfma_f32_16x16x32_bf16 v[74:77], v[142:145], v[190:193], v[74:77]
	v_mfma_f32_16x16x32_bf16 v[118:121], v[146:149], v[162:165], v[118:121]
	v_mfma_f32_16x16x32_bf16 v[114:117], v[154:157], v[162:165], v[114:117]
	v_mfma_f32_16x16x32_bf16 v[102:105], v[146:149], v[170:173], v[102:105]
	v_mfma_f32_16x16x32_bf16 v[98:101], v[154:157], v[170:173], v[98:101]
	v_mfma_f32_16x16x32_bf16 v[86:89], v[146:149], v[178:181], v[86:89]
	v_mfma_f32_16x16x32_bf16 v[82:85], v[154:157], v[178:181], v[82:85]
	v_mfma_f32_16x16x32_bf16 v[70:73], v[146:149], v[186:189], v[70:73]
	v_mfma_f32_16x16x32_bf16 v[66:69], v[154:157], v[186:189], v[66:69]
	v_mfma_f32_16x16x32_bf16 v[118:121], v[150:153], v[166:169], v[118:121]
	v_mfma_f32_16x16x32_bf16 v[114:117], v[158:161], v[166:169], v[114:117]
	v_mfma_f32_16x16x32_bf16 v[102:105], v[150:153], v[174:177], v[102:105]
	v_mfma_f32_16x16x32_bf16 v[98:101], v[158:161], v[174:177], v[98:101]
	v_mfma_f32_16x16x32_bf16 v[86:89], v[150:153], v[182:185], v[86:89]
	v_mfma_f32_16x16x32_bf16 v[82:85], v[158:161], v[182:185], v[82:85]
	v_mfma_f32_16x16x32_bf16 v[70:73], v[150:153], v[190:193], v[70:73]
	v_mfma_f32_16x16x32_bf16 v[66:69], v[158:161], v[190:193], v[66:69]
	s_setprio 0
	s_barrier
; #define PG8_STAGE(bufoff, gbase, voff) do { _Pragma("unroll") for (int _i = 0; _i < 2; ++_i) \
;         __builtin_amdgcn_global_load_lds((const unsigned*)((const char*)(gbase) + (voff)[_i]), (LAS unsigned*)(lds + (bufoff) + ldsw + _i * 8192), 16, 0, 0); } while (0)
; #define PG8_LDA(dst, b, h) do { _Pragma("unroll") for (int m = 0; m < 4; ++m) _Pragma("unroll") for (int k = 0; k < 2; ++k) dst[m][k] = *(const LAS bf16x8*)(lds + PG8_SA(b, h) + aoff + m * 2048 + k * 1024); } while (0)
; #define PG8_MMA(ai, bj, At, Bt) do { __builtin_amdgcn_s_setprio(1); _Pragma("unroll") for (int m = 0; m < 4; ++m) _Pragma("unroll") for (int n = 0; n < 2; ++n) _Pragma("unroll") for (int k = 0; k < 2; ++k) \
;         acc[ai][bj][m][n] = __builtin_amdgcn_mfma_f32_16x16x32_bf16(Bt[n][k], At[m][k], acc[ai][bj][m][n], 0, 0, 0); __builtin_amdgcn_s_setprio(0); } while (0)
; #define PG8_WAIT_V(n) asm volatile("s_waitcnt vmcnt(" #n ")" ::: "memory")
; #define PG8_WAIT_L(n) asm volatile("s_waitcnt lgkmcnt(" #n ")" ::: "memory")
; #define PG8_BAR __builtin_amdgcn_s_barrier()
; #define PG8_SCHED __builtin_amdgcn_sched_barrier(0)
; template <class Epi>
; __device__ __forceinline__ void gemm_phase(LAS unsigned char* lds, const Gemm g, const StaticOrder& S, const Epi& E, const int tid) {
;     ...
;             PG8_LDA(At, 1, 1); PG8_STAGE(PG8_SB(1, 0), b3, voffB); PG8_STAGE(PG8_SB(1, 1), b3 + hstepB, voffB); PG8_STAGE(PG8_SA(1, 0), a3, voffA);
;             PG8_WAIT_V(8); PG8_WAIT_L(0); PG8_BAR; PG8_MMA(1, 0, At, B0); PG8_MMA(1, 1, At, B1); PG8_BAR; PG8_SCHED;
;         }
	s_add_i32 s38, s63, s43
	v_lshl_add_u64 v[194:195], v[194:195], 0, s[80:81]
	s_mov_b32 m0, s38
	ds_read_b128 v[162:165], v235 offset:49152
	ds_read_b128 v[166:169], v235 offset:50176
	ds_read_b128 v[170:173], v235 offset:51200
	ds_read_b128 v[174:177], v235 offset:52224
	ds_read_b128 v[178:181], v235 offset:53248
	ds_read_b128 v[182:185], v235 offset:54272
	ds_read_b128 v[186:189], v235 offset:55296
	ds_read_b128 v[190:193], v235 offset:56320
	global_load_lds_dwordx4 v[194:195], off
	v_lshl_add_u64 v[194:195], v[212:213], 0, s[80:81]
	s_add_i32 m0, s38, 0x2000
	s_add_i32 s38, s64, s43
	global_load_lds_dwordx4 v[194:195], off
	v_lshl_add_u64 v[194:195], v[214:215], 0, s[80:81]
	s_mov_b32 m0, s38
	s_nop 0
	global_load_lds_dwordx4 v[194:195], off
	v_lshl_add_u64 v[194:195], v[216:217], 0, s[80:81]
	s_add_i32 m0, s38, 0x2000
	s_nop 0
	global_load_lds_dwordx4 v[194:195], off
	v_lshl_add_u64 v[194:195], v[218:219], 0, s[80:81]
	s_mov_b32 m0, s50
	s_nop 0
	global_load_lds_dwordx4 v[194:195], off
	v_lshl_add_u64 v[194:195], v[220:221], 0, s[80:81]
	s_mov_b32 m0, s51
	s_nop 0
	global_load_lds_dwordx4 v[194:195], off
	s_waitcnt vmcnt(8)
	s_waitcnt lgkmcnt(0)
	s_nop 0
	s_barrier
	s_setprio 1
	s_waitcnt lgkmcnt(0)
	v_mfma_f32_16x16x32_bf16 v[62:65], v[130:133], v[162:165], v[62:65]
	v_mfma_f32_16x16x32_bf16 v[58:61], v[138:141], v[162:165], v[58:61]
	v_mfma_f32_16x16x32_bf16 v[46:49], v[130:133], v[170:173], v[46:49]
	v_mfma_f32_16x16x32_bf16 v[42:45], v[138:141], v[170:173], v[42:45]
	v_mfma_f32_16x16x32_bf16 v[30:33], v[130:133], v[178:181], v[30:33]
	v_mfma_f32_16x16x32_bf16 v[26:29], v[138:141], v[178:181], v[26:29]
	v_mfma_f32_16x16x32_bf16 v[14:17], v[130:133], v[186:189], v[14:17]
	v_mfma_f32_16x16x32_bf16 v[10:13], v[138:141], v[186:189], v[10:13]
	v_mfma_f32_16x16x32_bf16 v[62:65], v[134:137], v[166:169], v[62:65]
	v_mfma_f32_16x16x32_bf16 v[58:61], v[142:145], v[166:169], v[58:61]
	v_mfma_f32_16x16x32_bf16 v[46:49], v[134:137], v[174:177], v[46:49]
	v_mfma_f32_16x16x32_bf16 v[42:45], v[142:145], v[174:177], v[42:45]
	v_mfma_f32_16x16x32_bf16 v[30:33], v[134:137], v[182:185], v[30:33]
	v_mfma_f32_16x16x32_bf16 v[26:29], v[142:145], v[182:185], v[26:29]
	v_mfma_f32_16x16x32_bf16 v[14:17], v[134:137], v[190:193], v[14:17]
	v_mfma_f32_16x16x32_bf16 v[10:13], v[142:145], v[190:193], v[10:13]
	v_mfma_f32_16x16x32_bf16 v[54:57], v[146:149], v[162:165], v[54:57]
	v_mfma_f32_16x16x32_bf16 v[50:53], v[154:157], v[162:165], v[50:53]
	v_mfma_f32_16x16x32_bf16 v[38:41], v[146:149], v[170:173], v[38:41]
	v_mfma_f32_16x16x32_bf16 v[34:37], v[154:157], v[170:173], v[34:37]
	v_mfma_f32_16x16x32_bf16 v[22:25], v[146:149], v[178:181], v[22:25]
	v_mfma_f32_16x16x32_bf16 v[18:21], v[154:157], v[178:181], v[18:21]
	v_mfma_f32_16x16x32_bf16 v[6:9], v[146:149], v[186:189], v[6:9]
	v_mfma_f32_16x16x32_bf16 v[2:5], v[154:157], v[186:189], v[2:5]
	v_mfma_f32_16x16x32_bf16 v[54:57], v[150:153], v[166:169], v[54:57]
	v_mfma_f32_16x16x32_bf16 v[50:53], v[158:161], v[166:169], v[50:53]
	v_mfma_f32_16x16x32_bf16 v[38:41], v[150:153], v[174:177], v[38:41]
	v_mfma_f32_16x16x32_bf16 v[34:37], v[158:161], v[174:177], v[34:37]
	v_mfma_f32_16x16x32_bf16 v[22:25], v[150:153], v[182:185], v[22:25]
	v_mfma_f32_16x16x32_bf16 v[18:21], v[158:161], v[182:185], v[18:21]
	v_mfma_f32_16x16x32_bf16 v[6:9], v[150:153], v[190:193], v[6:9]
	v_mfma_f32_16x16x32_bf16 v[2:5], v[158:161], v[190:193], v[2:5]
	s_setprio 0
	s_barrier
	s_add_u32 s0, s0, 0x100
	s_addc_u32 s1, s1, 0
	s_add_u32 s36, s36, 0x100
	s_addc_u32 s37, s37, 0
	s_cmp_ge_i32 s62, s53
	s_mov_b32 s38, s62
	s_cbranch_scc0 .LBB0_348

; #define PG8_STAGE(bufoff, gbase, voff) do { _Pragma("unroll") for (int _i = 0; _i < 2; ++_i) \
;         __builtin_amdgcn_global_load_lds((const unsigned*)((const char*)(gbase) + (voff)[_i]), (LAS unsigned*)(lds + (bufoff) + ldsw + _i * 8192), 16, 0, 0); } while (0)
; #define PG8_LDA(dst, b, h) do { _Pragma("unroll") for (int m = 0; m < 4; ++m) _Pragma("unroll") for (int k = 0; k < 2; ++k) dst[m][k] = *(const LAS bf16x8*)(lds + PG8_SA(b, h) + aoff + m * 2048 + k * 1024); } while (0)
; #define PG8_LDB(dst, b, h) do { _Pragma("unroll") for (int n = 0; n < 2; ++n) _Pragma("unroll") for (int k = 0; k < 2; ++k) dst[n][k] = *(const LAS bf16x8*)(lds + PG8_SB(b, h) + boff + n * 2048 + k * 1024); } while (0)
; #define PG8_MMA(ai, bj, At, Bt) do { __builtin_amdgcn_s_setprio(1); _Pragma("unroll") for (int m = 0; m < 4; ++m) _Pragma("unroll") for (int n = 0; n < 2; ++n) _Pragma("unroll") for (int k = 0; k < 2; ++k) \
;         acc[ai][bj][m][n] = __builtin_amdgcn_mfma_f32_16x16x32_bf16(Bt[n][k], At[m][k], acc[ai][bj][m][n], 0, 0, 0); __builtin_amdgcn_s_setprio(0); } while (0)
; #define PG8_WAIT_V(n) asm volatile("s_waitcnt vmcnt(" #n ")" ::: "memory")
; #define PG8_WAIT_L(n) asm volatile("s_waitcnt lgkmcnt(" #n ")" ::: "memory")
; #define PG8_BAR __builtin_amdgcn_s_barrier()
; #define PG8_SCHED __builtin_amdgcn_sched_barrier(0)
; template <class Epi>
; __device__ __forceinline__ void gemm_phase(LAS unsigned char* lds, const Gemm g, const StaticOrder& S, const Epi& E, const int tid) {
;     ...
;             PG8_LDB(B0, 0, 0); PG8_LDB(B1, 0, 1); PG8_SCHED; PG8_LDA(At, 0, 0); PG8_STAGE(PG8_SA(1, 1), a1 + hstepA, voffA);
;             PG8_WAIT_V(8); PG8_WAIT_L(0); PG8_BAR; PG8_MMA(0, 0, At, B0); PG8_MMA(0, 1, At, B1); PG8_BAR; PG8_SCHED;
;             PG8_LDA(At, 0, 1); PG8_STAGE(PG8_SB(0, 0), b2, voffB); PG8_STAGE(PG8_SB(0, 1), b2 + hstepB, voffB); PG8_STAGE(PG8_SA(0, 0), a2, voffA);
.Lkl427_nofa:
	s_waitcnt vmcnt(18)
	s_waitcnt lgkmcnt(0)
	s_barrier
	s_setprio 1
	s_waitcnt lgkmcnt(0)
	v_mfma_f32_16x16x32_bf16 v[142:145], v[66:69], v[172:175], 0
	v_mfma_f32_16x16x32_bf16 v[138:141], v[74:77], v[172:175], 0
	v_mfma_f32_16x16x32_bf16 v[126:129], v[66:69], v[180:183], 0
	v_mfma_f32_16x16x32_bf16 v[122:125], v[74:77], v[180:183], 0
	v_mfma_f32_16x16x32_bf16 v[110:113], v[66:69], v[188:191], 0
	v_mfma_f32_16x16x32_bf16 v[106:109], v[74:77], v[188:191], 0
	v_mfma_f32_16x16x32_bf16 v[94:97], v[66:69], v[202:205], 0
	v_mfma_f32_16x16x32_bf16 v[90:93], v[74:77], v[202:205], 0
	v_mfma_f32_16x16x32_bf16 v[142:145], v[70:73], v[176:179], v[142:145]
	v_mfma_f32_16x16x32_bf16 v[138:141], v[78:81], v[176:179], v[138:141]
	v_mfma_f32_16x16x32_bf16 v[126:129], v[70:73], v[184:187], v[126:129]
	v_mfma_f32_16x16x32_bf16 v[122:125], v[78:81], v[184:187], v[122:125]
	v_mfma_f32_16x16x32_bf16 v[110:113], v[70:73], v[192:195], v[110:113]
	v_mfma_f32_16x16x32_bf16 v[106:109], v[78:81], v[192:195], v[106:109]
	v_mfma_f32_16x16x32_bf16 v[94:97], v[70:73], v[206:209], v[94:97]
	v_mfma_f32_16x16x32_bf16 v[90:93], v[78:81], v[206:209], v[90:93]
	v_mfma_f32_16x16x32_bf16 v[134:137], v[156:159], v[172:175], 0
	v_mfma_f32_16x16x32_bf16 v[130:133], v[164:167], v[172:175], 0
	v_mfma_f32_16x16x32_bf16 v[118:121], v[156:159], v[180:183], 0
	v_mfma_f32_16x16x32_bf16 v[114:117], v[164:167], v[180:183], 0
	v_mfma_f32_16x16x32_bf16 v[102:105], v[156:159], v[188:191], 0
	v_mfma_f32_16x16x32_bf16 v[98:101], v[164:167], v[188:191], 0
	v_mfma_f32_16x16x32_bf16 v[86:89], v[156:159], v[202:205], 0
	v_mfma_f32_16x16x32_bf16 v[82:85], v[164:167], v[202:205], 0
	v_mfma_f32_16x16x32_bf16 v[134:137], v[160:163], v[176:179], v[134:137]
	v_mfma_f32_16x16x32_bf16 v[130:133], v[168:171], v[176:179], v[130:133]
	v_mfma_f32_16x16x32_bf16 v[118:121], v[160:163], v[184:187], v[118:121]
	v_mfma_f32_16x16x32_bf16 v[114:117], v[168:171], v[184:187], v[114:117]
	v_mfma_f32_16x16x32_bf16 v[102:105], v[160:163], v[192:195], v[102:105]
	v_mfma_f32_16x16x32_bf16 v[98:101], v[168:171], v[192:195], v[98:101]
	v_mfma_f32_16x16x32_bf16 v[86:89], v[160:163], v[206:209], v[86:89]
	v_mfma_f32_16x16x32_bf16 v[82:85], v[168:171], v[206:209], v[82:85]
	s_setprio 0
	s_barrier
	s_add_i32 s66, s66, s85
	v_lshl_add_u64 v[210:211], s[12:13], 0, v[0:1]
	s_mov_b32 m0, s66
	ds_read_b128 v[172:175], v223 offset:16384
	ds_read_b128 v[176:179], v223 offset:17408
	ds_read_b128 v[180:183], v223 offset:18432
	ds_read_b128 v[184:187], v223 offset:19456
	ds_read_b128 v[188:191], v223 offset:20480
	ds_read_b128 v[192:195], v223 offset:21504
	ds_read_b128 v[202:205], v223 offset:22528
	ds_read_b128 v[206:209], v223 offset:23552
	global_load_lds_dwordx4 v[210:211], off
	s_add_i32 m0, s66, 0x2000
	v_lshl_add_u64 v[212:213], s[12:13], 0, v[150:151]
	s_add_u32 s12, s12, s26
	s_addc_u32 s13, s13, s27
	s_add_i32 s11, s11, s85
	global_load_lds_dwordx4 v[212:213], off
	v_lshl_add_u64 v[214:215], s[12:13], 0, v[0:1]
	s_mov_b32 m0, s11
	v_lshl_add_u64 v[216:217], s[12:13], 0, v[150:151]
	global_load_lds_dwordx4 v[214:215], off
	s_add_i32 m0, s11, 0x2000
	v_lshl_add_u64 v[218:219], s[8:9], 0, v[146:147]
	global_load_lds_dwordx4 v[216:217], off
	s_mov_b32 m0, s44
	v_lshl_add_u64 v[220:221], s[8:9], 0, v[148:149]
	global_load_lds_dwordx4 v[218:219], off
	s_mov_b32 m0, s45
	s_nop 0
	global_load_lds_dwordx4 v[220:221], off
	s_cmp_eq_u32 s42, 1
	s_cbranch_scc1 .Lkl427_w1f
	s_waitcnt vmcnt(24)
	s_branch .Lkl427_w1j

; #define PG8_STAGE(bufoff, gbase, voff) do { _Pragma("unroll") for (int _i = 0; _i < 2; ++_i) \
;         __builtin_amdgcn_global_load_lds((const unsigned*)((const char*)(gbase) + (voff)[_i]), (LAS unsigned*)(lds + (bufoff) + ldsw + _i * 8192), 16, 0, 0); } while (0)
; #define PG8_LDA(dst, b, h) do { _Pragma("unroll") for (int m = 0; m < 4; ++m) _Pragma("unroll") for (int k = 0; k < 2; ++k) dst[m][k] = *(const LAS bf16x8*)(lds + PG8_SA(b, h) + aoff + m * 2048 + k * 1024); } while (0)
; #define PG8_LDB(dst, b, h) do { _Pragma("unroll") for (int n = 0; n < 2; ++n) _Pragma("unroll") for (int k = 0; k < 2; ++k) dst[n][k] = *(const LAS bf16x8*)(lds + PG8_SB(b, h) + boff + n * 2048 + k * 1024); } while (0)
; #define PG8_MMA(ai, bj, At, Bt) do { __builtin_amdgcn_s_setprio(1); _Pragma("unroll") for (int m = 0; m < 4; ++m) _Pragma("unroll") for (int n = 0; n < 2; ++n) _Pragma("unroll") for (int k = 0; k < 2; ++k) \
;         acc[ai][bj][m][n] = __builtin_amdgcn_mfma_f32_16x16x32_bf16(Bt[n][k], At[m][k], acc[ai][bj][m][n], 0, 0, 0); __builtin_amdgcn_s_setprio(0); } while (0)
; #define PG8_WAIT_V(n) asm volatile("s_waitcnt vmcnt(" #n ")" ::: "memory")
; #define PG8_WAIT_L(n) asm volatile("s_waitcnt lgkmcnt(" #n ")" ::: "memory")
; #define PG8_BAR __builtin_amdgcn_s_barrier()
; #define PG8_SCHED __builtin_amdgcn_sched_barrier(0)
; template <class Epi>
; __device__ __forceinline__ void gemm_phase(LAS unsigned char* lds, const Gemm g, const StaticOrder& S, const Epi& E, const int tid) {
;     ...
;             PG8_WAIT_V(8); PG8_WAIT_L(0); PG8_BAR; PG8_MMA(1, 0, At, B0); PG8_MMA(1, 1, At, B1); PG8_BAR; PG8_SCHED;
;             PG8_LDB(B0, 1, 0); PG8_LDB(B1, 1, 1); PG8_SCHED; PG8_LDA(At, 1, 0); PG8_STAGE(PG8_SA(0, 1), a2 + hstepA, voffA);
.Lkl427_w1j:
	s_waitcnt lgkmcnt(0)
	s_barrier
	s_setprio 1
	s_waitcnt lgkmcnt(0)
	v_mfma_f32_16x16x32_bf16 v[62:65], v[66:69], v[172:175], 0
	v_mfma_f32_16x16x32_bf16 v[58:61], v[74:77], v[172:175], 0
	v_mfma_f32_16x16x32_bf16 v[46:49], v[66:69], v[180:183], 0
	v_mfma_f32_16x16x32_bf16 v[42:45], v[74:77], v[180:183], 0
	v_mfma_f32_16x16x32_bf16 v[30:33], v[66:69], v[188:191], 0
	v_mfma_f32_16x16x32_bf16 v[26:29], v[74:77], v[188:191], 0
	v_mfma_f32_16x16x32_bf16 v[14:17], v[66:69], v[202:205], 0
	v_mfma_f32_16x16x32_bf16 v[10:13], v[74:77], v[202:205], 0
	v_mfma_f32_16x16x32_bf16 v[62:65], v[70:73], v[176:179], v[62:65]
	v_mfma_f32_16x16x32_bf16 v[58:61], v[78:81], v[176:179], v[58:61]
	v_mfma_f32_16x16x32_bf16 v[46:49], v[70:73], v[184:187], v[46:49]
	v_mfma_f32_16x16x32_bf16 v[42:45], v[78:81], v[184:187], v[42:45]
	v_mfma_f32_16x16x32_bf16 v[30:33], v[70:73], v[192:195], v[30:33]
	v_mfma_f32_16x16x32_bf16 v[26:29], v[78:81], v[192:195], v[26:29]
	v_mfma_f32_16x16x32_bf16 v[14:17], v[70:73], v[206:209], v[14:17]
	v_mfma_f32_16x16x32_bf16 v[10:13], v[78:81], v[206:209], v[10:13]
	v_mfma_f32_16x16x32_bf16 v[54:57], v[156:159], v[172:175], 0
	v_mfma_f32_16x16x32_bf16 v[50:53], v[164:167], v[172:175], 0
	v_mfma_f32_16x16x32_bf16 v[38:41], v[156:159], v[180:183], 0
	v_mfma_f32_16x16x32_bf16 v[34:37], v[164:167], v[180:183], 0
	v_mfma_f32_16x16x32_bf16 v[22:25], v[156:159], v[188:191], 0
	v_mfma_f32_16x16x32_bf16 v[18:21], v[164:167], v[188:191], 0
	v_mfma_f32_16x16x32_bf16 v[6:9], v[156:159], v[202:205], 0
	v_mfma_f32_16x16x32_bf16 v[2:5], v[164:167], v[202:205], 0
	v_mfma_f32_16x16x32_bf16 v[54:57], v[160:163], v[176:179], v[54:57]
	v_mfma_f32_16x16x32_bf16 v[50:53], v[168:171], v[176:179], v[50:53]
	v_mfma_f32_16x16x32_bf16 v[38:41], v[160:163], v[184:187], v[38:41]
	v_mfma_f32_16x16x32_bf16 v[34:37], v[168:171], v[184:187], v[34:37]
	v_mfma_f32_16x16x32_bf16 v[22:25], v[160:163], v[192:195], v[22:25]
	v_mfma_f32_16x16x32_bf16 v[18:21], v[168:171], v[192:195], v[18:21]
	v_mfma_f32_16x16x32_bf16 v[6:9], v[160:163], v[206:209], v[6:9]
	v_mfma_f32_16x16x32_bf16 v[2:5], v[168:171], v[206:209], v[2:5]
	s_setprio 0
	s_barrier
	s_add_i32 s11, 0, 0x18000
	s_add_i32 s12, 0, 0x1c000
	v_add_u32_e32 v78, s11, v222
	v_add_u32_e32 v168, s12, v222
	ds_read_b128 v[66:69], v78
	ds_read_b128 v[70:73], v78 offset:1024
	ds_read_b128 v[74:77], v78 offset:2048
	ds_read_b128 v[78:81], v78 offset:3072
	ds_read_b128 v[156:159], v168
	ds_read_b128 v[160:163], v168 offset:1024
	ds_read_b128 v[164:167], v168 offset:2048
	ds_read_b128 v[168:171], v168 offset:3072
	s_add_u32 s8, s8, s24
	s_addc_u32 s9, s9, s25
	s_mov_b32 m0, s52
	v_lshl_add_u64 v[224:225], s[8:9], 0, v[146:147]
	ds_read_b128 v[172:175], v223 offset:32768
	ds_read_b128 v[176:179], v223 offset:33792
	ds_read_b128 v[180:183], v223 offset:34816
	ds_read_b128 v[184:187], v223 offset:35840
	ds_read_b128 v[188:191], v223 offset:36864
	ds_read_b128 v[192:195], v223 offset:37888
	ds_read_b128 v[202:205], v223 offset:38912
	ds_read_b128 v[206:209], v223 offset:39936
	global_load_lds_dwordx4 v[224:225], off
	v_lshl_add_u64 v[224:225], s[8:9], 0, v[148:149]
	s_mov_b32 m0, s53
	s_nop 0
	global_load_lds_dwordx4 v[224:225], off
	s_cmp_eq_u32 s42, 1
	s_cbranch_scc1 .Lkl427_w2f
	s_waitcnt vmcnt(24)
	s_branch .Lkl427_w2j

; #define PG8_STAGE(bufoff, gbase, voff) do { _Pragma("unroll") for (int _i = 0; _i < 2; ++_i) \
;         __builtin_amdgcn_global_load_lds((const unsigned*)((const char*)(gbase) + (voff)[_i]), (LAS unsigned*)(lds + (bufoff) + ldsw + _i * 8192), 16, 0, 0); } while (0)
; #define PG8_LDA(dst, b, h) do { _Pragma("unroll") for (int m = 0; m < 4; ++m) _Pragma("unroll") for (int k = 0; k < 2; ++k) dst[m][k] = *(const LAS bf16x8*)(lds + PG8_SA(b, h) + aoff + m * 2048 + k * 1024); } while (0)
; #define PG8_LDB(dst, b, h) do { _Pragma("unroll") for (int n = 0; n < 2; ++n) _Pragma("unroll") for (int k = 0; k < 2; ++k) dst[n][k] = *(const LAS bf16x8*)(lds + PG8_SB(b, h) + boff + n * 2048 + k * 1024); } while (0)
; #define PG8_MMA(ai, bj, At, Bt) do { __builtin_amdgcn_s_setprio(1); _Pragma("unroll") for (int m = 0; m < 4; ++m) _Pragma("unroll") for (int n = 0; n < 2; ++n) _Pragma("unroll") for (int k = 0; k < 2; ++k) \
;         acc[ai][bj][m][n] = __builtin_amdgcn_mfma_f32_16x16x32_bf16(Bt[n][k], At[m][k], acc[ai][bj][m][n], 0, 0, 0); __builtin_amdgcn_s_setprio(0); } while (0)
; #define PG8_WAIT_V(n) asm volatile("s_waitcnt vmcnt(" #n ")" ::: "memory")
; #define PG8_WAIT_L(n) asm volatile("s_waitcnt lgkmcnt(" #n ")" ::: "memory")
; #define PG8_BAR __builtin_amdgcn_s_barrier()
; #define PG8_SCHED __builtin_amdgcn_sched_barrier(0)
; template <class Epi>
; __device__ __forceinline__ void gemm_phase(LAS unsigned char* lds, const Gemm g, const StaticOrder& S, const Epi& E, const int tid) {
;     ...
;         for (int t = 0; t < nt; t += 2) {
;             const bool last = (t == nt - 2);
;             const char* a1 = cA + (size_t)(t + 1) * kstep;
;             const char* a2 = last ? nA : cA + (size_t)(t + 2) * kstep; const char* b2 = last ? nB : cB + (size_t)(t + 2) * kstep;
;             const char* a3 = a2 + kstep; const char* b3 = b2 + kstep;
;             PG8_LDB(B0, 0, 0); PG8_LDB(B1, 0, 1); PG8_SCHED; PG8_LDA(At, 0, 0); PG8_STAGE(PG8_SA(1, 1), a1 + hstepA, voffA);
;             PG8_WAIT_V(8); PG8_WAIT_L(0); PG8_BAR; PG8_MMA(0, 0, At, B0); PG8_MMA(0, 1, At, B1); PG8_BAR; PG8_SCHED;
;     ...
;             PG8_WAIT_V(8); PG8_WAIT_L(0); PG8_BAR; PG8_MMA(0, 0, At, B0); PG8_MMA(0, 1, At, B1); PG8_BAR; PG8_SCHED;
.Lkl427_w2j:
	s_waitcnt lgkmcnt(0)
	s_barrier
	s_setprio 1
	s_waitcnt lgkmcnt(0)
	v_mfma_f32_16x16x32_bf16 v[142:145], v[66:69], v[172:175], v[142:145]
	v_mfma_f32_16x16x32_bf16 v[138:141], v[74:77], v[172:175], v[138:141]
	v_mfma_f32_16x16x32_bf16 v[126:129], v[66:69], v[180:183], v[126:129]
	v_mfma_f32_16x16x32_bf16 v[122:125], v[74:77], v[180:183], v[122:125]
	v_mfma_f32_16x16x32_bf16 v[110:113], v[66:69], v[188:191], v[110:113]
	v_mfma_f32_16x16x32_bf16 v[106:109], v[74:77], v[188:191], v[106:109]
	v_mfma_f32_16x16x32_bf16 v[94:97], v[66:69], v[202:205], v[94:97]
	v_mfma_f32_16x16x32_bf16 v[90:93], v[74:77], v[202:205], v[90:93]
	v_mfma_f32_16x16x32_bf16 v[142:145], v[70:73], v[176:179], v[142:145]
	v_mfma_f32_16x16x32_bf16 v[138:141], v[78:81], v[176:179], v[138:141]
	v_mfma_f32_16x16x32_bf16 v[126:129], v[70:73], v[184:187], v[126:129]
	v_mfma_f32_16x16x32_bf16 v[122:125], v[78:81], v[184:187], v[122:125]
	v_mfma_f32_16x16x32_bf16 v[110:113], v[70:73], v[192:195], v[110:113]
	v_mfma_f32_16x16x32_bf16 v[106:109], v[78:81], v[192:195], v[106:109]
	v_mfma_f32_16x16x32_bf16 v[94:97], v[70:73], v[206:209], v[94:97]
	v_mfma_f32_16x16x32_bf16 v[90:93], v[78:81], v[206:209], v[90:93]
	v_mfma_f32_16x16x32_bf16 v[134:137], v[156:159], v[172:175], v[134:137]
	v_mfma_f32_16x16x32_bf16 v[130:133], v[164:167], v[172:175], v[130:133]
	v_mfma_f32_16x16x32_bf16 v[118:121], v[156:159], v[180:183], v[118:121]
	v_mfma_f32_16x16x32_bf16 v[114:117], v[164:167], v[180:183], v[114:117]
	v_mfma_f32_16x16x32_bf16 v[102:105], v[156:159], v[188:191], v[102:105]
	v_mfma_f32_16x16x32_bf16 v[98:101], v[164:167], v[188:191], v[98:101]
	v_mfma_f32_16x16x32_bf16 v[86:89], v[156:159], v[202:205], v[86:89]
	v_mfma_f32_16x16x32_bf16 v[82:85], v[164:167], v[202:205], v[82:85]
	v_mfma_f32_16x16x32_bf16 v[134:137], v[160:163], v[176:179], v[134:137]
	v_mfma_f32_16x16x32_bf16 v[130:133], v[168:171], v[176:179], v[130:133]
	v_mfma_f32_16x16x32_bf16 v[118:121], v[160:163], v[184:187], v[118:121]
	v_mfma_f32_16x16x32_bf16 v[114:117], v[168:171], v[184:187], v[114:117]
	v_mfma_f32_16x16x32_bf16 v[102:105], v[160:163], v[192:195], v[102:105]
	v_mfma_f32_16x16x32_bf16 v[98:101], v[168:171], v[192:195], v[98:101]
	v_mfma_f32_16x16x32_bf16 v[86:89], v[160:163], v[206:209], v[86:89]
	v_mfma_f32_16x16x32_bf16 v[82:85], v[168:171], v[206:209], v[82:85]
	s_setprio 0
	s_barrier
	s_branch .Lkl427_sp3
.LBB0_427:
	s_add_i32 s10, s8, 2
	s_add_u32 s11, s6, 0x80
	s_addc_u32 s9, s7, 0
	s_add_i32 s66, 0, 0x10000
	s_cmp_eq_u32 s43, s8
	s_cselect_b32 s9, s63, s9
	s_cselect_b32 s8, s62, s11
	s_cselect_b32 s13, s65, s1
	s_cselect_b32 s12, s64, s0
	s_add_i32 s11, 0, 0x14000
	v_add_u32_e32 v78, s66, v222
	v_add_u32_e32 v168, s11, v222
	ds_read_b128 v[66:69], v78
	ds_read_b128 v[70:73], v78 offset:1024
	ds_read_b128 v[74:77], v78 offset:2048
	ds_read_b128 v[78:81], v78 offset:3072
	ds_read_b128 v[156:159], v168
	ds_read_b128 v[160:163], v168 offset:1024
	ds_read_b128 v[164:167], v168 offset:2048
	ds_read_b128 v[168:171], v168 offset:3072
	v_lshl_add_u64 v[210:211], s[6:7], 0, v[154:155]
	s_add_i32 m0, s44, 0xc000
	ds_read_b128 v[172:175], v223
	ds_read_b128 v[176:179], v223 offset:1024
	ds_read_b128 v[180:183], v223 offset:2048
	ds_read_b128 v[184:187], v223 offset:3072
	ds_read_b128 v[188:191], v223 offset:4096
	ds_read_b128 v[192:195], v223 offset:5120
	ds_read_b128 v[202:205], v223 offset:6144
	ds_read_b128 v[206:209], v223 offset:7168
	global_load_lds_dwordx4 v[210:211], off
	v_lshl_add_u64 v[210:211], s[6:7], 0, v[152:153]
	s_add_i32 m0, s44, 0xe000
	s_nop 0
	global_load_lds_dwordx4 v[210:211], off
	s_waitcnt vmcnt(8)
	s_waitcnt lgkmcnt(0)
	s_barrier
	s_setprio 1
	s_waitcnt lgkmcnt(0)
	v_mfma_f32_16x16x32_bf16 v[142:145], v[66:69], v[172:175], v[142:145]
	v_mfma_f32_16x16x32_bf16 v[138:141], v[74:77], v[172:175], v[138:141]
	v_mfma_f32_16x16x32_bf16 v[126:129], v[66:69], v[180:183], v[126:129]
	v_mfma_f32_16x16x32_bf16 v[122:125], v[74:77], v[180:183], v[122:125]
	v_mfma_f32_16x16x32_bf16 v[110:113], v[66:69], v[188:191], v[110:113]
	v_mfma_f32_16x16x32_bf16 v[106:109], v[74:77], v[188:191], v[106:109]
	v_mfma_f32_16x16x32_bf16 v[94:97], v[66:69], v[202:205], v[94:97]
	v_mfma_f32_16x16x32_bf16 v[90:93], v[74:77], v[202:205], v[90:93]
	v_mfma_f32_16x16x32_bf16 v[142:145], v[70:73], v[176:179], v[142:145]
	v_mfma_f32_16x16x32_bf16 v[138:141], v[78:81], v[176:179], v[138:141]
	v_mfma_f32_16x16x32_bf16 v[126:129], v[70:73], v[184:187], v[126:129]
	v_mfma_f32_16x16x32_bf16 v[122:125], v[78:81], v[184:187], v[122:125]
	v_mfma_f32_16x16x32_bf16 v[110:113], v[70:73], v[192:195], v[110:113]
	v_mfma_f32_16x16x32_bf16 v[106:109], v[78:81], v[192:195], v[106:109]
	v_mfma_f32_16x16x32_bf16 v[94:97], v[70:73], v[206:209], v[94:97]
	v_mfma_f32_16x16x32_bf16 v[90:93], v[78:81], v[206:209], v[90:93]
	v_mfma_f32_16x16x32_bf16 v[134:137], v[156:159], v[172:175], v[134:137]
	v_mfma_f32_16x16x32_bf16 v[130:133], v[164:167], v[172:175], v[130:133]
	v_mfma_f32_16x16x32_bf16 v[118:121], v[156:159], v[180:183], v[118:121]
	v_mfma_f32_16x16x32_bf16 v[114:117], v[164:167], v[180:183], v[114:117]
	v_mfma_f32_16x16x32_bf16 v[102:105], v[156:159], v[188:191], v[102:105]
	v_mfma_f32_16x16x32_bf16 v[98:101], v[164:167], v[188:191], v[98:101]
	v_mfma_f32_16x16x32_bf16 v[86:89], v[156:159], v[202:205], v[86:89]
	v_mfma_f32_16x16x32_bf16 v[82:85], v[164:167], v[202:205], v[82:85]
	v_mfma_f32_16x16x32_bf16 v[134:137], v[160:163], v[176:179], v[134:137]
	v_mfma_f32_16x16x32_bf16 v[130:133], v[168:171], v[176:179], v[130:133]
	v_mfma_f32_16x16x32_bf16 v[118:121], v[160:163], v[184:187], v[118:121]
	v_mfma_f32_16x16x32_bf16 v[114:117], v[168:171], v[184:187], v[114:117]
	v_mfma_f32_16x16x32_bf16 v[102:105], v[160:163], v[192:195], v[102:105]
	v_mfma_f32_16x16x32_bf16 v[98:101], v[168:171], v[192:195], v[98:101]
	v_mfma_f32_16x16x32_bf16 v[86:89], v[160:163], v[206:209], v[86:89]
	v_mfma_f32_16x16x32_bf16 v[82:85], v[168:171], v[206:209], v[82:85]
	s_setprio 0
	s_barrier
; #define PG8_STAGE(bufoff, gbase, voff) do { _Pragma("unroll") for (int _i = 0; _i < 2; ++_i) \
;         __builtin_amdgcn_global_load_lds((const unsigned*)((const char*)(gbase) + (voff)[_i]), (LAS unsigned*)(lds + (bufoff) + ldsw + _i * 8192), 16, 0, 0); } while (0)
; #define PG8_LDA(dst, b, h) do { _Pragma("unroll") for (int m = 0; m < 4; ++m) _Pragma("unroll") for (int k = 0; k < 2; ++k) dst[m][k] = *(const LAS bf16x8*)(lds + PG8_SA(b, h) + aoff + m * 2048 + k * 1024); } while (0)
; #define PG8_LDB(dst, b, h) do { _Pragma("unroll") for (int n = 0; n < 2; ++n) _Pragma("unroll") for (int k = 0; k < 2; ++k) dst[n][k] = *(const LAS bf16x8*)(lds + PG8_SB(b, h) + boff + n * 2048 + k * 1024); } while (0)
; #define PG8_MMA(ai, bj, At, Bt) do { __builtin_amdgcn_s_setprio(1); _Pragma("unroll") for (int m = 0; m < 4; ++m) _Pragma("unroll") for (int n = 0; n < 2; ++n) _Pragma("unroll") for (int k = 0; k < 2; ++k) \
;         acc[ai][bj][m][n] = __builtin_amdgcn_mfma_f32_16x16x32_bf16(Bt[n][k], At[m][k], acc[ai][bj][m][n], 0, 0, 0); __builtin_amdgcn_s_setprio(0); } while (0)
; #define PG8_WAIT_V(n) asm volatile("s_waitcnt vmcnt(" #n ")" ::: "memory")
; #define PG8_WAIT_L(n) asm volatile("s_waitcnt lgkmcnt(" #n ")" ::: "memory")
; #define PG8_BAR __builtin_amdgcn_s_barrier()
; #define PG8_SCHED __builtin_amdgcn_sched_barrier(0)
; template <class Epi>
; __device__ __forceinline__ void gemm_phase(LAS unsigned char* lds, const Gemm g, const StaticOrder& S, const Epi& E, const int tid) {
;     ...
;             PG8_LDA(At, 0, 1); PG8_STAGE(PG8_SB(0, 0), b2, voffB); PG8_STAGE(PG8_SB(0, 1), b2 + hstepB, voffB); PG8_STAGE(PG8_SA(0, 0), a2, voffA);
;             PG8_WAIT_V(8); PG8_WAIT_L(0); PG8_BAR; PG8_MMA(1, 0, At, B0); PG8_MMA(1, 1, At, B1); PG8_BAR; PG8_SCHED;
;             PG8_LDB(B0, 1, 0); PG8_LDB(B1, 1, 1); PG8_SCHED; PG8_LDA(At, 1, 0); PG8_STAGE(PG8_SA(0, 1), a2 + hstepA, voffA);
;             PG8_WAIT_V(8); PG8_WAIT_L(0); PG8_BAR; PG8_MMA(0, 0, At, B0); PG8_MMA(0, 1, At, B1); PG8_BAR; PG8_SCHED;
	s_add_i32 s66, s66, s85
	v_lshl_add_u64 v[210:211], s[12:13], 0, v[0:1]
	s_mov_b32 m0, s66
	ds_read_b128 v[172:175], v223 offset:16384
	ds_read_b128 v[176:179], v223 offset:17408
	ds_read_b128 v[180:183], v223 offset:18432
	ds_read_b128 v[184:187], v223 offset:19456
	ds_read_b128 v[188:191], v223 offset:20480
	ds_read_b128 v[192:195], v223 offset:21504
	ds_read_b128 v[202:205], v223 offset:22528
	ds_read_b128 v[206:209], v223 offset:23552
	global_load_lds_dwordx4 v[210:211], off
	s_add_i32 m0, s66, 0x2000
	v_lshl_add_u64 v[212:213], s[12:13], 0, v[150:151]
	s_add_u32 s12, s12, s26
	s_addc_u32 s13, s13, s27
	s_add_i32 s11, s11, s85
	global_load_lds_dwordx4 v[212:213], off
	v_lshl_add_u64 v[214:215], s[12:13], 0, v[0:1]
	s_mov_b32 m0, s11
	v_lshl_add_u64 v[216:217], s[12:13], 0, v[150:151]
	global_load_lds_dwordx4 v[214:215], off
	s_add_i32 m0, s11, 0x2000
	v_lshl_add_u64 v[218:219], s[8:9], 0, v[146:147]
	global_load_lds_dwordx4 v[216:217], off
	s_mov_b32 m0, s44
	v_lshl_add_u64 v[220:221], s[8:9], 0, v[148:149]
	global_load_lds_dwordx4 v[218:219], off
	s_mov_b32 m0, s45
	s_nop 0
	global_load_lds_dwordx4 v[220:221], off
	s_waitcnt vmcnt(8)
	s_waitcnt lgkmcnt(0)
	s_barrier
	s_setprio 1
	s_waitcnt lgkmcnt(0)
	v_mfma_f32_16x16x32_bf16 v[62:65], v[66:69], v[172:175], v[62:65]
	v_mfma_f32_16x16x32_bf16 v[58:61], v[74:77], v[172:175], v[58:61]
	v_mfma_f32_16x16x32_bf16 v[46:49], v[66:69], v[180:183], v[46:49]
	v_mfma_f32_16x16x32_bf16 v[42:45], v[74:77], v[180:183], v[42:45]
	v_mfma_f32_16x16x32_bf16 v[30:33], v[66:69], v[188:191], v[30:33]
	v_mfma_f32_16x16x32_bf16 v[26:29], v[74:77], v[188:191], v[26:29]
	v_mfma_f32_16x16x32_bf16 v[14:17], v[66:69], v[202:205], v[14:17]
	v_mfma_f32_16x16x32_bf16 v[10:13], v[74:77], v[202:205], v[10:13]
	v_mfma_f32_16x16x32_bf16 v[62:65], v[70:73], v[176:179], v[62:65]
	v_mfma_f32_16x16x32_bf16 v[58:61], v[78:81], v[176:179], v[58:61]
	v_mfma_f32_16x16x32_bf16 v[46:49], v[70:73], v[184:187], v[46:49]
	v_mfma_f32_16x16x32_bf16 v[42:45], v[78:81], v[184:187], v[42:45]
	v_mfma_f32_16x16x32_bf16 v[30:33], v[70:73], v[192:195], v[30:33]
	v_mfma_f32_16x16x32_bf16 v[26:29], v[78:81], v[192:195], v[26:29]
	v_mfma_f32_16x16x32_bf16 v[14:17], v[70:73], v[206:209], v[14:17]
	v_mfma_f32_16x16x32_bf16 v[10:13], v[78:81], v[206:209], v[10:13]
	v_mfma_f32_16x16x32_bf16 v[54:57], v[156:159], v[172:175], v[54:57]
	v_mfma_f32_16x16x32_bf16 v[50:53], v[164:167], v[172:175], v[50:53]
	v_mfma_f32_16x16x32_bf16 v[38:41], v[156:159], v[180:183], v[38:41]
	v_mfma_f32_16x16x32_bf16 v[34:37], v[164:167], v[180:183], v[34:37]
	v_mfma_f32_16x16x32_bf16 v[22:25], v[156:159], v[188:191], v[22:25]
	v_mfma_f32_16x16x32_bf16 v[18:21], v[164:167], v[188:191], v[18:21]
	v_mfma_f32_16x16x32_bf16 v[6:9], v[156:159], v[202:205], v[6:9]
	v_mfma_f32_16x16x32_bf16 v[2:5], v[164:167], v[202:205], v[2:5]
	v_mfma_f32_16x16x32_bf16 v[54:57], v[160:163], v[176:179], v[54:57]
	v_mfma_f32_16x16x32_bf16 v[50:53], v[168:171], v[176:179], v[50:53]
	v_mfma_f32_16x16x32_bf16 v[38:41], v[160:163], v[184:187], v[38:41]
	v_mfma_f32_16x16x32_bf16 v[34:37], v[168:171], v[184:187], v[34:37]
	v_mfma_f32_16x16x32_bf16 v[22:25], v[160:163], v[192:195], v[22:25]
	v_mfma_f32_16x16x32_bf16 v[18:21], v[168:171], v[192:195], v[18:21]
	v_mfma_f32_16x16x32_bf16 v[6:9], v[160:163], v[206:209], v[6:9]
	v_mfma_f32_16x16x32_bf16 v[2:5], v[168:171], v[206:209], v[2:5]
	s_setprio 0
	s_barrier
.Lkl427_sp2:
	s_add_i32 s11, 0, 0x18000
	s_add_i32 s12, 0, 0x1c000
	v_add_u32_e32 v78, s11, v222
	v_add_u32_e32 v168, s12, v222
	ds_read_b128 v[66:69], v78
	ds_read_b128 v[70:73], v78 offset:1024
	ds_read_b128 v[74:77], v78 offset:2048
	ds_read_b128 v[78:81], v78 offset:3072
	ds_read_b128 v[156:159], v168
	ds_read_b128 v[160:163], v168 offset:1024
	ds_read_b128 v[164:167], v168 offset:2048
	ds_read_b128 v[168:171], v168 offset:3072
	s_add_u32 s8, s8, s24
	s_addc_u32 s9, s9, s25
	s_mov_b32 m0, s52
	v_lshl_add_u64 v[224:225], s[8:9], 0, v[146:147]
	ds_read_b128 v[172:175], v223 offset:32768
	ds_read_b128 v[176:179], v223 offset:33792
	ds_read_b128 v[180:183], v223 offset:34816
	ds_read_b128 v[184:187], v223 offset:35840
	ds_read_b128 v[188:191], v223 offset:36864
	ds_read_b128 v[192:195], v223 offset:37888
	ds_read_b128 v[202:205], v223 offset:38912
	ds_read_b128 v[206:209], v223 offset:39936
	global_load_lds_dwordx4 v[224:225], off
	v_lshl_add_u64 v[224:225], s[8:9], 0, v[148:149]
	s_mov_b32 m0, s53
	s_nop 0
	global_load_lds_dwordx4 v[224:225], off
	s_waitcnt vmcnt(8)
	s_waitcnt lgkmcnt(0)
	s_barrier
	s_setprio 1
	s_waitcnt lgkmcnt(0)
	v_mfma_f32_16x16x32_bf16 v[142:145], v[66:69], v[172:175], v[142:145]
	v_mfma_f32_16x16x32_bf16 v[138:141], v[74:77], v[172:175], v[138:141]
	v_mfma_f32_16x16x32_bf16 v[126:129], v[66:69], v[180:183], v[126:129]
	v_mfma_f32_16x16x32_bf16 v[122:125], v[74:77], v[180:183], v[122:125]
	v_mfma_f32_16x16x32_bf16 v[110:113], v[66:69], v[188:191], v[110:113]
	v_mfma_f32_16x16x32_bf16 v[106:109], v[74:77], v[188:191], v[106:109]
	v_mfma_f32_16x16x32_bf16 v[94:97], v[66:69], v[202:205], v[94:97]
	v_mfma_f32_16x16x32_bf16 v[90:93], v[74:77], v[202:205], v[90:93]
	v_mfma_f32_16x16x32_bf16 v[142:145], v[70:73], v[176:179], v[142:145]
	v_mfma_f32_16x16x32_bf16 v[138:141], v[78:81], v[176:179], v[138:141]
	v_mfma_f32_16x16x32_bf16 v[126:129], v[70:73], v[184:187], v[126:129]
	v_mfma_f32_16x16x32_bf16 v[122:125], v[78:81], v[184:187], v[122:125]
	v_mfma_f32_16x16x32_bf16 v[110:113], v[70:73], v[192:195], v[110:113]
	v_mfma_f32_16x16x32_bf16 v[106:109], v[78:81], v[192:195], v[106:109]
	v_mfma_f32_16x16x32_bf16 v[94:97], v[70:73], v[206:209], v[94:97]
	v_mfma_f32_16x16x32_bf16 v[90:93], v[78:81], v[206:209], v[90:93]
	v_mfma_f32_16x16x32_bf16 v[134:137], v[156:159], v[172:175], v[134:137]
	v_mfma_f32_16x16x32_bf16 v[130:133], v[164:167], v[172:175], v[130:133]
	v_mfma_f32_16x16x32_bf16 v[118:121], v[156:159], v[180:183], v[118:121]
	v_mfma_f32_16x16x32_bf16 v[114:117], v[164:167], v[180:183], v[114:117]
	v_mfma_f32_16x16x32_bf16 v[102:105], v[156:159], v[188:191], v[102:105]
	v_mfma_f32_16x16x32_bf16 v[98:101], v[164:167], v[188:191], v[98:101]
	v_mfma_f32_16x16x32_bf16 v[86:89], v[156:159], v[202:205], v[86:89]
	v_mfma_f32_16x16x32_bf16 v[82:85], v[164:167], v[202:205], v[82:85]
	v_mfma_f32_16x16x32_bf16 v[134:137], v[160:163], v[176:179], v[134:137]
	v_mfma_f32_16x16x32_bf16 v[130:133], v[168:171], v[176:179], v[130:133]
	v_mfma_f32_16x16x32_bf16 v[118:121], v[160:163], v[184:187], v[118:121]
	v_mfma_f32_16x16x32_bf16 v[114:117], v[168:171], v[184:187], v[114:117]
	v_mfma_f32_16x16x32_bf16 v[102:105], v[160:163], v[192:195], v[102:105]
	v_mfma_f32_16x16x32_bf16 v[98:101], v[168:171], v[192:195], v[98:101]
	v_mfma_f32_16x16x32_bf16 v[86:89], v[160:163], v[206:209], v[86:89]
	v_mfma_f32_16x16x32_bf16 v[82:85], v[168:171], v[206:209], v[82:85]
	s_setprio 0
	s_barrier
; #define PG8_STAGE(bufoff, gbase, voff) do { _Pragma("unroll") for (int _i = 0; _i < 2; ++_i) \
;         __builtin_amdgcn_global_load_lds((const unsigned*)((const char*)(gbase) + (voff)[_i]), (LAS unsigned*)(lds + (bufoff) + ldsw + _i * 8192), 16, 0, 0); } while (0)
; #define PG8_LDA(dst, b, h) do { _Pragma("unroll") for (int m = 0; m < 4; ++m) _Pragma("unroll") for (int k = 0; k < 2; ++k) dst[m][k] = *(const LAS bf16x8*)(lds + PG8_SA(b, h) + aoff + m * 2048 + k * 1024); } while (0)
; #define PG8_MMA(ai, bj, At, Bt) do { __builtin_amdgcn_s_setprio(1); _Pragma("unroll") for (int m = 0; m < 4; ++m) _Pragma("unroll") for (int n = 0; n < 2; ++n) _Pragma("unroll") for (int k = 0; k < 2; ++k) \
;         acc[ai][bj][m][n] = __builtin_amdgcn_mfma_f32_16x16x32_bf16(Bt[n][k], At[m][k], acc[ai][bj][m][n], 0, 0, 0); __builtin_amdgcn_s_setprio(0); } while (0)
; #define PG8_WAIT_V(n) asm volatile("s_waitcnt vmcnt(" #n ")" ::: "memory")
; #define PG8_WAIT_L(n) asm volatile("s_waitcnt lgkmcnt(" #n ")" ::: "memory")
; #define PG8_BAR __builtin_amdgcn_s_barrier()
; #define PG8_SCHED __builtin_amdgcn_sched_barrier(0)
; template <class Epi>
; __device__ __forceinline__ void gemm_phase(LAS unsigned char* lds, const Gemm g, const StaticOrder& S, const Epi& E, const int tid) {
;     ...
;             PG8_LDA(At, 1, 1); PG8_STAGE(PG8_SB(1, 0), b3, voffB); PG8_STAGE(PG8_SB(1, 1), b3 + hstepB, voffB); PG8_STAGE(PG8_SA(1, 0), a3, voffA);
;             PG8_WAIT_V(8); PG8_WAIT_L(0); PG8_BAR; PG8_MMA(1, 0, At, B0); PG8_MMA(1, 1, At, B1); PG8_BAR; PG8_SCHED;
;         }
;         if (wr == 0) PG8_BAR;
.Lkl427_sp3:
	s_add_i32 s8, s11, s85
	v_lshl_add_u64 v[210:211], v[210:211], 0, s[80:81]
	s_mov_b32 m0, s8
	ds_read_b128 v[172:175], v223 offset:49152
	ds_read_b128 v[176:179], v223 offset:50176
	ds_read_b128 v[180:183], v223 offset:51200
	ds_read_b128 v[184:187], v223 offset:52224
	ds_read_b128 v[188:191], v223 offset:53248
	ds_read_b128 v[192:195], v223 offset:54272
	ds_read_b128 v[202:205], v223 offset:55296
	ds_read_b128 v[206:209], v223 offset:56320
	global_load_lds_dwordx4 v[210:211], off
	v_lshl_add_u64 v[210:211], v[212:213], 0, s[80:81]
	s_add_i32 m0, s8, 0x2000
	s_add_i32 s8, s12, s85
	global_load_lds_dwordx4 v[210:211], off
	v_lshl_add_u64 v[210:211], v[214:215], 0, s[80:81]
	s_mov_b32 m0, s8
	s_nop 0
	global_load_lds_dwordx4 v[210:211], off
	v_lshl_add_u64 v[210:211], v[216:217], 0, s[80:81]
	s_add_i32 m0, s8, 0x2000
	s_nop 0
	global_load_lds_dwordx4 v[210:211], off
	v_lshl_add_u64 v[210:211], v[218:219], 0, s[80:81]
	s_mov_b32 m0, s36
	s_nop 0
	global_load_lds_dwordx4 v[210:211], off
	v_lshl_add_u64 v[210:211], v[220:221], 0, s[80:81]
	s_mov_b32 m0, s37
	s_nop 0
	global_load_lds_dwordx4 v[210:211], off
	s_waitcnt vmcnt(8)
	s_waitcnt lgkmcnt(0)
	s_nop 0
	s_barrier
	s_setprio 1
	s_waitcnt lgkmcnt(0)
	v_mfma_f32_16x16x32_bf16 v[62:65], v[66:69], v[172:175], v[62:65]
	v_mfma_f32_16x16x32_bf16 v[58:61], v[74:77], v[172:175], v[58:61]
	v_mfma_f32_16x16x32_bf16 v[46:49], v[66:69], v[180:183], v[46:49]
	v_mfma_f32_16x16x32_bf16 v[42:45], v[74:77], v[180:183], v[42:45]
	v_mfma_f32_16x16x32_bf16 v[30:33], v[66:69], v[188:191], v[30:33]
	v_mfma_f32_16x16x32_bf16 v[26:29], v[74:77], v[188:191], v[26:29]
	v_mfma_f32_16x16x32_bf16 v[14:17], v[66:69], v[202:205], v[14:17]
	v_mfma_f32_16x16x32_bf16 v[10:13], v[74:77], v[202:205], v[10:13]
	v_mfma_f32_16x16x32_bf16 v[62:65], v[70:73], v[176:179], v[62:65]
	v_mfma_f32_16x16x32_bf16 v[58:61], v[78:81], v[176:179], v[58:61]
	v_mfma_f32_16x16x32_bf16 v[46:49], v[70:73], v[184:187], v[46:49]
	v_mfma_f32_16x16x32_bf16 v[42:45], v[78:81], v[184:187], v[42:45]
	v_mfma_f32_16x16x32_bf16 v[30:33], v[70:73], v[192:195], v[30:33]
	v_mfma_f32_16x16x32_bf16 v[26:29], v[78:81], v[192:195], v[26:29]
	v_mfma_f32_16x16x32_bf16 v[14:17], v[70:73], v[206:209], v[14:17]
	v_mfma_f32_16x16x32_bf16 v[10:13], v[78:81], v[206:209], v[10:13]
	v_mfma_f32_16x16x32_bf16 v[54:57], v[156:159], v[172:175], v[54:57]
	v_mfma_f32_16x16x32_bf16 v[50:53], v[164:167], v[172:175], v[50:53]
	v_mfma_f32_16x16x32_bf16 v[38:41], v[156:159], v[180:183], v[38:41]
	v_mfma_f32_16x16x32_bf16 v[34:37], v[164:167], v[180:183], v[34:37]
	v_mfma_f32_16x16x32_bf16 v[22:25], v[156:159], v[188:191], v[22:25]
	v_mfma_f32_16x16x32_bf16 v[18:21], v[164:167], v[188:191], v[18:21]
	v_mfma_f32_16x16x32_bf16 v[6:9], v[156:159], v[202:205], v[6:9]
	v_mfma_f32_16x16x32_bf16 v[2:5], v[164:167], v[202:205], v[2:5]
	v_mfma_f32_16x16x32_bf16 v[54:57], v[160:163], v[176:179], v[54:57]
	v_mfma_f32_16x16x32_bf16 v[50:53], v[168:171], v[176:179], v[50:53]
	v_mfma_f32_16x16x32_bf16 v[38:41], v[160:163], v[184:187], v[38:41]
	v_mfma_f32_16x16x32_bf16 v[34:37], v[168:171], v[184:187], v[34:37]
	v_mfma_f32_16x16x32_bf16 v[22:25], v[160:163], v[192:195], v[22:25]
	v_mfma_f32_16x16x32_bf16 v[18:21], v[168:171], v[192:195], v[18:21]
	v_mfma_f32_16x16x32_bf16 v[6:9], v[160:163], v[206:209], v[6:9]
	v_mfma_f32_16x16x32_bf16 v[2:5], v[168:171], v[206:209], v[2:5]
	s_setprio 0
	s_barrier
	s_add_u32 s0, s0, 0x100
	s_addc_u32 s1, s1, 0
	s_add_u32 s6, s6, 0x100
	s_addc_u32 s7, s7, 0
	s_cmp_ge_i32 s10, s35
	s_mov_b32 s8, s10
	s_cbranch_scc0 .LBB0_427
	s_and_b64 vcc, exec, s[4:5]
	s_cbranch_vccnz .Lkl427_noa
	s_add_u32 s98, s62, 0x80
	s_addc_u32 s99, s63, 0
	v_lshl_add_u64 v[210:211], s[98:99], 0, v[154:155]
	s_add_i32 m0, s44, 0xc000
	s_nop 0
	global_load_lds_dwordx4 v[210:211], off
	v_lshl_add_u64 v[210:211], s[98:99], 0, v[152:153]
	s_add_i32 m0, s44, 0xe000
	s_nop 0
	global_load_lds_dwordx4 v[210:211], off

; #define PG8_STAGE(bufoff, gbase, voff) do { _Pragma("unroll") for (int _i = 0; _i < 2; ++_i) \
;         __builtin_amdgcn_global_load_lds((const unsigned*)((const char*)(gbase) + (voff)[_i]), (LAS unsigned*)(lds + (bufoff) + ldsw + _i * 8192), 16, 0, 0); } while (0)
; #define PG8_LDA(dst, b, h) do { _Pragma("unroll") for (int m = 0; m < 4; ++m) _Pragma("unroll") for (int k = 0; k < 2; ++k) dst[m][k] = *(const LAS bf16x8*)(lds + PG8_SA(b, h) + aoff + m * 2048 + k * 1024); } while (0)
; #define PG8_LDB(dst, b, h) do { _Pragma("unroll") for (int n = 0; n < 2; ++n) _Pragma("unroll") for (int k = 0; k < 2; ++k) dst[n][k] = *(const LAS bf16x8*)(lds + PG8_SB(b, h) + boff + n * 2048 + k * 1024); } while (0)
; #define PG8_MMA(ai, bj, At, Bt) do { __builtin_amdgcn_s_setprio(1); _Pragma("unroll") for (int m = 0; m < 4; ++m) _Pragma("unroll") for (int n = 0; n < 2; ++n) _Pragma("unroll") for (int k = 0; k < 2; ++k) \
;         acc[ai][bj][m][n] = __builtin_amdgcn_mfma_f32_16x16x32_bf16(Bt[n][k], At[m][k], acc[ai][bj][m][n], 0, 0, 0); __builtin_amdgcn_s_setprio(0); } while (0)
; #define PG8_WAIT_V(n) asm volatile("s_waitcnt vmcnt(" #n ")" ::: "memory")
; #define PG8_WAIT_L(n) asm volatile("s_waitcnt lgkmcnt(" #n ")" ::: "memory")
; #define PG8_BAR __builtin_amdgcn_s_barrier()
; #define PG8_SCHED __builtin_amdgcn_sched_barrier(0)
; template <class Epi>
; __device__ __forceinline__ void gemm_phase(LAS unsigned char* lds, const Gemm g, const StaticOrder& S, const Epi& E, const int tid) {
;     ...
;             PG8_LDB(B0, 0, 0); PG8_LDB(B1, 0, 1); PG8_SCHED; PG8_LDA(At, 0, 0); PG8_STAGE(PG8_SA(1, 1), a1 + hstepA, voffA);
;             PG8_WAIT_V(8); PG8_WAIT_L(0); PG8_BAR; PG8_MMA(0, 0, At, B0); PG8_MMA(0, 1, At, B1); PG8_BAR; PG8_SCHED;
;             PG8_LDA(At, 0, 1); PG8_STAGE(PG8_SB(0, 0), b2, voffB); PG8_STAGE(PG8_SB(0, 1), b2 + hstepB, voffB); PG8_STAGE(PG8_SA(0, 0), a2, voffA);
.Lkl652_nofa:
	s_waitcnt vmcnt(10)
	s_waitcnt lgkmcnt(0)
	s_barrier
	s_setprio 1
	s_waitcnt lgkmcnt(0)
	v_mfma_f32_16x16x32_bf16 v[110:113], v[130:133], v[162:165], 0
	v_mfma_f32_16x16x32_bf16 v[106:109], v[138:141], v[162:165], 0
	v_mfma_f32_16x16x32_bf16 v[94:97], v[130:133], v[170:173], 0
	v_mfma_f32_16x16x32_bf16 v[90:93], v[138:141], v[170:173], 0
	v_mfma_f32_16x16x32_bf16 v[114:117], v[130:133], v[192:195], 0
	v_mfma_f32_16x16x32_bf16 v[62:65], v[138:141], v[192:195], 0
	v_mfma_f32_16x16x32_bf16 v[126:129], v[130:133], v[210:213], 0
	v_mfma_f32_16x16x32_bf16 v[70:73], v[138:141], v[210:213], 0
	v_mfma_f32_16x16x32_bf16 v[110:113], v[134:137], v[166:169], v[110:113]
	v_mfma_f32_16x16x32_bf16 v[106:109], v[142:145], v[166:169], v[106:109]
	v_mfma_f32_16x16x32_bf16 v[94:97], v[134:137], v[174:177], v[94:97]
	v_mfma_f32_16x16x32_bf16 v[90:93], v[142:145], v[174:177], v[90:93]
	v_mfma_f32_16x16x32_bf16 v[114:117], v[134:137], v[206:209], v[114:117]
	v_mfma_f32_16x16x32_bf16 v[62:65], v[142:145], v[206:209], v[62:65]
	v_mfma_f32_16x16x32_bf16 v[126:129], v[134:137], v[214:217], v[126:129]
	v_mfma_f32_16x16x32_bf16 v[70:73], v[142:145], v[214:217], v[70:73]
	v_mfma_f32_16x16x32_bf16 v[102:105], v[146:149], v[162:165], 0
	v_mfma_f32_16x16x32_bf16 v[98:101], v[154:157], v[162:165], 0
	v_mfma_f32_16x16x32_bf16 v[86:89], v[146:149], v[170:173], 0
	v_mfma_f32_16x16x32_bf16 v[82:85], v[154:157], v[170:173], 0
	v_mfma_f32_16x16x32_bf16 v[118:121], v[146:149], v[192:195], 0
	v_mfma_f32_16x16x32_bf16 v[58:61], v[154:157], v[192:195], 0
	v_mfma_f32_16x16x32_bf16 v[122:125], v[146:149], v[210:213], 0
	v_mfma_f32_16x16x32_bf16 v[66:69], v[154:157], v[210:213], 0
	v_mfma_f32_16x16x32_bf16 v[102:105], v[150:153], v[166:169], v[102:105]
	v_mfma_f32_16x16x32_bf16 v[98:101], v[158:161], v[166:169], v[98:101]
	v_mfma_f32_16x16x32_bf16 v[86:89], v[150:153], v[174:177], v[86:89]
	v_mfma_f32_16x16x32_bf16 v[82:85], v[158:161], v[174:177], v[82:85]
	v_mfma_f32_16x16x32_bf16 v[118:121], v[150:153], v[206:209], v[118:121]
	v_mfma_f32_16x16x32_bf16 v[58:61], v[158:161], v[206:209], v[58:61]
	v_mfma_f32_16x16x32_bf16 v[122:125], v[150:153], v[214:217], v[122:125]
	v_mfma_f32_16x16x32_bf16 v[66:69], v[158:161], v[214:217], v[66:69]
	s_setprio 0
	s_barrier
	s_add_i32 s43, s43, s53
	v_lshl_add_u64 v[178:179], s[44:45], 0, v[182:183]
	s_mov_b32 m0, s43
	ds_read_b128 v[162:165], v205 offset:16384
	ds_read_b128 v[166:169], v205 offset:17408
	ds_read_b128 v[170:173], v205 offset:18432
	ds_read_b128 v[174:177], v205 offset:19456
	ds_read_b128 v[192:195], v205 offset:20480
	ds_read_b128 v[206:209], v205 offset:21504
	ds_read_b128 v[210:213], v205 offset:22528
	ds_read_b128 v[214:217], v205 offset:23552
	global_load_lds_dwordx4 v[178:179], off
	s_add_i32 m0, s43, 0x2000
	v_lshl_add_u64 v[202:203], s[44:45], 0, v[186:187]
	s_add_u32 s44, s44, s12
	s_addc_u32 s45, s45, s13
	s_add_i32 s11, s11, s53
	global_load_lds_dwordx4 v[202:203], off
	v_lshl_add_u64 v[218:219], s[44:45], 0, v[182:183]
	s_mov_b32 m0, s11
	v_lshl_add_u64 v[220:221], s[44:45], 0, v[186:187]
	global_load_lds_dwordx4 v[218:219], off
	s_add_i32 m0, s11, 0x2000
	v_lshl_add_u64 v[222:223], s[8:9], 0, v[180:181]
	global_load_lds_dwordx4 v[220:221], off
	s_mov_b32 m0, s54
	v_lshl_add_u64 v[224:225], s[8:9], 0, v[184:185]
	global_load_lds_dwordx4 v[222:223], off
	s_mov_b32 m0, s55
	s_nop 0
	global_load_lds_dwordx4 v[224:225], off
	s_cmp_eq_u32 s73, 1
	s_cbranch_scc1 .Lkl652_w1f
	s_waitcnt vmcnt(16)
	s_branch .Lkl652_w1j

; #define PG8_STAGE(bufoff, gbase, voff) do { _Pragma("unroll") for (int _i = 0; _i < 2; ++_i) \
;         __builtin_amdgcn_global_load_lds((const unsigned*)((const char*)(gbase) + (voff)[_i]), (LAS unsigned*)(lds + (bufoff) + ldsw + _i * 8192), 16, 0, 0); } while (0)
; #define PG8_LDA(dst, b, h) do { _Pragma("unroll") for (int m = 0; m < 4; ++m) _Pragma("unroll") for (int k = 0; k < 2; ++k) dst[m][k] = *(const LAS bf16x8*)(lds + PG8_SA(b, h) + aoff + m * 2048 + k * 1024); } while (0)
; #define PG8_LDB(dst, b, h) do { _Pragma("unroll") for (int n = 0; n < 2; ++n) _Pragma("unroll") for (int k = 0; k < 2; ++k) dst[n][k] = *(const LAS bf16x8*)(lds + PG8_SB(b, h) + boff + n * 2048 + k * 1024); } while (0)
; #define PG8_MMA(ai, bj, At, Bt) do { __builtin_amdgcn_s_setprio(1); _Pragma("unroll") for (int m = 0; m < 4; ++m) _Pragma("unroll") for (int n = 0; n < 2; ++n) _Pragma("unroll") for (int k = 0; k < 2; ++k) \
;         acc[ai][bj][m][n] = __builtin_amdgcn_mfma_f32_16x16x32_bf16(Bt[n][k], At[m][k], acc[ai][bj][m][n], 0, 0, 0); __builtin_amdgcn_s_setprio(0); } while (0)
; #define PG8_WAIT_V(n) asm volatile("s_waitcnt vmcnt(" #n ")" ::: "memory")
; #define PG8_WAIT_L(n) asm volatile("s_waitcnt lgkmcnt(" #n ")" ::: "memory")
; #define PG8_BAR __builtin_amdgcn_s_barrier()
; #define PG8_SCHED __builtin_amdgcn_sched_barrier(0)
; template <class Epi>
; __device__ __forceinline__ void gemm_phase(LAS unsigned char* lds, const Gemm g, const StaticOrder& S, const Epi& E, const int tid) {
;     ...
;             PG8_WAIT_V(8); PG8_WAIT_L(0); PG8_BAR; PG8_MMA(1, 0, At, B0); PG8_MMA(1, 1, At, B1); PG8_BAR; PG8_SCHED;
;             PG8_LDB(B0, 1, 0); PG8_LDB(B1, 1, 1); PG8_SCHED; PG8_LDA(At, 1, 0); PG8_STAGE(PG8_SA(0, 1), a2 + hstepA, voffA);
.Lkl652_w1j:
	s_waitcnt lgkmcnt(0)
	s_barrier
	s_setprio 1
	s_waitcnt lgkmcnt(0)
	v_mfma_f32_16x16x32_bf16 v[46:49], v[130:133], v[162:165], 0
	v_mfma_f32_16x16x32_bf16 v[30:33], v[138:141], v[162:165], 0
	v_mfma_f32_16x16x32_bf16 v[38:41], v[130:133], v[170:173], 0
	v_mfma_f32_16x16x32_bf16 v[18:21], v[138:141], v[170:173], 0
	v_mfma_f32_16x16x32_bf16 v[50:53], v[130:133], v[192:195], 0
	v_mfma_f32_16x16x32_bf16 v[2:5], v[138:141], v[192:195], 0
	v_mfma_f32_16x16x32_bf16 v[74:77], v[130:133], v[210:213], 0
	v_mfma_f32_16x16x32_bf16 v[10:13], v[138:141], v[210:213], 0
	v_mfma_f32_16x16x32_bf16 v[46:49], v[134:137], v[166:169], v[46:49]
	v_mfma_f32_16x16x32_bf16 v[30:33], v[142:145], v[166:169], v[30:33]
	v_mfma_f32_16x16x32_bf16 v[38:41], v[134:137], v[174:177], v[38:41]
	v_mfma_f32_16x16x32_bf16 v[18:21], v[142:145], v[174:177], v[18:21]
	v_mfma_f32_16x16x32_bf16 v[50:53], v[134:137], v[206:209], v[50:53]
	v_mfma_f32_16x16x32_bf16 v[2:5], v[142:145], v[206:209], v[2:5]
	v_mfma_f32_16x16x32_bf16 v[74:77], v[134:137], v[214:217], v[74:77]
	v_mfma_f32_16x16x32_bf16 v[10:13], v[142:145], v[214:217], v[10:13]
	v_mfma_f32_16x16x32_bf16 v[42:45], v[146:149], v[162:165], 0
	v_mfma_f32_16x16x32_bf16 v[34:37], v[154:157], v[162:165], 0
	v_mfma_f32_16x16x32_bf16 v[26:29], v[146:149], v[170:173], 0
	v_mfma_f32_16x16x32_bf16 v[22:25], v[154:157], v[170:173], 0
	v_mfma_f32_16x16x32_bf16 v[54:57], v[146:149], v[192:195], 0
	v_mfma_f32_16x16x32_bf16 v[6:9], v[154:157], v[192:195], 0
	v_mfma_f32_16x16x32_bf16 v[78:81], v[146:149], v[210:213], 0
	v_mfma_f32_16x16x32_bf16 v[14:17], v[154:157], v[210:213], 0
	v_mfma_f32_16x16x32_bf16 v[42:45], v[150:153], v[166:169], v[42:45]
	v_mfma_f32_16x16x32_bf16 v[34:37], v[158:161], v[166:169], v[34:37]
	v_mfma_f32_16x16x32_bf16 v[26:29], v[150:153], v[174:177], v[26:29]
	v_mfma_f32_16x16x32_bf16 v[22:25], v[158:161], v[174:177], v[22:25]
	v_mfma_f32_16x16x32_bf16 v[54:57], v[150:153], v[206:209], v[54:57]
	v_mfma_f32_16x16x32_bf16 v[6:9], v[158:161], v[206:209], v[6:9]
	v_mfma_f32_16x16x32_bf16 v[78:81], v[150:153], v[214:217], v[78:81]
	v_mfma_f32_16x16x32_bf16 v[14:17], v[158:161], v[214:217], v[14:17]
	s_setprio 0
	s_barrier
	s_add_i32 s11, 0, 0x18000
	v_add_u32_e32 v0, s11, v204
	s_add_i32 s43, 0, 0x1c000
	ds_read_b128 v[130:133], v0
	ds_read_b128 v[134:137], v0 offset:1024
	ds_read_b128 v[138:141], v0 offset:2048
	ds_read_b128 v[142:145], v0 offset:3072
	v_add_u32_e32 v0, s43, v204
	ds_read_b128 v[146:149], v0
	ds_read_b128 v[150:153], v0 offset:1024
	ds_read_b128 v[154:157], v0 offset:2048
	ds_read_b128 v[158:161], v0 offset:3072
	s_add_u32 s8, s8, s0
	s_addc_u32 s9, s9, s1
	s_mov_b32 m0, s56
	v_lshl_add_u64 v[226:227], s[8:9], 0, v[180:181]
	ds_read_b128 v[162:165], v205 offset:32768
	ds_read_b128 v[166:169], v205 offset:33792
	ds_read_b128 v[170:173], v205 offset:34816
	ds_read_b128 v[174:177], v205 offset:35840
	ds_read_b128 v[192:195], v205 offset:36864
	ds_read_b128 v[206:209], v205 offset:37888
	ds_read_b128 v[210:213], v205 offset:38912
	ds_read_b128 v[214:217], v205 offset:39936
	global_load_lds_dwordx4 v[226:227], off
	v_lshl_add_u64 v[226:227], s[8:9], 0, v[184:185]
	s_mov_b32 m0, s57
	s_nop 0
	global_load_lds_dwordx4 v[226:227], off
	s_cmp_eq_u32 s73, 1
	s_cbranch_scc1 .Lkl652_w2f
	s_waitcnt vmcnt(16)
	s_branch .Lkl652_w2j

; #define PG8_STAGE(bufoff, gbase, voff) do { _Pragma("unroll") for (int _i = 0; _i < 2; ++_i) \
;         __builtin_amdgcn_global_load_lds((const unsigned*)((const char*)(gbase) + (voff)[_i]), (LAS unsigned*)(lds + (bufoff) + ldsw + _i * 8192), 16, 0, 0); } while (0)
; #define PG8_LDA(dst, b, h) do { _Pragma("unroll") for (int m = 0; m < 4; ++m) _Pragma("unroll") for (int k = 0; k < 2; ++k) dst[m][k] = *(const LAS bf16x8*)(lds + PG8_SA(b, h) + aoff + m * 2048 + k * 1024); } while (0)
; #define PG8_LDB(dst, b, h) do { _Pragma("unroll") for (int n = 0; n < 2; ++n) _Pragma("unroll") for (int k = 0; k < 2; ++k) dst[n][k] = *(const LAS bf16x8*)(lds + PG8_SB(b, h) + boff + n * 2048 + k * 1024); } while (0)
; #define PG8_MMA(ai, bj, At, Bt) do { __builtin_amdgcn_s_setprio(1); _Pragma("unroll") for (int m = 0; m < 4; ++m) _Pragma("unroll") for (int n = 0; n < 2; ++n) _Pragma("unroll") for (int k = 0; k < 2; ++k) \
;         acc[ai][bj][m][n] = __builtin_amdgcn_mfma_f32_16x16x32_bf16(Bt[n][k], At[m][k], acc[ai][bj][m][n], 0, 0, 0); __builtin_amdgcn_s_setprio(0); } while (0)
; #define PG8_WAIT_V(n) asm volatile("s_waitcnt vmcnt(" #n ")" ::: "memory")
; #define PG8_WAIT_L(n) asm volatile("s_waitcnt lgkmcnt(" #n ")" ::: "memory")
; #define PG8_BAR __builtin_amdgcn_s_barrier()
; #define PG8_SCHED __builtin_amdgcn_sched_barrier(0)
; template <class Epi>
; __device__ __forceinline__ void gemm_phase(LAS unsigned char* lds, const Gemm g, const StaticOrder& S, const Epi& E, const int tid) {
;     ...
;         for (int t = 0; t < nt; t += 2) {
;             const bool last = (t == nt - 2);
;             const char* a1 = cA + (size_t)(t + 1) * kstep;
;             const char* a2 = last ? nA : cA + (size_t)(t + 2) * kstep; const char* b2 = last ? nB : cB + (size_t)(t + 2) * kstep;
;             const char* a3 = a2 + kstep; const char* b3 = b2 + kstep;
;             PG8_LDB(B0, 0, 0); PG8_LDB(B1, 0, 1); PG8_SCHED; PG8_LDA(At, 0, 0); PG8_STAGE(PG8_SA(1, 1), a1 + hstepA, voffA);
;             PG8_WAIT_V(8); PG8_WAIT_L(0); PG8_BAR; PG8_MMA(0, 0, At, B0); PG8_MMA(0, 1, At, B1); PG8_BAR; PG8_SCHED;
;     ...
;             PG8_WAIT_V(8); PG8_WAIT_L(0); PG8_BAR; PG8_MMA(0, 0, At, B0); PG8_MMA(0, 1, At, B1); PG8_BAR; PG8_SCHED;
.Lkl652_w2j:
	s_waitcnt lgkmcnt(0)
	s_barrier
	s_setprio 1
	s_waitcnt lgkmcnt(0)
	v_mfma_f32_16x16x32_bf16 v[110:113], v[130:133], v[162:165], v[110:113]
	v_mfma_f32_16x16x32_bf16 v[106:109], v[138:141], v[162:165], v[106:109]
	v_mfma_f32_16x16x32_bf16 v[94:97], v[130:133], v[170:173], v[94:97]
	v_mfma_f32_16x16x32_bf16 v[90:93], v[138:141], v[170:173], v[90:93]
	v_mfma_f32_16x16x32_bf16 v[114:117], v[130:133], v[192:195], v[114:117]
	v_mfma_f32_16x16x32_bf16 v[62:65], v[138:141], v[192:195], v[62:65]
	v_mfma_f32_16x16x32_bf16 v[126:129], v[130:133], v[210:213], v[126:129]
	v_mfma_f32_16x16x32_bf16 v[70:73], v[138:141], v[210:213], v[70:73]
	v_mfma_f32_16x16x32_bf16 v[110:113], v[134:137], v[166:169], v[110:113]
	v_mfma_f32_16x16x32_bf16 v[106:109], v[142:145], v[166:169], v[106:109]
	v_mfma_f32_16x16x32_bf16 v[94:97], v[134:137], v[174:177], v[94:97]
	v_mfma_f32_16x16x32_bf16 v[90:93], v[142:145], v[174:177], v[90:93]
	v_mfma_f32_16x16x32_bf16 v[114:117], v[134:137], v[206:209], v[114:117]
	v_mfma_f32_16x16x32_bf16 v[62:65], v[142:145], v[206:209], v[62:65]
	v_mfma_f32_16x16x32_bf16 v[126:129], v[134:137], v[214:217], v[126:129]
	v_mfma_f32_16x16x32_bf16 v[70:73], v[142:145], v[214:217], v[70:73]
	v_mfma_f32_16x16x32_bf16 v[102:105], v[146:149], v[162:165], v[102:105]
	v_mfma_f32_16x16x32_bf16 v[98:101], v[154:157], v[162:165], v[98:101]
	v_mfma_f32_16x16x32_bf16 v[86:89], v[146:149], v[170:173], v[86:89]
	v_mfma_f32_16x16x32_bf16 v[82:85], v[154:157], v[170:173], v[82:85]
	v_mfma_f32_16x16x32_bf16 v[118:121], v[146:149], v[192:195], v[118:121]
	v_mfma_f32_16x16x32_bf16 v[58:61], v[154:157], v[192:195], v[58:61]
	v_mfma_f32_16x16x32_bf16 v[122:125], v[146:149], v[210:213], v[122:125]
	v_mfma_f32_16x16x32_bf16 v[66:69], v[154:157], v[210:213], v[66:69]
	v_mfma_f32_16x16x32_bf16 v[102:105], v[150:153], v[166:169], v[102:105]
	v_mfma_f32_16x16x32_bf16 v[98:101], v[158:161], v[166:169], v[98:101]
	v_mfma_f32_16x16x32_bf16 v[86:89], v[150:153], v[174:177], v[86:89]
	v_mfma_f32_16x16x32_bf16 v[82:85], v[158:161], v[174:177], v[82:85]
	v_mfma_f32_16x16x32_bf16 v[118:121], v[150:153], v[206:209], v[118:121]
	v_mfma_f32_16x16x32_bf16 v[58:61], v[158:161], v[206:209], v[58:61]
	v_mfma_f32_16x16x32_bf16 v[122:125], v[150:153], v[214:217], v[122:125]
	v_mfma_f32_16x16x32_bf16 v[66:69], v[158:161], v[214:217], v[66:69]
	s_setprio 0
	s_barrier
	s_branch .Lkl652_sp3
.LBB0_652:
	s_add_i32 s10, s8, 2
	s_add_u32 s11, s6, 0x80
	s_addc_u32 s9, s7, 0
	s_add_i32 s43, 0, 0x10000
	s_cmp_eq_u32 s67, s8
	s_cselect_b32 s9, s39, s9
	s_cselect_b32 s8, s38, s11
	v_add_u32_e32 v0, s43, v204
	s_cselect_b32 s45, s41, s42
	s_cselect_b32 s44, s40, s21
	s_add_i32 s11, 0, 0x14000
	ds_read_b128 v[130:133], v0
	ds_read_b128 v[134:137], v0 offset:1024
	ds_read_b128 v[138:141], v0 offset:2048
	ds_read_b128 v[142:145], v0 offset:3072
	v_add_u32_e32 v0, s11, v204
	ds_read_b128 v[146:149], v0
	ds_read_b128 v[150:153], v0 offset:1024
	ds_read_b128 v[154:157], v0 offset:2048
	ds_read_b128 v[158:161], v0 offset:3072
	v_lshl_add_u64 v[178:179], s[6:7], 0, v[190:191]
	s_add_i32 m0, s54, 0xc000
	ds_read_b128 v[162:165], v205
	ds_read_b128 v[166:169], v205 offset:1024
	ds_read_b128 v[170:173], v205 offset:2048
	ds_read_b128 v[174:177], v205 offset:3072
	ds_read_b128 v[192:195], v205 offset:4096
	ds_read_b128 v[206:209], v205 offset:5120
	ds_read_b128 v[210:213], v205 offset:6144
	ds_read_b128 v[214:217], v205 offset:7168
	global_load_lds_dwordx4 v[178:179], off
	v_lshl_add_u64 v[178:179], s[6:7], 0, v[188:189]
	s_add_i32 m0, s54, 0xe000
	s_nop 0
	global_load_lds_dwordx4 v[178:179], off
	s_waitcnt vmcnt(8)
	s_waitcnt lgkmcnt(0)
	s_barrier
	s_setprio 1
	s_waitcnt lgkmcnt(0)
	v_mfma_f32_16x16x32_bf16 v[110:113], v[130:133], v[162:165], v[110:113]
	v_mfma_f32_16x16x32_bf16 v[106:109], v[138:141], v[162:165], v[106:109]
	v_mfma_f32_16x16x32_bf16 v[94:97], v[130:133], v[170:173], v[94:97]
	v_mfma_f32_16x16x32_bf16 v[90:93], v[138:141], v[170:173], v[90:93]
	v_mfma_f32_16x16x32_bf16 v[114:117], v[130:133], v[192:195], v[114:117]
	v_mfma_f32_16x16x32_bf16 v[62:65], v[138:141], v[192:195], v[62:65]
	v_mfma_f32_16x16x32_bf16 v[126:129], v[130:133], v[210:213], v[126:129]
	v_mfma_f32_16x16x32_bf16 v[70:73], v[138:141], v[210:213], v[70:73]
	v_mfma_f32_16x16x32_bf16 v[110:113], v[134:137], v[166:169], v[110:113]
	v_mfma_f32_16x16x32_bf16 v[106:109], v[142:145], v[166:169], v[106:109]
	v_mfma_f32_16x16x32_bf16 v[94:97], v[134:137], v[174:177], v[94:97]
	v_mfma_f32_16x16x32_bf16 v[90:93], v[142:145], v[174:177], v[90:93]
	v_mfma_f32_16x16x32_bf16 v[114:117], v[134:137], v[206:209], v[114:117]
	v_mfma_f32_16x16x32_bf16 v[62:65], v[142:145], v[206:209], v[62:65]
	v_mfma_f32_16x16x32_bf16 v[126:129], v[134:137], v[214:217], v[126:129]
	v_mfma_f32_16x16x32_bf16 v[70:73], v[142:145], v[214:217], v[70:73]
	v_mfma_f32_16x16x32_bf16 v[102:105], v[146:149], v[162:165], v[102:105]
	v_mfma_f32_16x16x32_bf16 v[98:101], v[154:157], v[162:165], v[98:101]
	v_mfma_f32_16x16x32_bf16 v[86:89], v[146:149], v[170:173], v[86:89]
	v_mfma_f32_16x16x32_bf16 v[82:85], v[154:157], v[170:173], v[82:85]
	v_mfma_f32_16x16x32_bf16 v[118:121], v[146:149], v[192:195], v[118:121]
	v_mfma_f32_16x16x32_bf16 v[58:61], v[154:157], v[192:195], v[58:61]
	v_mfma_f32_16x16x32_bf16 v[122:125], v[146:149], v[210:213], v[122:125]
	v_mfma_f32_16x16x32_bf16 v[66:69], v[154:157], v[210:213], v[66:69]
	v_mfma_f32_16x16x32_bf16 v[102:105], v[150:153], v[166:169], v[102:105]
	v_mfma_f32_16x16x32_bf16 v[98:101], v[158:161], v[166:169], v[98:101]
	v_mfma_f32_16x16x32_bf16 v[86:89], v[150:153], v[174:177], v[86:89]
	v_mfma_f32_16x16x32_bf16 v[82:85], v[158:161], v[174:177], v[82:85]
	v_mfma_f32_16x16x32_bf16 v[118:121], v[150:153], v[206:209], v[118:121]
	v_mfma_f32_16x16x32_bf16 v[58:61], v[158:161], v[206:209], v[58:61]
	v_mfma_f32_16x16x32_bf16 v[122:125], v[150:153], v[214:217], v[122:125]
	v_mfma_f32_16x16x32_bf16 v[66:69], v[158:161], v[214:217], v[66:69]
	s_setprio 0
	s_barrier
; #define PG8_STAGE(bufoff, gbase, voff) do { _Pragma("unroll") for (int _i = 0; _i < 2; ++_i) \
;         __builtin_amdgcn_global_load_lds((const unsigned*)((const char*)(gbase) + (voff)[_i]), (LAS unsigned*)(lds + (bufoff) + ldsw + _i * 8192), 16, 0, 0); } while (0)
; #define PG8_LDA(dst, b, h) do { _Pragma("unroll") for (int m = 0; m < 4; ++m) _Pragma("unroll") for (int k = 0; k < 2; ++k) dst[m][k] = *(const LAS bf16x8*)(lds + PG8_SA(b, h) + aoff + m * 2048 + k * 1024); } while (0)
; #define PG8_LDB(dst, b, h) do { _Pragma("unroll") for (int n = 0; n < 2; ++n) _Pragma("unroll") for (int k = 0; k < 2; ++k) dst[n][k] = *(const LAS bf16x8*)(lds + PG8_SB(b, h) + boff + n * 2048 + k * 1024); } while (0)
; #define PG8_MMA(ai, bj, At, Bt) do { __builtin_amdgcn_s_setprio(1); _Pragma("unroll") for (int m = 0; m < 4; ++m) _Pragma("unroll") for (int n = 0; n < 2; ++n) _Pragma("unroll") for (int k = 0; k < 2; ++k) \
;         acc[ai][bj][m][n] = __builtin_amdgcn_mfma_f32_16x16x32_bf16(Bt[n][k], At[m][k], acc[ai][bj][m][n], 0, 0, 0); __builtin_amdgcn_s_setprio(0); } while (0)
; #define PG8_WAIT_V(n) asm volatile("s_waitcnt vmcnt(" #n ")" ::: "memory")
; #define PG8_WAIT_L(n) asm volatile("s_waitcnt lgkmcnt(" #n ")" ::: "memory")
; #define PG8_BAR __builtin_amdgcn_s_barrier()
; #define PG8_SCHED __builtin_amdgcn_sched_barrier(0)
; template <class Epi>
; __device__ __forceinline__ void gemm_phase(LAS unsigned char* lds, const Gemm g, const StaticOrder& S, const Epi& E, const int tid) {
;     ...
;             PG8_LDA(At, 0, 1); PG8_STAGE(PG8_SB(0, 0), b2, voffB); PG8_STAGE(PG8_SB(0, 1), b2 + hstepB, voffB); PG8_STAGE(PG8_SA(0, 0), a2, voffA);
;             PG8_WAIT_V(8); PG8_WAIT_L(0); PG8_BAR; PG8_MMA(1, 0, At, B0); PG8_MMA(1, 1, At, B1); PG8_BAR; PG8_SCHED;
;             PG8_LDB(B0, 1, 0); PG8_LDB(B1, 1, 1); PG8_SCHED; PG8_LDA(At, 1, 0); PG8_STAGE(PG8_SA(0, 1), a2 + hstepA, voffA);
;             PG8_WAIT_V(8); PG8_WAIT_L(0); PG8_BAR; PG8_MMA(0, 0, At, B0); PG8_MMA(0, 1, At, B1); PG8_BAR; PG8_SCHED;
	s_add_i32 s43, s43, s53
	v_lshl_add_u64 v[178:179], s[44:45], 0, v[182:183]
	s_mov_b32 m0, s43
	ds_read_b128 v[162:165], v205 offset:16384
	ds_read_b128 v[166:169], v205 offset:17408
	ds_read_b128 v[170:173], v205 offset:18432
	ds_read_b128 v[174:177], v205 offset:19456
	ds_read_b128 v[192:195], v205 offset:20480
	ds_read_b128 v[206:209], v205 offset:21504
	ds_read_b128 v[210:213], v205 offset:22528
	ds_read_b128 v[214:217], v205 offset:23552
	global_load_lds_dwordx4 v[178:179], off
	s_add_i32 m0, s43, 0x2000
	v_lshl_add_u64 v[202:203], s[44:45], 0, v[186:187]
	s_add_u32 s44, s44, s12
	s_addc_u32 s45, s45, s13
	s_add_i32 s11, s11, s53
	global_load_lds_dwordx4 v[202:203], off
	v_lshl_add_u64 v[218:219], s[44:45], 0, v[182:183]
	s_mov_b32 m0, s11
	v_lshl_add_u64 v[220:221], s[44:45], 0, v[186:187]
	global_load_lds_dwordx4 v[218:219], off
	s_add_i32 m0, s11, 0x2000
	v_lshl_add_u64 v[222:223], s[8:9], 0, v[180:181]
	global_load_lds_dwordx4 v[220:221], off
	s_mov_b32 m0, s54
	v_lshl_add_u64 v[224:225], s[8:9], 0, v[184:185]
	global_load_lds_dwordx4 v[222:223], off
	s_mov_b32 m0, s55
	s_nop 0
	global_load_lds_dwordx4 v[224:225], off
	s_waitcnt vmcnt(8)
	s_waitcnt lgkmcnt(0)
	s_barrier
	s_setprio 1
	s_waitcnt lgkmcnt(0)
	v_mfma_f32_16x16x32_bf16 v[46:49], v[130:133], v[162:165], v[46:49]
	v_mfma_f32_16x16x32_bf16 v[30:33], v[138:141], v[162:165], v[30:33]
	v_mfma_f32_16x16x32_bf16 v[38:41], v[130:133], v[170:173], v[38:41]
	v_mfma_f32_16x16x32_bf16 v[18:21], v[138:141], v[170:173], v[18:21]
	v_mfma_f32_16x16x32_bf16 v[50:53], v[130:133], v[192:195], v[50:53]
	v_mfma_f32_16x16x32_bf16 v[2:5], v[138:141], v[192:195], v[2:5]
	v_mfma_f32_16x16x32_bf16 v[74:77], v[130:133], v[210:213], v[74:77]
	v_mfma_f32_16x16x32_bf16 v[10:13], v[138:141], v[210:213], v[10:13]
	v_mfma_f32_16x16x32_bf16 v[46:49], v[134:137], v[166:169], v[46:49]
	v_mfma_f32_16x16x32_bf16 v[30:33], v[142:145], v[166:169], v[30:33]
	v_mfma_f32_16x16x32_bf16 v[38:41], v[134:137], v[174:177], v[38:41]
	v_mfma_f32_16x16x32_bf16 v[18:21], v[142:145], v[174:177], v[18:21]
	v_mfma_f32_16x16x32_bf16 v[50:53], v[134:137], v[206:209], v[50:53]
	v_mfma_f32_16x16x32_bf16 v[2:5], v[142:145], v[206:209], v[2:5]
	v_mfma_f32_16x16x32_bf16 v[74:77], v[134:137], v[214:217], v[74:77]
	v_mfma_f32_16x16x32_bf16 v[10:13], v[142:145], v[214:217], v[10:13]
	v_mfma_f32_16x16x32_bf16 v[42:45], v[146:149], v[162:165], v[42:45]
	v_mfma_f32_16x16x32_bf16 v[34:37], v[154:157], v[162:165], v[34:37]
	v_mfma_f32_16x16x32_bf16 v[26:29], v[146:149], v[170:173], v[26:29]
	v_mfma_f32_16x16x32_bf16 v[22:25], v[154:157], v[170:173], v[22:25]
	v_mfma_f32_16x16x32_bf16 v[54:57], v[146:149], v[192:195], v[54:57]
	v_mfma_f32_16x16x32_bf16 v[6:9], v[154:157], v[192:195], v[6:9]
	v_mfma_f32_16x16x32_bf16 v[78:81], v[146:149], v[210:213], v[78:81]
	v_mfma_f32_16x16x32_bf16 v[14:17], v[154:157], v[210:213], v[14:17]
	v_mfma_f32_16x16x32_bf16 v[42:45], v[150:153], v[166:169], v[42:45]
	v_mfma_f32_16x16x32_bf16 v[34:37], v[158:161], v[166:169], v[34:37]
	v_mfma_f32_16x16x32_bf16 v[26:29], v[150:153], v[174:177], v[26:29]
	v_mfma_f32_16x16x32_bf16 v[22:25], v[158:161], v[174:177], v[22:25]
	v_mfma_f32_16x16x32_bf16 v[54:57], v[150:153], v[206:209], v[54:57]
	v_mfma_f32_16x16x32_bf16 v[6:9], v[158:161], v[206:209], v[6:9]
	v_mfma_f32_16x16x32_bf16 v[78:81], v[150:153], v[214:217], v[78:81]
	v_mfma_f32_16x16x32_bf16 v[14:17], v[158:161], v[214:217], v[14:17]
	s_setprio 0
	s_barrier
.Lkl652_sp2:
	s_add_i32 s11, 0, 0x18000
	v_add_u32_e32 v0, s11, v204
	s_add_i32 s43, 0, 0x1c000
	ds_read_b128 v[130:133], v0
	ds_read_b128 v[134:137], v0 offset:1024
	ds_read_b128 v[138:141], v0 offset:2048
	ds_read_b128 v[142:145], v0 offset:3072
	v_add_u32_e32 v0, s43, v204
	ds_read_b128 v[146:149], v0
	ds_read_b128 v[150:153], v0 offset:1024
	ds_read_b128 v[154:157], v0 offset:2048
	ds_read_b128 v[158:161], v0 offset:3072
	s_add_u32 s8, s8, s0
	s_addc_u32 s9, s9, s1
	s_mov_b32 m0, s56
	v_lshl_add_u64 v[226:227], s[8:9], 0, v[180:181]
	ds_read_b128 v[162:165], v205 offset:32768
	ds_read_b128 v[166:169], v205 offset:33792
	ds_read_b128 v[170:173], v205 offset:34816
	ds_read_b128 v[174:177], v205 offset:35840
	ds_read_b128 v[192:195], v205 offset:36864
	ds_read_b128 v[206:209], v205 offset:37888
	ds_read_b128 v[210:213], v205 offset:38912
	ds_read_b128 v[214:217], v205 offset:39936
	global_load_lds_dwordx4 v[226:227], off
	v_lshl_add_u64 v[226:227], s[8:9], 0, v[184:185]
	s_mov_b32 m0, s57
	s_nop 0
	global_load_lds_dwordx4 v[226:227], off
	s_waitcnt vmcnt(8)
	s_waitcnt lgkmcnt(0)
	s_barrier
	s_setprio 1
	s_waitcnt lgkmcnt(0)
	v_mfma_f32_16x16x32_bf16 v[110:113], v[130:133], v[162:165], v[110:113]
	v_mfma_f32_16x16x32_bf16 v[106:109], v[138:141], v[162:165], v[106:109]
	v_mfma_f32_16x16x32_bf16 v[94:97], v[130:133], v[170:173], v[94:97]
	v_mfma_f32_16x16x32_bf16 v[90:93], v[138:141], v[170:173], v[90:93]
	v_mfma_f32_16x16x32_bf16 v[114:117], v[130:133], v[192:195], v[114:117]
	v_mfma_f32_16x16x32_bf16 v[62:65], v[138:141], v[192:195], v[62:65]
	v_mfma_f32_16x16x32_bf16 v[126:129], v[130:133], v[210:213], v[126:129]
	v_mfma_f32_16x16x32_bf16 v[70:73], v[138:141], v[210:213], v[70:73]
	v_mfma_f32_16x16x32_bf16 v[110:113], v[134:137], v[166:169], v[110:113]
	v_mfma_f32_16x16x32_bf16 v[106:109], v[142:145], v[166:169], v[106:109]
	v_mfma_f32_16x16x32_bf16 v[94:97], v[134:137], v[174:177], v[94:97]
	v_mfma_f32_16x16x32_bf16 v[90:93], v[142:145], v[174:177], v[90:93]
	v_mfma_f32_16x16x32_bf16 v[114:117], v[134:137], v[206:209], v[114:117]
	v_mfma_f32_16x16x32_bf16 v[62:65], v[142:145], v[206:209], v[62:65]
	v_mfma_f32_16x16x32_bf16 v[126:129], v[134:137], v[214:217], v[126:129]
	v_mfma_f32_16x16x32_bf16 v[70:73], v[142:145], v[214:217], v[70:73]
	v_mfma_f32_16x16x32_bf16 v[102:105], v[146:149], v[162:165], v[102:105]
	v_mfma_f32_16x16x32_bf16 v[98:101], v[154:157], v[162:165], v[98:101]
	v_mfma_f32_16x16x32_bf16 v[86:89], v[146:149], v[170:173], v[86:89]
	v_mfma_f32_16x16x32_bf16 v[82:85], v[154:157], v[170:173], v[82:85]
	v_mfma_f32_16x16x32_bf16 v[118:121], v[146:149], v[192:195], v[118:121]
	v_mfma_f32_16x16x32_bf16 v[58:61], v[154:157], v[192:195], v[58:61]
	v_mfma_f32_16x16x32_bf16 v[122:125], v[146:149], v[210:213], v[122:125]
	v_mfma_f32_16x16x32_bf16 v[66:69], v[154:157], v[210:213], v[66:69]
	v_mfma_f32_16x16x32_bf16 v[102:105], v[150:153], v[166:169], v[102:105]
	v_mfma_f32_16x16x32_bf16 v[98:101], v[158:161], v[166:169], v[98:101]
	v_mfma_f32_16x16x32_bf16 v[86:89], v[150:153], v[174:177], v[86:89]
	v_mfma_f32_16x16x32_bf16 v[82:85], v[158:161], v[174:177], v[82:85]
	v_mfma_f32_16x16x32_bf16 v[118:121], v[150:153], v[206:209], v[118:121]
	v_mfma_f32_16x16x32_bf16 v[58:61], v[158:161], v[206:209], v[58:61]
	v_mfma_f32_16x16x32_bf16 v[122:125], v[150:153], v[214:217], v[122:125]
	v_mfma_f32_16x16x32_bf16 v[66:69], v[158:161], v[214:217], v[66:69]
	s_setprio 0
	s_barrier
; #define PG8_STAGE(bufoff, gbase, voff) do { _Pragma("unroll") for (int _i = 0; _i < 2; ++_i) \
;         __builtin_amdgcn_global_load_lds((const unsigned*)((const char*)(gbase) + (voff)[_i]), (LAS unsigned*)(lds + (bufoff) + ldsw + _i * 8192), 16, 0, 0); } while (0)
; #define PG8_LDA(dst, b, h) do { _Pragma("unroll") for (int m = 0; m < 4; ++m) _Pragma("unroll") for (int k = 0; k < 2; ++k) dst[m][k] = *(const LAS bf16x8*)(lds + PG8_SA(b, h) + aoff + m * 2048 + k * 1024); } while (0)
; #define PG8_MMA(ai, bj, At, Bt) do { __builtin_amdgcn_s_setprio(1); _Pragma("unroll") for (int m = 0; m < 4; ++m) _Pragma("unroll") for (int n = 0; n < 2; ++n) _Pragma("unroll") for (int k = 0; k < 2; ++k) \
;         acc[ai][bj][m][n] = __builtin_amdgcn_mfma_f32_16x16x32_bf16(Bt[n][k], At[m][k], acc[ai][bj][m][n], 0, 0, 0); __builtin_amdgcn_s_setprio(0); } while (0)
; #define PG8_WAIT_V(n) asm volatile("s_waitcnt vmcnt(" #n ")" ::: "memory")
; #define PG8_WAIT_L(n) asm volatile("s_waitcnt lgkmcnt(" #n ")" ::: "memory")
; #define PG8_BAR __builtin_amdgcn_s_barrier()
; #define PG8_SCHED __builtin_amdgcn_sched_barrier(0)
; template <class Epi>
; __device__ __forceinline__ void gemm_phase(LAS unsigned char* lds, const Gemm g, const StaticOrder& S, const Epi& E, const int tid) {
;     ...
;             PG8_LDA(At, 1, 1); PG8_STAGE(PG8_SB(1, 0), b3, voffB); PG8_STAGE(PG8_SB(1, 1), b3 + hstepB, voffB); PG8_STAGE(PG8_SA(1, 0), a3, voffA);
;             PG8_WAIT_V(8); PG8_WAIT_L(0); PG8_BAR; PG8_MMA(1, 0, At, B0); PG8_MMA(1, 1, At, B1); PG8_BAR; PG8_SCHED;
;         }
;         if (wr == 0) PG8_BAR;
.Lkl652_sp3:
	s_add_i32 s8, s11, s53
	v_lshl_add_u64 v[178:179], v[178:179], 0, s[80:81]
	s_mov_b32 m0, s8
	ds_read_b128 v[162:165], v205 offset:49152
	ds_read_b128 v[166:169], v205 offset:50176
	ds_read_b128 v[170:173], v205 offset:51200
	ds_read_b128 v[174:177], v205 offset:52224
	ds_read_b128 v[192:195], v205 offset:53248
	ds_read_b128 v[206:209], v205 offset:54272
	ds_read_b128 v[210:213], v205 offset:55296
	ds_read_b128 v[214:217], v205 offset:56320
	global_load_lds_dwordx4 v[178:179], off
	v_lshl_add_u64 v[178:179], v[202:203], 0, s[80:81]
	s_add_i32 m0, s8, 0x2000
	s_add_i32 s8, s43, s53
	global_load_lds_dwordx4 v[178:179], off
	v_lshl_add_u64 v[178:179], v[218:219], 0, s[80:81]
	s_mov_b32 m0, s8
	s_nop 0
	global_load_lds_dwordx4 v[178:179], off
	v_lshl_add_u64 v[178:179], v[220:221], 0, s[80:81]
	s_add_i32 m0, s8, 0x2000
	s_nop 0
	global_load_lds_dwordx4 v[178:179], off
	v_lshl_add_u64 v[178:179], v[222:223], 0, s[80:81]
	s_mov_b32 m0, s62
	s_nop 0
	global_load_lds_dwordx4 v[178:179], off
	v_lshl_add_u64 v[178:179], v[224:225], 0, s[80:81]
	s_mov_b32 m0, s63
	s_nop 0
	global_load_lds_dwordx4 v[178:179], off
	s_waitcnt vmcnt(8)
	s_waitcnt lgkmcnt(0)
	s_nop 0
	s_barrier
	s_setprio 1
	s_waitcnt lgkmcnt(0)
	v_mfma_f32_16x16x32_bf16 v[46:49], v[130:133], v[162:165], v[46:49]
	v_mfma_f32_16x16x32_bf16 v[30:33], v[138:141], v[162:165], v[30:33]
	v_mfma_f32_16x16x32_bf16 v[38:41], v[130:133], v[170:173], v[38:41]
	v_mfma_f32_16x16x32_bf16 v[18:21], v[138:141], v[170:173], v[18:21]
	v_mfma_f32_16x16x32_bf16 v[50:53], v[130:133], v[192:195], v[50:53]
	v_mfma_f32_16x16x32_bf16 v[2:5], v[138:141], v[192:195], v[2:5]
	v_mfma_f32_16x16x32_bf16 v[74:77], v[130:133], v[210:213], v[74:77]
	v_mfma_f32_16x16x32_bf16 v[10:13], v[138:141], v[210:213], v[10:13]
	v_mfma_f32_16x16x32_bf16 v[46:49], v[134:137], v[166:169], v[46:49]
	v_mfma_f32_16x16x32_bf16 v[30:33], v[142:145], v[166:169], v[30:33]
	v_mfma_f32_16x16x32_bf16 v[38:41], v[134:137], v[174:177], v[38:41]
	v_mfma_f32_16x16x32_bf16 v[18:21], v[142:145], v[174:177], v[18:21]
	v_mfma_f32_16x16x32_bf16 v[50:53], v[134:137], v[206:209], v[50:53]
	v_mfma_f32_16x16x32_bf16 v[2:5], v[142:145], v[206:209], v[2:5]
	v_mfma_f32_16x16x32_bf16 v[74:77], v[134:137], v[214:217], v[74:77]
	v_mfma_f32_16x16x32_bf16 v[10:13], v[142:145], v[214:217], v[10:13]
	v_mfma_f32_16x16x32_bf16 v[42:45], v[146:149], v[162:165], v[42:45]
	v_mfma_f32_16x16x32_bf16 v[34:37], v[154:157], v[162:165], v[34:37]
	v_mfma_f32_16x16x32_bf16 v[26:29], v[146:149], v[170:173], v[26:29]
	v_mfma_f32_16x16x32_bf16 v[22:25], v[154:157], v[170:173], v[22:25]
	v_mfma_f32_16x16x32_bf16 v[54:57], v[146:149], v[192:195], v[54:57]
	v_mfma_f32_16x16x32_bf16 v[6:9], v[154:157], v[192:195], v[6:9]
	v_mfma_f32_16x16x32_bf16 v[78:81], v[146:149], v[210:213], v[78:81]
	v_mfma_f32_16x16x32_bf16 v[14:17], v[154:157], v[210:213], v[14:17]
	v_mfma_f32_16x16x32_bf16 v[42:45], v[150:153], v[166:169], v[42:45]
	v_mfma_f32_16x16x32_bf16 v[34:37], v[158:161], v[166:169], v[34:37]
	v_mfma_f32_16x16x32_bf16 v[26:29], v[150:153], v[174:177], v[26:29]
	v_mfma_f32_16x16x32_bf16 v[22:25], v[158:161], v[174:177], v[22:25]
	v_mfma_f32_16x16x32_bf16 v[54:57], v[150:153], v[206:209], v[54:57]
	v_mfma_f32_16x16x32_bf16 v[6:9], v[158:161], v[206:209], v[6:9]
	v_mfma_f32_16x16x32_bf16 v[78:81], v[150:153], v[214:217], v[78:81]
	v_mfma_f32_16x16x32_bf16 v[14:17], v[158:161], v[214:217], v[14:17]
	s_setprio 0
	s_barrier
	s_add_u32 s21, s21, 0x100
	s_addc_u32 s42, s42, 0
	s_add_u32 s6, s6, 0x100
	s_addc_u32 s7, s7, 0
	s_cmp_ge_i32 s10, s64
	s_mov_b32 s8, s10
	s_cbranch_scc0 .LBB0_652
	s_and_b64 vcc, exec, s[4:5]
	s_cbranch_vccnz .Lkl652_noa
	s_add_u32 s98, s38, 0x80
	s_addc_u32 s99, s39, 0
	v_lshl_add_u64 v[178:179], s[98:99], 0, v[190:191]
	s_add_i32 m0, s54, 0xc000
	s_nop 0
	global_load_lds_dwordx4 v[178:179], off
	v_lshl_add_u64 v[178:179], s[98:99], 0, v[188:189]
	s_add_i32 m0, s54, 0xe000
	s_nop 0
	global_load_lds_dwordx4 v[178:179], off
